# K-loops without the per-block s_setprio pairs (measured neutral earlier; two fewer scalar slots around every MMA block)
# speedup vs baseline: 1.0063x; 1.0029x over previous
.LBB0_211:
	s_ashr_i32 s17, s16, 31
	s_lshl_b64 s[18:19], s[16:17], 19
	s_add_u32 s18, s68, s18
	s_addc_u32 s19, s69, s19
	s_and_b64 s[20:21], s[0:1], exec
	s_cselect_b32 s17, s19, s25
	s_cselect_b32 s44, s18, s24
	s_ashr_i32 s15, s14, 31
	s_lshl_b64 s[20:21], s[14:15], 19
	s_add_u32 s20, s3, s20
	s_addc_u32 s21, s6, s21
	s_and_b64 s[28:29], s[0:1], exec
	s_cselect_b32 s15, s21, s27
	s_cselect_b32 s45, s20, s26
	s_add_u32 s24, s24, 0x40080
	s_addc_u32 s25, s25, 0
	s_add_u32 s46, s26, 0x100
	s_addc_u32 s47, s27, 0
	s_mov_b32 s70, -2
	ds_read_b128 v[146:149], v153
	ds_read_b128 v[156:159], v153 offset:1024
	ds_read_b128 v[160:163], v153 offset:2048
	ds_read_b128 v[164:167], v153 offset:3072
	ds_read_b128 v[174:177], v154
	ds_read_b128 v[178:181], v154 offset:1024
	ds_read_b128 v[182:185], v154 offset:2048
	ds_read_b128 v[186:189], v154 offset:3072
	s_add_u32 s26, s24, 0xfffc0080
	s_addc_u32 s27, s25, -1
	s_cmp_eq_u32 s70, 12
	s_cselect_b32 s29, s17, s27
	s_cselect_b32 s28, s44, s26
	s_cselect_b32 s27, s15, s47
	s_cselect_b32 s26, s45, s46
	s_add_i32 m0, s23, 0xc000
	ds_read_b128 v[190:193], v155
	ds_read_b128 v[194:197], v155 offset:1024
	ds_read_b128 v[198:201], v155 offset:2048
	ds_read_b128 v[202:205], v155 offset:3072
	ds_read_b128 v[206:209], v155 offset:4096
	ds_read_b128 v[210:213], v155 offset:5120
	ds_read_b128 v[214:217], v155 offset:6144
	ds_read_b128 v[218:221], v155 offset:7168
	global_load_lds_dwordx4 v138, s[24:25]
	s_add_i32 m0, s23, 0xe000
	s_nop 0
	global_load_lds_dwordx4 v140, s[24:25]
	s_waitcnt vmcnt(8)
	s_waitcnt lgkmcnt(0)
	s_barrier
	v_mfma_f32_16x16x32_bf16 v[126:129], v[146:149], v[190:193], 0
	v_mfma_f32_16x16x32_bf16 v[122:125], v[160:163], v[190:193], 0
	v_mfma_f32_16x16x32_bf16 v[118:121], v[146:149], v[198:201], 0
	v_mfma_f32_16x16x32_bf16 v[110:113], v[160:163], v[198:201], 0
	v_mfma_f32_16x16x32_bf16 v[102:105], v[146:149], v[206:209], 0
	v_mfma_f32_16x16x32_bf16 v[94:97], v[160:163], v[206:209], 0
	v_mfma_f32_16x16x32_bf16 v[86:89], v[146:149], v[214:217], 0
	v_mfma_f32_16x16x32_bf16 v[78:81], v[160:163], v[214:217], 0
	v_mfma_f32_16x16x32_bf16 v[126:129], v[156:159], v[194:197], v[126:129]
	v_mfma_f32_16x16x32_bf16 v[122:125], v[164:167], v[194:197], v[122:125]
	v_mfma_f32_16x16x32_bf16 v[118:121], v[156:159], v[202:205], v[118:121]
	v_mfma_f32_16x16x32_bf16 v[110:113], v[164:167], v[202:205], v[110:113]
	v_mfma_f32_16x16x32_bf16 v[102:105], v[156:159], v[210:213], v[102:105]
	v_mfma_f32_16x16x32_bf16 v[94:97], v[164:167], v[210:213], v[94:97]
	v_mfma_f32_16x16x32_bf16 v[86:89], v[156:159], v[218:221], v[86:89]
	v_mfma_f32_16x16x32_bf16 v[78:81], v[164:167], v[218:221], v[78:81]
	v_mfma_f32_16x16x32_bf16 v[114:117], v[174:177], v[190:193], 0
	v_mfma_f32_16x16x32_bf16 v[106:109], v[182:185], v[190:193], 0
	v_mfma_f32_16x16x32_bf16 v[98:101], v[174:177], v[198:201], 0
	v_mfma_f32_16x16x32_bf16 v[90:93], v[182:185], v[198:201], 0
	v_mfma_f32_16x16x32_bf16 v[82:85], v[174:177], v[206:209], 0
	v_mfma_f32_16x16x32_bf16 v[74:77], v[182:185], v[206:209], 0
	v_mfma_f32_16x16x32_bf16 v[70:73], v[174:177], v[214:217], 0
	v_mfma_f32_16x16x32_bf16 v[66:69], v[182:185], v[214:217], 0
	v_mfma_f32_16x16x32_bf16 v[114:117], v[178:181], v[194:197], v[114:117]
	v_mfma_f32_16x16x32_bf16 v[106:109], v[186:189], v[194:197], v[106:109]
	v_mfma_f32_16x16x32_bf16 v[98:101], v[178:181], v[202:205], v[98:101]
	v_mfma_f32_16x16x32_bf16 v[90:93], v[186:189], v[202:205], v[90:93]
	v_mfma_f32_16x16x32_bf16 v[82:85], v[178:181], v[210:213], v[82:85]
	v_mfma_f32_16x16x32_bf16 v[74:77], v[186:189], v[210:213], v[74:77]
	v_mfma_f32_16x16x32_bf16 v[70:73], v[178:181], v[218:221], v[70:73]
	v_mfma_f32_16x16x32_bf16 v[66:69], v[186:189], v[218:221], v[66:69]
	s_barrier
	s_add_u32 s98, s26, 0x80
	s_addc_u32 s99, s27, 0
	s_add_u32 s100, s28, 0x80
	s_addc_u32 s101, s29, 0
	s_add_i32 s71, s40, s7
	s_mov_b32 m0, s71
	ds_read_b128 v[190:193], v155 offset:16384
	ds_read_b128 v[194:197], v155 offset:17408
	ds_read_b128 v[198:201], v155 offset:18432
	ds_read_b128 v[202:205], v155 offset:19456
	ds_read_b128 v[206:209], v155 offset:20480
	ds_read_b128 v[210:213], v155 offset:21504
	ds_read_b128 v[214:217], v155 offset:22528
	ds_read_b128 v[218:221], v155 offset:23552
	global_load_lds_dwordx4 v134, s[26:27]
	s_add_i32 m0, s71, 0x2000
	s_add_u32 s74, s26, 0x40000
	s_addc_u32 s75, s27, 0
	s_add_i32 s71, s41, s7
	global_load_lds_dwordx4 v130, s[26:27]
	s_mov_b32 m0, s71
	s_nop 0
	global_load_lds_dwordx4 v134, s[74:75]
	s_add_i32 m0, s71, 0x2000
	s_nop 0
	global_load_lds_dwordx4 v130, s[74:75]
	s_mov_b32 m0, s23
	s_nop 0
	global_load_lds_dwordx4 v136, s[28:29]
	s_mov_b32 m0, s31
	s_nop 0
	global_load_lds_dwordx4 v132, s[28:29]
	s_waitcnt vmcnt(8)
	s_waitcnt lgkmcnt(0)
	s_barrier
	v_mfma_f32_16x16x32_bf16 v[62:65], v[146:149], v[190:193], 0
	v_mfma_f32_16x16x32_bf16 v[58:61], v[160:163], v[190:193], 0
	v_mfma_f32_16x16x32_bf16 v[54:57], v[146:149], v[198:201], 0
	v_mfma_f32_16x16x32_bf16 v[46:49], v[160:163], v[198:201], 0
	v_mfma_f32_16x16x32_bf16 v[38:41], v[146:149], v[206:209], 0
	v_mfma_f32_16x16x32_bf16 v[30:33], v[160:163], v[206:209], 0
	v_mfma_f32_16x16x32_bf16 v[22:25], v[146:149], v[214:217], 0
	v_mfma_f32_16x16x32_bf16 v[14:17], v[160:163], v[214:217], 0
	v_mfma_f32_16x16x32_bf16 v[62:65], v[156:159], v[194:197], v[62:65]
	v_mfma_f32_16x16x32_bf16 v[58:61], v[164:167], v[194:197], v[58:61]
	v_mfma_f32_16x16x32_bf16 v[54:57], v[156:159], v[202:205], v[54:57]
	v_mfma_f32_16x16x32_bf16 v[46:49], v[164:167], v[202:205], v[46:49]
	v_mfma_f32_16x16x32_bf16 v[38:41], v[156:159], v[210:213], v[38:41]
	v_mfma_f32_16x16x32_bf16 v[30:33], v[164:167], v[210:213], v[30:33]
	v_mfma_f32_16x16x32_bf16 v[22:25], v[156:159], v[218:221], v[22:25]
	v_mfma_f32_16x16x32_bf16 v[14:17], v[164:167], v[218:221], v[14:17]
	v_mfma_f32_16x16x32_bf16 v[50:53], v[174:177], v[190:193], 0
	v_mfma_f32_16x16x32_bf16 v[42:45], v[182:185], v[190:193], 0
	v_mfma_f32_16x16x32_bf16 v[34:37], v[174:177], v[198:201], 0
	v_mfma_f32_16x16x32_bf16 v[26:29], v[182:185], v[198:201], 0
	v_mfma_f32_16x16x32_bf16 v[18:21], v[174:177], v[206:209], 0
	v_mfma_f32_16x16x32_bf16 v[10:13], v[182:185], v[206:209], 0
	v_mfma_f32_16x16x32_bf16 v[6:9], v[174:177], v[214:217], 0
	v_mfma_f32_16x16x32_bf16 v[2:5], v[182:185], v[214:217], 0
	v_mfma_f32_16x16x32_bf16 v[50:53], v[178:181], v[194:197], v[50:53]
	v_mfma_f32_16x16x32_bf16 v[42:45], v[186:189], v[194:197], v[42:45]
	v_mfma_f32_16x16x32_bf16 v[34:37], v[178:181], v[202:205], v[34:37]
	v_mfma_f32_16x16x32_bf16 v[26:29], v[186:189], v[202:205], v[26:29]
	v_mfma_f32_16x16x32_bf16 v[18:21], v[178:181], v[210:213], v[18:21]
	v_mfma_f32_16x16x32_bf16 v[10:13], v[186:189], v[210:213], v[10:13]
	v_mfma_f32_16x16x32_bf16 v[6:9], v[178:181], v[218:221], v[6:9]
	v_mfma_f32_16x16x32_bf16 v[2:5], v[186:189], v[218:221], v[2:5]
	s_barrier
	s_add_i32 s71, 0, 0x18000
	v_add_u32_e32 v1, s71, v151
	s_add_i32 s74, 0, 0x1c000
	ds_read_b128 v[146:149], v1
	ds_read_b128 v[156:159], v1 offset:1024
	ds_read_b128 v[160:163], v1 offset:2048
	ds_read_b128 v[164:167], v1 offset:3072
	v_add_u32_e32 v1, s74, v151
	ds_read_b128 v[174:177], v1
	ds_read_b128 v[178:181], v1 offset:1024
	ds_read_b128 v[182:185], v1 offset:2048
	ds_read_b128 v[186:189], v1 offset:3072
	s_add_u32 s28, s28, 0x40000
	s_addc_u32 s29, s29, 0
	s_mov_b32 m0, s34
	ds_read_b128 v[190:193], v155 offset:32768
	ds_read_b128 v[194:197], v155 offset:33792
	ds_read_b128 v[198:201], v155 offset:34816
	ds_read_b128 v[202:205], v155 offset:35840
	ds_read_b128 v[206:209], v155 offset:36864
	ds_read_b128 v[210:213], v155 offset:37888
	ds_read_b128 v[214:217], v155 offset:38912
	ds_read_b128 v[218:221], v155 offset:39936
	global_load_lds_dwordx4 v136, s[28:29]
	s_mov_b32 m0, s35
	s_nop 0
	global_load_lds_dwordx4 v132, s[28:29]
	s_waitcnt vmcnt(8)
	s_waitcnt lgkmcnt(0)
	s_barrier
	v_mfma_f32_16x16x32_bf16 v[126:129], v[146:149], v[190:193], v[126:129]
	v_mfma_f32_16x16x32_bf16 v[122:125], v[160:163], v[190:193], v[122:125]
	v_mfma_f32_16x16x32_bf16 v[118:121], v[146:149], v[198:201], v[118:121]
	v_mfma_f32_16x16x32_bf16 v[110:113], v[160:163], v[198:201], v[110:113]
	v_mfma_f32_16x16x32_bf16 v[102:105], v[146:149], v[206:209], v[102:105]
	v_mfma_f32_16x16x32_bf16 v[94:97], v[160:163], v[206:209], v[94:97]
	v_mfma_f32_16x16x32_bf16 v[86:89], v[146:149], v[214:217], v[86:89]
	v_mfma_f32_16x16x32_bf16 v[78:81], v[160:163], v[214:217], v[78:81]
	v_mfma_f32_16x16x32_bf16 v[126:129], v[156:159], v[194:197], v[126:129]
	v_mfma_f32_16x16x32_bf16 v[122:125], v[164:167], v[194:197], v[122:125]
	v_mfma_f32_16x16x32_bf16 v[118:121], v[156:159], v[202:205], v[118:121]
	v_mfma_f32_16x16x32_bf16 v[110:113], v[164:167], v[202:205], v[110:113]
	v_mfma_f32_16x16x32_bf16 v[102:105], v[156:159], v[210:213], v[102:105]
	v_mfma_f32_16x16x32_bf16 v[94:97], v[164:167], v[210:213], v[94:97]
	v_mfma_f32_16x16x32_bf16 v[86:89], v[156:159], v[218:221], v[86:89]
	v_mfma_f32_16x16x32_bf16 v[78:81], v[164:167], v[218:221], v[78:81]
	v_mfma_f32_16x16x32_bf16 v[114:117], v[174:177], v[190:193], v[114:117]
	v_mfma_f32_16x16x32_bf16 v[106:109], v[182:185], v[190:193], v[106:109]
	v_mfma_f32_16x16x32_bf16 v[98:101], v[174:177], v[198:201], v[98:101]
	v_mfma_f32_16x16x32_bf16 v[90:93], v[182:185], v[198:201], v[90:93]
	v_mfma_f32_16x16x32_bf16 v[82:85], v[174:177], v[206:209], v[82:85]
	v_mfma_f32_16x16x32_bf16 v[74:77], v[182:185], v[206:209], v[74:77]
	v_mfma_f32_16x16x32_bf16 v[70:73], v[174:177], v[214:217], v[70:73]
	v_mfma_f32_16x16x32_bf16 v[66:69], v[182:185], v[214:217], v[66:69]
	v_mfma_f32_16x16x32_bf16 v[114:117], v[178:181], v[194:197], v[114:117]
	v_mfma_f32_16x16x32_bf16 v[106:109], v[186:189], v[194:197], v[106:109]
	v_mfma_f32_16x16x32_bf16 v[98:101], v[178:181], v[202:205], v[98:101]
	v_mfma_f32_16x16x32_bf16 v[90:93], v[186:189], v[202:205], v[90:93]
	v_mfma_f32_16x16x32_bf16 v[82:85], v[178:181], v[210:213], v[82:85]
	v_mfma_f32_16x16x32_bf16 v[74:77], v[186:189], v[210:213], v[74:77]
	v_mfma_f32_16x16x32_bf16 v[70:73], v[178:181], v[218:221], v[70:73]
	v_mfma_f32_16x16x32_bf16 v[66:69], v[186:189], v[218:221], v[66:69]
	s_barrier
	s_add_i32 s28, s71, s7
	s_mov_b32 m0, s28
	ds_read_b128 v[190:193], v155 offset:49152
	ds_read_b128 v[194:197], v155 offset:50176
	ds_read_b128 v[198:201], v155 offset:51200
	ds_read_b128 v[202:205], v155 offset:52224
	ds_read_b128 v[206:209], v155 offset:53248
	ds_read_b128 v[210:213], v155 offset:54272
	ds_read_b128 v[214:217], v155 offset:55296
	ds_read_b128 v[218:221], v155 offset:56320
	global_load_lds_dwordx4 v134, s[98:99]
	s_add_i32 m0, s28, 0x2000
	s_add_u32 s26, s26, 0x40080
	s_addc_u32 s27, s27, 0
	s_add_i32 s28, s74, s7
	global_load_lds_dwordx4 v130, s[98:99]
	s_mov_b32 m0, s28
	s_nop 0
	global_load_lds_dwordx4 v134, s[26:27]
	s_add_i32 m0, s28, 0x2000
	s_nop 0
	global_load_lds_dwordx4 v130, s[26:27]
	s_mov_b32 m0, s37
	s_nop 0
	global_load_lds_dwordx4 v136, s[100:101]
	s_mov_b32 m0, s38
	s_nop 0
	global_load_lds_dwordx4 v132, s[100:101]
	s_waitcnt vmcnt(8)
	s_waitcnt lgkmcnt(0)
	s_barrier
	v_mfma_f32_16x16x32_bf16 v[62:65], v[146:149], v[190:193], v[62:65]
	v_mfma_f32_16x16x32_bf16 v[58:61], v[160:163], v[190:193], v[58:61]
	v_mfma_f32_16x16x32_bf16 v[54:57], v[146:149], v[198:201], v[54:57]
	v_mfma_f32_16x16x32_bf16 v[46:49], v[160:163], v[198:201], v[46:49]
	v_mfma_f32_16x16x32_bf16 v[38:41], v[146:149], v[206:209], v[38:41]
	v_mfma_f32_16x16x32_bf16 v[30:33], v[160:163], v[206:209], v[30:33]
	v_mfma_f32_16x16x32_bf16 v[22:25], v[146:149], v[214:217], v[22:25]
	v_mfma_f32_16x16x32_bf16 v[14:17], v[160:163], v[214:217], v[14:17]
	v_mfma_f32_16x16x32_bf16 v[62:65], v[156:159], v[194:197], v[62:65]
	v_mfma_f32_16x16x32_bf16 v[58:61], v[164:167], v[194:197], v[58:61]
	v_mfma_f32_16x16x32_bf16 v[54:57], v[156:159], v[202:205], v[54:57]
	v_mfma_f32_16x16x32_bf16 v[46:49], v[164:167], v[202:205], v[46:49]
	v_mfma_f32_16x16x32_bf16 v[38:41], v[156:159], v[210:213], v[38:41]
	v_mfma_f32_16x16x32_bf16 v[30:33], v[164:167], v[210:213], v[30:33]
	v_mfma_f32_16x16x32_bf16 v[22:25], v[156:159], v[218:221], v[22:25]
	v_mfma_f32_16x16x32_bf16 v[14:17], v[164:167], v[218:221], v[14:17]
	v_mfma_f32_16x16x32_bf16 v[50:53], v[174:177], v[190:193], v[50:53]
	v_mfma_f32_16x16x32_bf16 v[42:45], v[182:185], v[190:193], v[42:45]
	v_mfma_f32_16x16x32_bf16 v[34:37], v[174:177], v[198:201], v[34:37]
	v_mfma_f32_16x16x32_bf16 v[26:29], v[182:185], v[198:201], v[26:29]
	v_mfma_f32_16x16x32_bf16 v[18:21], v[174:177], v[206:209], v[18:21]
	v_mfma_f32_16x16x32_bf16 v[10:13], v[182:185], v[206:209], v[10:13]
	v_mfma_f32_16x16x32_bf16 v[6:9], v[174:177], v[214:217], v[6:9]
	v_mfma_f32_16x16x32_bf16 v[2:5], v[182:185], v[214:217], v[2:5]
	v_mfma_f32_16x16x32_bf16 v[50:53], v[178:181], v[194:197], v[50:53]
	v_mfma_f32_16x16x32_bf16 v[42:45], v[186:189], v[194:197], v[42:45]
	v_mfma_f32_16x16x32_bf16 v[34:37], v[178:181], v[202:205], v[34:37]
	v_mfma_f32_16x16x32_bf16 v[26:29], v[186:189], v[202:205], v[26:29]
	v_mfma_f32_16x16x32_bf16 v[18:21], v[178:181], v[210:213], v[18:21]
	v_mfma_f32_16x16x32_bf16 v[10:13], v[186:189], v[210:213], v[10:13]
	v_mfma_f32_16x16x32_bf16 v[6:9], v[178:181], v[218:221], v[6:9]
	v_mfma_f32_16x16x32_bf16 v[2:5], v[186:189], v[218:221], v[2:5]
	s_barrier
	s_add_i32 s70, s70, 2
	s_add_u32 s24, s24, 0x100
	s_addc_u32 s25, s25, 0
	s_add_u32 s46, s46, 0x100
	s_addc_u32 s47, s47, 0
	s_cmp_gt_u32 s70, 13
.LBB0_212:
	ds_read_b128 v[146:149], v153
	ds_read_b128 v[156:159], v153 offset:1024
	ds_read_b128 v[160:163], v153 offset:2048
	ds_read_b128 v[164:167], v153 offset:3072
	ds_read_b128 v[174:177], v154
	ds_read_b128 v[178:181], v154 offset:1024
	ds_read_b128 v[182:185], v154 offset:2048
	ds_read_b128 v[186:189], v154 offset:3072
	s_add_u32 s26, s24, 0xfffc0080
	s_addc_u32 s27, s25, -1
	s_cmp_eq_u32 s70, 12
	s_cselect_b32 s29, s17, s27
	s_cselect_b32 s28, s44, s26
	s_cselect_b32 s27, s15, s47
	s_cselect_b32 s26, s45, s46
	s_add_i32 m0, s23, 0xc000
	ds_read_b128 v[190:193], v155
	ds_read_b128 v[194:197], v155 offset:1024
	ds_read_b128 v[198:201], v155 offset:2048
	ds_read_b128 v[202:205], v155 offset:3072
	ds_read_b128 v[206:209], v155 offset:4096
	ds_read_b128 v[210:213], v155 offset:5120
	ds_read_b128 v[214:217], v155 offset:6144
	ds_read_b128 v[218:221], v155 offset:7168
	global_load_lds_dwordx4 v138, s[24:25]
	s_add_i32 m0, s23, 0xe000
	s_nop 0
	global_load_lds_dwordx4 v140, s[24:25]
	s_waitcnt vmcnt(8)
	s_waitcnt lgkmcnt(0)
	s_barrier
	v_mfma_f32_16x16x32_bf16 v[126:129], v[146:149], v[190:193], v[126:129]
	v_mfma_f32_16x16x32_bf16 v[122:125], v[160:163], v[190:193], v[122:125]
	v_mfma_f32_16x16x32_bf16 v[118:121], v[146:149], v[198:201], v[118:121]
	v_mfma_f32_16x16x32_bf16 v[110:113], v[160:163], v[198:201], v[110:113]
	v_mfma_f32_16x16x32_bf16 v[102:105], v[146:149], v[206:209], v[102:105]
	v_mfma_f32_16x16x32_bf16 v[94:97], v[160:163], v[206:209], v[94:97]
	v_mfma_f32_16x16x32_bf16 v[86:89], v[146:149], v[214:217], v[86:89]
	v_mfma_f32_16x16x32_bf16 v[78:81], v[160:163], v[214:217], v[78:81]
	v_mfma_f32_16x16x32_bf16 v[126:129], v[156:159], v[194:197], v[126:129]
	v_mfma_f32_16x16x32_bf16 v[122:125], v[164:167], v[194:197], v[122:125]
	v_mfma_f32_16x16x32_bf16 v[118:121], v[156:159], v[202:205], v[118:121]
	v_mfma_f32_16x16x32_bf16 v[110:113], v[164:167], v[202:205], v[110:113]
	v_mfma_f32_16x16x32_bf16 v[102:105], v[156:159], v[210:213], v[102:105]
	v_mfma_f32_16x16x32_bf16 v[94:97], v[164:167], v[210:213], v[94:97]
	v_mfma_f32_16x16x32_bf16 v[86:89], v[156:159], v[218:221], v[86:89]
	v_mfma_f32_16x16x32_bf16 v[78:81], v[164:167], v[218:221], v[78:81]
	v_mfma_f32_16x16x32_bf16 v[114:117], v[174:177], v[190:193], v[114:117]
	v_mfma_f32_16x16x32_bf16 v[106:109], v[182:185], v[190:193], v[106:109]
	v_mfma_f32_16x16x32_bf16 v[98:101], v[174:177], v[198:201], v[98:101]
	v_mfma_f32_16x16x32_bf16 v[90:93], v[182:185], v[198:201], v[90:93]
	v_mfma_f32_16x16x32_bf16 v[82:85], v[174:177], v[206:209], v[82:85]
	v_mfma_f32_16x16x32_bf16 v[74:77], v[182:185], v[206:209], v[74:77]
	v_mfma_f32_16x16x32_bf16 v[70:73], v[174:177], v[214:217], v[70:73]
	v_mfma_f32_16x16x32_bf16 v[66:69], v[182:185], v[214:217], v[66:69]
	v_mfma_f32_16x16x32_bf16 v[114:117], v[178:181], v[194:197], v[114:117]
	v_mfma_f32_16x16x32_bf16 v[106:109], v[186:189], v[194:197], v[106:109]
	v_mfma_f32_16x16x32_bf16 v[98:101], v[178:181], v[202:205], v[98:101]
	v_mfma_f32_16x16x32_bf16 v[90:93], v[186:189], v[202:205], v[90:93]
	v_mfma_f32_16x16x32_bf16 v[82:85], v[178:181], v[210:213], v[82:85]
	v_mfma_f32_16x16x32_bf16 v[74:77], v[186:189], v[210:213], v[74:77]
	v_mfma_f32_16x16x32_bf16 v[70:73], v[178:181], v[218:221], v[70:73]
	v_mfma_f32_16x16x32_bf16 v[66:69], v[186:189], v[218:221], v[66:69]
	s_barrier
	s_add_u32 s98, s26, 0x80
	s_addc_u32 s99, s27, 0
	s_add_u32 s100, s28, 0x80
	s_addc_u32 s101, s29, 0
	s_add_i32 s71, s40, s7
	s_mov_b32 m0, s71
	ds_read_b128 v[190:193], v155 offset:16384
	ds_read_b128 v[194:197], v155 offset:17408
	ds_read_b128 v[198:201], v155 offset:18432
	ds_read_b128 v[202:205], v155 offset:19456
	ds_read_b128 v[206:209], v155 offset:20480
	ds_read_b128 v[210:213], v155 offset:21504
	ds_read_b128 v[214:217], v155 offset:22528
	ds_read_b128 v[218:221], v155 offset:23552
	global_load_lds_dwordx4 v134, s[26:27]
	s_add_i32 m0, s71, 0x2000
	s_add_u32 s74, s26, 0x40000
	s_addc_u32 s75, s27, 0
	s_add_i32 s71, s41, s7
	global_load_lds_dwordx4 v130, s[26:27]
	s_mov_b32 m0, s71
	s_nop 0
	global_load_lds_dwordx4 v134, s[74:75]
	s_add_i32 m0, s71, 0x2000
	s_nop 0
	global_load_lds_dwordx4 v130, s[74:75]
	s_mov_b32 m0, s23
	s_nop 0
	global_load_lds_dwordx4 v136, s[28:29]
	s_mov_b32 m0, s31
	s_nop 0
	global_load_lds_dwordx4 v132, s[28:29]
	s_waitcnt vmcnt(8)
	s_waitcnt lgkmcnt(0)
	s_barrier
	v_mfma_f32_16x16x32_bf16 v[62:65], v[146:149], v[190:193], v[62:65]
	v_mfma_f32_16x16x32_bf16 v[58:61], v[160:163], v[190:193], v[58:61]
	v_mfma_f32_16x16x32_bf16 v[54:57], v[146:149], v[198:201], v[54:57]
	v_mfma_f32_16x16x32_bf16 v[46:49], v[160:163], v[198:201], v[46:49]
	v_mfma_f32_16x16x32_bf16 v[38:41], v[146:149], v[206:209], v[38:41]
	v_mfma_f32_16x16x32_bf16 v[30:33], v[160:163], v[206:209], v[30:33]
	v_mfma_f32_16x16x32_bf16 v[22:25], v[146:149], v[214:217], v[22:25]
	v_mfma_f32_16x16x32_bf16 v[14:17], v[160:163], v[214:217], v[14:17]
	v_mfma_f32_16x16x32_bf16 v[62:65], v[156:159], v[194:197], v[62:65]
	v_mfma_f32_16x16x32_bf16 v[58:61], v[164:167], v[194:197], v[58:61]
	v_mfma_f32_16x16x32_bf16 v[54:57], v[156:159], v[202:205], v[54:57]
	v_mfma_f32_16x16x32_bf16 v[46:49], v[164:167], v[202:205], v[46:49]
	v_mfma_f32_16x16x32_bf16 v[38:41], v[156:159], v[210:213], v[38:41]
	v_mfma_f32_16x16x32_bf16 v[30:33], v[164:167], v[210:213], v[30:33]
	v_mfma_f32_16x16x32_bf16 v[22:25], v[156:159], v[218:221], v[22:25]
	v_mfma_f32_16x16x32_bf16 v[14:17], v[164:167], v[218:221], v[14:17]
	v_mfma_f32_16x16x32_bf16 v[50:53], v[174:177], v[190:193], v[50:53]
	v_mfma_f32_16x16x32_bf16 v[42:45], v[182:185], v[190:193], v[42:45]
	v_mfma_f32_16x16x32_bf16 v[34:37], v[174:177], v[198:201], v[34:37]
	v_mfma_f32_16x16x32_bf16 v[26:29], v[182:185], v[198:201], v[26:29]
	v_mfma_f32_16x16x32_bf16 v[18:21], v[174:177], v[206:209], v[18:21]
	v_mfma_f32_16x16x32_bf16 v[10:13], v[182:185], v[206:209], v[10:13]
	v_mfma_f32_16x16x32_bf16 v[6:9], v[174:177], v[214:217], v[6:9]
	v_mfma_f32_16x16x32_bf16 v[2:5], v[182:185], v[214:217], v[2:5]
	v_mfma_f32_16x16x32_bf16 v[50:53], v[178:181], v[194:197], v[50:53]
	v_mfma_f32_16x16x32_bf16 v[42:45], v[186:189], v[194:197], v[42:45]
	v_mfma_f32_16x16x32_bf16 v[34:37], v[178:181], v[202:205], v[34:37]
	v_mfma_f32_16x16x32_bf16 v[26:29], v[186:189], v[202:205], v[26:29]
	v_mfma_f32_16x16x32_bf16 v[18:21], v[178:181], v[210:213], v[18:21]
	v_mfma_f32_16x16x32_bf16 v[10:13], v[186:189], v[210:213], v[10:13]
	v_mfma_f32_16x16x32_bf16 v[6:9], v[178:181], v[218:221], v[6:9]
	v_mfma_f32_16x16x32_bf16 v[2:5], v[186:189], v[218:221], v[2:5]
	s_barrier
	s_add_i32 s71, 0, 0x18000
	v_add_u32_e32 v1, s71, v151
	s_add_i32 s74, 0, 0x1c000
	ds_read_b128 v[146:149], v1
	ds_read_b128 v[156:159], v1 offset:1024
	ds_read_b128 v[160:163], v1 offset:2048
	ds_read_b128 v[164:167], v1 offset:3072
	v_add_u32_e32 v1, s74, v151
	ds_read_b128 v[174:177], v1
	ds_read_b128 v[178:181], v1 offset:1024
	ds_read_b128 v[182:185], v1 offset:2048
	ds_read_b128 v[186:189], v1 offset:3072
	s_add_u32 s28, s28, 0x40000
	s_addc_u32 s29, s29, 0
	s_mov_b32 m0, s34
	ds_read_b128 v[190:193], v155 offset:32768
	ds_read_b128 v[194:197], v155 offset:33792
	ds_read_b128 v[198:201], v155 offset:34816
	ds_read_b128 v[202:205], v155 offset:35840
	ds_read_b128 v[206:209], v155 offset:36864
	ds_read_b128 v[210:213], v155 offset:37888
	ds_read_b128 v[214:217], v155 offset:38912
	ds_read_b128 v[218:221], v155 offset:39936
	global_load_lds_dwordx4 v136, s[28:29]
	s_mov_b32 m0, s35
	s_nop 0
	global_load_lds_dwordx4 v132, s[28:29]
	s_waitcnt vmcnt(8)
	s_waitcnt lgkmcnt(0)
	s_barrier
	v_mfma_f32_16x16x32_bf16 v[126:129], v[146:149], v[190:193], v[126:129]
	v_mfma_f32_16x16x32_bf16 v[122:125], v[160:163], v[190:193], v[122:125]
	v_mfma_f32_16x16x32_bf16 v[118:121], v[146:149], v[198:201], v[118:121]
	v_mfma_f32_16x16x32_bf16 v[110:113], v[160:163], v[198:201], v[110:113]
	v_mfma_f32_16x16x32_bf16 v[102:105], v[146:149], v[206:209], v[102:105]
	v_mfma_f32_16x16x32_bf16 v[94:97], v[160:163], v[206:209], v[94:97]
	v_mfma_f32_16x16x32_bf16 v[86:89], v[146:149], v[214:217], v[86:89]
	v_mfma_f32_16x16x32_bf16 v[78:81], v[160:163], v[214:217], v[78:81]
	v_mfma_f32_16x16x32_bf16 v[126:129], v[156:159], v[194:197], v[126:129]
	v_mfma_f32_16x16x32_bf16 v[122:125], v[164:167], v[194:197], v[122:125]
	v_mfma_f32_16x16x32_bf16 v[118:121], v[156:159], v[202:205], v[118:121]
	v_mfma_f32_16x16x32_bf16 v[110:113], v[164:167], v[202:205], v[110:113]
	v_mfma_f32_16x16x32_bf16 v[102:105], v[156:159], v[210:213], v[102:105]
	v_mfma_f32_16x16x32_bf16 v[94:97], v[164:167], v[210:213], v[94:97]
	v_mfma_f32_16x16x32_bf16 v[86:89], v[156:159], v[218:221], v[86:89]
	v_mfma_f32_16x16x32_bf16 v[78:81], v[164:167], v[218:221], v[78:81]
	v_mfma_f32_16x16x32_bf16 v[114:117], v[174:177], v[190:193], v[114:117]
	v_mfma_f32_16x16x32_bf16 v[106:109], v[182:185], v[190:193], v[106:109]
	v_mfma_f32_16x16x32_bf16 v[98:101], v[174:177], v[198:201], v[98:101]
	v_mfma_f32_16x16x32_bf16 v[90:93], v[182:185], v[198:201], v[90:93]
	v_mfma_f32_16x16x32_bf16 v[82:85], v[174:177], v[206:209], v[82:85]
	v_mfma_f32_16x16x32_bf16 v[74:77], v[182:185], v[206:209], v[74:77]
	v_mfma_f32_16x16x32_bf16 v[70:73], v[174:177], v[214:217], v[70:73]
	v_mfma_f32_16x16x32_bf16 v[66:69], v[182:185], v[214:217], v[66:69]
	v_mfma_f32_16x16x32_bf16 v[114:117], v[178:181], v[194:197], v[114:117]
	v_mfma_f32_16x16x32_bf16 v[106:109], v[186:189], v[194:197], v[106:109]
	v_mfma_f32_16x16x32_bf16 v[98:101], v[178:181], v[202:205], v[98:101]
	v_mfma_f32_16x16x32_bf16 v[90:93], v[186:189], v[202:205], v[90:93]
	v_mfma_f32_16x16x32_bf16 v[82:85], v[178:181], v[210:213], v[82:85]
	v_mfma_f32_16x16x32_bf16 v[74:77], v[186:189], v[210:213], v[74:77]
	v_mfma_f32_16x16x32_bf16 v[70:73], v[178:181], v[218:221], v[70:73]
	v_mfma_f32_16x16x32_bf16 v[66:69], v[186:189], v[218:221], v[66:69]
	s_barrier
	s_add_i32 s28, s71, s7
	s_mov_b32 m0, s28
	ds_read_b128 v[190:193], v155 offset:49152
	ds_read_b128 v[194:197], v155 offset:50176
	ds_read_b128 v[198:201], v155 offset:51200
	ds_read_b128 v[202:205], v155 offset:52224
	ds_read_b128 v[206:209], v155 offset:53248
	ds_read_b128 v[210:213], v155 offset:54272
	ds_read_b128 v[214:217], v155 offset:55296
	ds_read_b128 v[218:221], v155 offset:56320
	global_load_lds_dwordx4 v134, s[98:99]
	s_add_i32 m0, s28, 0x2000
	s_add_u32 s26, s26, 0x40080
	s_addc_u32 s27, s27, 0
	s_add_i32 s28, s74, s7
	global_load_lds_dwordx4 v130, s[98:99]
	s_mov_b32 m0, s28
	s_nop 0
	global_load_lds_dwordx4 v134, s[26:27]
	s_add_i32 m0, s28, 0x2000
	s_nop 0
	global_load_lds_dwordx4 v130, s[26:27]
	s_mov_b32 m0, s37
	s_nop 0
	global_load_lds_dwordx4 v136, s[100:101]
	s_mov_b32 m0, s38
	s_nop 0
	global_load_lds_dwordx4 v132, s[100:101]
	s_waitcnt vmcnt(8)
	s_waitcnt lgkmcnt(0)
	s_barrier
	v_mfma_f32_16x16x32_bf16 v[62:65], v[146:149], v[190:193], v[62:65]
	v_mfma_f32_16x16x32_bf16 v[58:61], v[160:163], v[190:193], v[58:61]
	v_mfma_f32_16x16x32_bf16 v[54:57], v[146:149], v[198:201], v[54:57]
	v_mfma_f32_16x16x32_bf16 v[46:49], v[160:163], v[198:201], v[46:49]
	v_mfma_f32_16x16x32_bf16 v[38:41], v[146:149], v[206:209], v[38:41]
	v_mfma_f32_16x16x32_bf16 v[30:33], v[160:163], v[206:209], v[30:33]
	v_mfma_f32_16x16x32_bf16 v[22:25], v[146:149], v[214:217], v[22:25]
	v_mfma_f32_16x16x32_bf16 v[14:17], v[160:163], v[214:217], v[14:17]
	v_mfma_f32_16x16x32_bf16 v[62:65], v[156:159], v[194:197], v[62:65]
	v_mfma_f32_16x16x32_bf16 v[58:61], v[164:167], v[194:197], v[58:61]
	v_mfma_f32_16x16x32_bf16 v[54:57], v[156:159], v[202:205], v[54:57]
	v_mfma_f32_16x16x32_bf16 v[46:49], v[164:167], v[202:205], v[46:49]
	v_mfma_f32_16x16x32_bf16 v[38:41], v[156:159], v[210:213], v[38:41]
	v_mfma_f32_16x16x32_bf16 v[30:33], v[164:167], v[210:213], v[30:33]
	v_mfma_f32_16x16x32_bf16 v[22:25], v[156:159], v[218:221], v[22:25]
	v_mfma_f32_16x16x32_bf16 v[14:17], v[164:167], v[218:221], v[14:17]
	v_mfma_f32_16x16x32_bf16 v[50:53], v[174:177], v[190:193], v[50:53]
	v_mfma_f32_16x16x32_bf16 v[42:45], v[182:185], v[190:193], v[42:45]
	v_mfma_f32_16x16x32_bf16 v[34:37], v[174:177], v[198:201], v[34:37]
	v_mfma_f32_16x16x32_bf16 v[26:29], v[182:185], v[198:201], v[26:29]
	v_mfma_f32_16x16x32_bf16 v[18:21], v[174:177], v[206:209], v[18:21]
	v_mfma_f32_16x16x32_bf16 v[10:13], v[182:185], v[206:209], v[10:13]
	v_mfma_f32_16x16x32_bf16 v[6:9], v[174:177], v[214:217], v[6:9]
	v_mfma_f32_16x16x32_bf16 v[2:5], v[182:185], v[214:217], v[2:5]
	v_mfma_f32_16x16x32_bf16 v[50:53], v[178:181], v[194:197], v[50:53]
	v_mfma_f32_16x16x32_bf16 v[42:45], v[186:189], v[194:197], v[42:45]
	v_mfma_f32_16x16x32_bf16 v[34:37], v[178:181], v[202:205], v[34:37]
	v_mfma_f32_16x16x32_bf16 v[26:29], v[186:189], v[202:205], v[26:29]
	v_mfma_f32_16x16x32_bf16 v[18:21], v[178:181], v[210:213], v[18:21]
	v_mfma_f32_16x16x32_bf16 v[10:13], v[186:189], v[210:213], v[10:13]
	v_mfma_f32_16x16x32_bf16 v[6:9], v[178:181], v[218:221], v[6:9]
	v_mfma_f32_16x16x32_bf16 v[2:5], v[186:189], v[218:221], v[2:5]
	s_barrier
	s_add_i32 s70, s70, 2
	s_add_u32 s24, s24, 0x100
	s_addc_u32 s25, s25, 0
	s_add_u32 s46, s46, 0x100
	s_addc_u32 s47, s47, 0
	s_cmp_gt_u32 s70, 13
	s_cbranch_scc0 .LBB0_212
	s_and_b64 vcc, exec, s[12:13]
	s_cbranch_vccz .LBB0_215
	s_barrier

.LBB0_449:
	s_ashr_i32 s21, s20, 31
	s_lshl_b64 s[22:23], s[20:21], 19
	s_add_u32 s22, s52, s22
	s_addc_u32 s23, s53, s23
	s_and_b64 s[24:25], s[4:5], exec
	s_cselect_b32 s21, s23, s31
	s_cselect_b32 s27, s22, s30
	s_ashr_i32 s19, s18, 31
	s_lshl_b64 s[24:25], s[18:19], 19
	s_add_u32 s24, s3, s24
	s_addc_u32 s25, s6, s25
	s_and_b64 s[36:37], s[4:5], exec
	s_cselect_b32 s19, s25, s35
	s_cselect_b32 s29, s24, s34
	s_add_u32 s30, s30, 0x40080
	s_addc_u32 s31, s31, 0
	s_add_u32 s55, s34, 0x100
	s_addc_u32 s70, s35, 0
	s_mov_b32 s71, -2
	s_waitcnt lgkmcnt(0)
	ds_read_b128 v[98:101], v213
	ds_read_b128 v[102:105], v213 offset:1024
	ds_read_b128 v[106:109], v213 offset:2048
	ds_read_b128 v[110:113], v213 offset:3072
	ds_read_b128 v[146:149], v214
	ds_read_b128 v[150:153], v214 offset:1024
	ds_read_b128 v[154:157], v214 offset:2048
	ds_read_b128 v[158:161], v214 offset:3072
	s_add_u32 s34, s30, 0xfffc0080
	s_addc_u32 s35, s31, -1
	s_cmp_eq_u32 s71, 12
	s_cselect_b32 s37, s21, s35
	s_cselect_b32 s36, s27, s34
	s_cselect_b32 s35, s19, s70
	s_cselect_b32 s34, s29, s55
	s_add_i32 m0, s38, 0xc000
	ds_read_b128 v[182:185], v215
	ds_read_b128 v[186:189], v215 offset:1024
	ds_read_b128 v[190:193], v215 offset:2048
	ds_read_b128 v[194:197], v215 offset:3072
	ds_read_b128 v[198:201], v215 offset:4096
	ds_read_b128 v[202:205], v215 offset:5120
	ds_read_b128 v[206:209], v215 offset:6144
	ds_read_b128 v[218:221], v215 offset:7168
	global_load_lds_dwordx4 v174, s[30:31]
	s_add_i32 m0, s38, 0xe000
	s_nop 0
	global_load_lds_dwordx4 v176, s[30:31]
	s_waitcnt vmcnt(8)
	s_waitcnt lgkmcnt(0)
	s_barrier
	v_mfma_f32_16x16x32_bf16 v[142:145], v[98:101], v[182:185], 0
	v_mfma_f32_16x16x32_bf16 v[138:141], v[106:109], v[182:185], 0
	v_mfma_f32_16x16x32_bf16 v[126:129], v[98:101], v[190:193], 0
	v_mfma_f32_16x16x32_bf16 v[122:125], v[106:109], v[190:193], 0
	v_mfma_f32_16x16x32_bf16 v[94:97], v[98:101], v[198:201], 0
	v_mfma_f32_16x16x32_bf16 v[90:93], v[106:109], v[198:201], 0
	v_mfma_f32_16x16x32_bf16 v[78:81], v[98:101], v[206:209], 0
	v_mfma_f32_16x16x32_bf16 v[74:77], v[106:109], v[206:209], 0
	v_mfma_f32_16x16x32_bf16 v[142:145], v[102:105], v[186:189], v[142:145]
	v_mfma_f32_16x16x32_bf16 v[138:141], v[110:113], v[186:189], v[138:141]
	v_mfma_f32_16x16x32_bf16 v[126:129], v[102:105], v[194:197], v[126:129]
	v_mfma_f32_16x16x32_bf16 v[122:125], v[110:113], v[194:197], v[122:125]
	v_mfma_f32_16x16x32_bf16 v[94:97], v[102:105], v[202:205], v[94:97]
	v_mfma_f32_16x16x32_bf16 v[90:93], v[110:113], v[202:205], v[90:93]
	v_mfma_f32_16x16x32_bf16 v[78:81], v[102:105], v[218:221], v[78:81]
	v_mfma_f32_16x16x32_bf16 v[74:77], v[110:113], v[218:221], v[74:77]
	v_mfma_f32_16x16x32_bf16 v[134:137], v[146:149], v[182:185], 0
	v_mfma_f32_16x16x32_bf16 v[130:133], v[154:157], v[182:185], 0
	v_mfma_f32_16x16x32_bf16 v[118:121], v[146:149], v[190:193], 0
	v_mfma_f32_16x16x32_bf16 v[114:117], v[154:157], v[190:193], 0
	v_mfma_f32_16x16x32_bf16 v[86:89], v[146:149], v[198:201], 0
	v_mfma_f32_16x16x32_bf16 v[82:85], v[154:157], v[198:201], 0
	v_mfma_f32_16x16x32_bf16 v[70:73], v[146:149], v[206:209], 0
	v_mfma_f32_16x16x32_bf16 v[66:69], v[154:157], v[206:209], 0
	v_mfma_f32_16x16x32_bf16 v[134:137], v[150:153], v[186:189], v[134:137]
	v_mfma_f32_16x16x32_bf16 v[130:133], v[158:161], v[186:189], v[130:133]
	v_mfma_f32_16x16x32_bf16 v[118:121], v[150:153], v[194:197], v[118:121]
	v_mfma_f32_16x16x32_bf16 v[114:117], v[158:161], v[194:197], v[114:117]
	v_mfma_f32_16x16x32_bf16 v[86:89], v[150:153], v[202:205], v[86:89]
	v_mfma_f32_16x16x32_bf16 v[82:85], v[158:161], v[202:205], v[82:85]
	v_mfma_f32_16x16x32_bf16 v[70:73], v[150:153], v[218:221], v[70:73]
	v_mfma_f32_16x16x32_bf16 v[66:69], v[158:161], v[218:221], v[66:69]
	s_barrier
	s_add_u32 s98, s34, 0x80
	s_addc_u32 s99, s35, 0
	s_add_u32 s100, s36, 0x80
	s_addc_u32 s101, s37, 0
	s_add_i32 s74, s51, s7
	s_mov_b32 m0, s74
	ds_read_b128 v[182:185], v215 offset:16384
	ds_read_b128 v[186:189], v215 offset:17408
	ds_read_b128 v[190:193], v215 offset:18432
	ds_read_b128 v[194:197], v215 offset:19456
	ds_read_b128 v[198:201], v215 offset:20480
	ds_read_b128 v[202:205], v215 offset:21504
	ds_read_b128 v[206:209], v215 offset:22528
	ds_read_b128 v[218:221], v215 offset:23552
	s_cmp_eq_u32 s71, 12
	s_cselect_b64 exec, 0, -1
	s_cmp_lg_u32 s33, 0x100
	s_cselect_b64 exec, -1, exec
	global_load_lds_dwordx4 v164, s[34:35]
	s_add_i32 m0, s74, 0x2000
	s_add_u32 s74, s34, 0x40000
	s_addc_u32 s75, s35, 0
	s_add_i32 s76, s54, s7
	global_load_lds_dwordx4 v168, s[34:35]
	s_mov_b32 m0, s76
	s_nop 0
	global_load_lds_dwordx4 v164, s[74:75]
	s_add_i32 m0, s76, 0x2000
	s_nop 0
	global_load_lds_dwordx4 v168, s[74:75]
	s_mov_b32 m0, s38
	s_nop 0
	global_load_lds_dwordx4 v162, s[36:37]
	s_mov_b32 m0, s39
	s_nop 0
	global_load_lds_dwordx4 v166, s[36:37]
	s_mov_b64 exec, -1
	s_waitcnt vmcnt(8)
	s_waitcnt lgkmcnt(0)
	s_barrier
	v_mfma_f32_16x16x32_bf16 v[62:65], v[98:101], v[182:185], 0
	v_mfma_f32_16x16x32_bf16 v[58:61], v[106:109], v[182:185], 0
	v_mfma_f32_16x16x32_bf16 v[46:49], v[98:101], v[190:193], 0
	v_mfma_f32_16x16x32_bf16 v[42:45], v[106:109], v[190:193], 0
	v_mfma_f32_16x16x32_bf16 v[30:33], v[98:101], v[198:201], 0
	v_mfma_f32_16x16x32_bf16 v[26:29], v[106:109], v[198:201], 0
	v_mfma_f32_16x16x32_bf16 v[14:17], v[98:101], v[206:209], 0
	v_mfma_f32_16x16x32_bf16 v[10:13], v[106:109], v[206:209], 0
	v_mfma_f32_16x16x32_bf16 v[62:65], v[102:105], v[186:189], v[62:65]
	v_mfma_f32_16x16x32_bf16 v[58:61], v[110:113], v[186:189], v[58:61]
	v_mfma_f32_16x16x32_bf16 v[46:49], v[102:105], v[194:197], v[46:49]
	v_mfma_f32_16x16x32_bf16 v[42:45], v[110:113], v[194:197], v[42:45]
	v_mfma_f32_16x16x32_bf16 v[30:33], v[102:105], v[202:205], v[30:33]
	v_mfma_f32_16x16x32_bf16 v[26:29], v[110:113], v[202:205], v[26:29]
	v_mfma_f32_16x16x32_bf16 v[14:17], v[102:105], v[218:221], v[14:17]
	v_mfma_f32_16x16x32_bf16 v[10:13], v[110:113], v[218:221], v[10:13]
	v_mfma_f32_16x16x32_bf16 v[54:57], v[146:149], v[182:185], 0
	v_mfma_f32_16x16x32_bf16 v[50:53], v[154:157], v[182:185], 0
	v_mfma_f32_16x16x32_bf16 v[38:41], v[146:149], v[190:193], 0
	v_mfma_f32_16x16x32_bf16 v[34:37], v[154:157], v[190:193], 0
	v_mfma_f32_16x16x32_bf16 v[22:25], v[146:149], v[198:201], 0
	v_mfma_f32_16x16x32_bf16 v[18:21], v[154:157], v[198:201], 0
	v_mfma_f32_16x16x32_bf16 v[6:9], v[146:149], v[206:209], 0
	v_mfma_f32_16x16x32_bf16 v[2:5], v[154:157], v[206:209], 0
	v_mfma_f32_16x16x32_bf16 v[54:57], v[150:153], v[186:189], v[54:57]
	v_mfma_f32_16x16x32_bf16 v[50:53], v[158:161], v[186:189], v[50:53]
	v_mfma_f32_16x16x32_bf16 v[38:41], v[150:153], v[194:197], v[38:41]
	v_mfma_f32_16x16x32_bf16 v[34:37], v[158:161], v[194:197], v[34:37]
	v_mfma_f32_16x16x32_bf16 v[22:25], v[150:153], v[202:205], v[22:25]
	v_mfma_f32_16x16x32_bf16 v[18:21], v[158:161], v[202:205], v[18:21]
	v_mfma_f32_16x16x32_bf16 v[6:9], v[150:153], v[218:221], v[6:9]
	v_mfma_f32_16x16x32_bf16 v[2:5], v[158:161], v[218:221], v[2:5]
	s_barrier
	s_add_i32 s74, 0, 0x18000
	v_add_u32_e32 v1, s74, v173
	s_add_i32 s75, 0, 0x1c000
	ds_read_b128 v[98:101], v1
	ds_read_b128 v[102:105], v1 offset:1024
	ds_read_b128 v[106:109], v1 offset:2048
	ds_read_b128 v[110:113], v1 offset:3072
	v_add_u32_e32 v1, s75, v173
	ds_read_b128 v[146:149], v1
	ds_read_b128 v[150:153], v1 offset:1024
	ds_read_b128 v[154:157], v1 offset:2048
	ds_read_b128 v[158:161], v1 offset:3072
	s_add_u32 s36, s36, 0x40000
	s_addc_u32 s37, s37, 0
	s_mov_b32 m0, s40
	ds_read_b128 v[182:185], v215 offset:32768
	ds_read_b128 v[186:189], v215 offset:33792
	ds_read_b128 v[190:193], v215 offset:34816
	ds_read_b128 v[194:197], v215 offset:35840
	ds_read_b128 v[198:201], v215 offset:36864
	ds_read_b128 v[202:205], v215 offset:37888
	ds_read_b128 v[206:209], v215 offset:38912
	ds_read_b128 v[218:221], v215 offset:39936
	s_cmp_eq_u32 s71, 12
	s_cselect_b64 exec, 0, -1
	s_cmp_lg_u32 s33, 0x100
	s_cselect_b64 exec, -1, exec
	global_load_lds_dwordx4 v162, s[36:37]
	s_mov_b32 m0, s41
	s_nop 0
	global_load_lds_dwordx4 v166, s[36:37]
	s_mov_b64 exec, -1
	s_waitcnt vmcnt(8)
	s_waitcnt lgkmcnt(0)
	s_barrier
	v_mfma_f32_16x16x32_bf16 v[142:145], v[98:101], v[182:185], v[142:145]
	v_mfma_f32_16x16x32_bf16 v[138:141], v[106:109], v[182:185], v[138:141]
	v_mfma_f32_16x16x32_bf16 v[126:129], v[98:101], v[190:193], v[126:129]
	v_mfma_f32_16x16x32_bf16 v[122:125], v[106:109], v[190:193], v[122:125]
	v_mfma_f32_16x16x32_bf16 v[94:97], v[98:101], v[198:201], v[94:97]
	v_mfma_f32_16x16x32_bf16 v[90:93], v[106:109], v[198:201], v[90:93]
	v_mfma_f32_16x16x32_bf16 v[78:81], v[98:101], v[206:209], v[78:81]
	v_mfma_f32_16x16x32_bf16 v[74:77], v[106:109], v[206:209], v[74:77]
	v_mfma_f32_16x16x32_bf16 v[142:145], v[102:105], v[186:189], v[142:145]
	v_mfma_f32_16x16x32_bf16 v[138:141], v[110:113], v[186:189], v[138:141]
	v_mfma_f32_16x16x32_bf16 v[126:129], v[102:105], v[194:197], v[126:129]
	v_mfma_f32_16x16x32_bf16 v[122:125], v[110:113], v[194:197], v[122:125]
	v_mfma_f32_16x16x32_bf16 v[94:97], v[102:105], v[202:205], v[94:97]
	v_mfma_f32_16x16x32_bf16 v[90:93], v[110:113], v[202:205], v[90:93]
	v_mfma_f32_16x16x32_bf16 v[78:81], v[102:105], v[218:221], v[78:81]
	v_mfma_f32_16x16x32_bf16 v[74:77], v[110:113], v[218:221], v[74:77]
	v_mfma_f32_16x16x32_bf16 v[134:137], v[146:149], v[182:185], v[134:137]
	v_mfma_f32_16x16x32_bf16 v[130:133], v[154:157], v[182:185], v[130:133]
	v_mfma_f32_16x16x32_bf16 v[118:121], v[146:149], v[190:193], v[118:121]
	v_mfma_f32_16x16x32_bf16 v[114:117], v[154:157], v[190:193], v[114:117]
	v_mfma_f32_16x16x32_bf16 v[86:89], v[146:149], v[198:201], v[86:89]
	v_mfma_f32_16x16x32_bf16 v[82:85], v[154:157], v[198:201], v[82:85]
	v_mfma_f32_16x16x32_bf16 v[70:73], v[146:149], v[206:209], v[70:73]
	v_mfma_f32_16x16x32_bf16 v[66:69], v[154:157], v[206:209], v[66:69]
	v_mfma_f32_16x16x32_bf16 v[134:137], v[150:153], v[186:189], v[134:137]
	v_mfma_f32_16x16x32_bf16 v[130:133], v[158:161], v[186:189], v[130:133]
	v_mfma_f32_16x16x32_bf16 v[118:121], v[150:153], v[194:197], v[118:121]
	v_mfma_f32_16x16x32_bf16 v[114:117], v[158:161], v[194:197], v[114:117]
	v_mfma_f32_16x16x32_bf16 v[86:89], v[150:153], v[202:205], v[86:89]
	v_mfma_f32_16x16x32_bf16 v[82:85], v[158:161], v[202:205], v[82:85]
	v_mfma_f32_16x16x32_bf16 v[70:73], v[150:153], v[218:221], v[70:73]
	v_mfma_f32_16x16x32_bf16 v[66:69], v[158:161], v[218:221], v[66:69]
	s_barrier
	s_add_i32 s36, s74, s7
	s_mov_b32 m0, s36
	ds_read_b128 v[182:185], v215 offset:49152
	ds_read_b128 v[186:189], v215 offset:50176
	ds_read_b128 v[190:193], v215 offset:51200
	ds_read_b128 v[194:197], v215 offset:52224
	ds_read_b128 v[198:201], v215 offset:53248
	ds_read_b128 v[202:205], v215 offset:54272
	ds_read_b128 v[206:209], v215 offset:55296
	ds_read_b128 v[218:221], v215 offset:56320
	s_cmp_eq_u32 s71, 12
	s_cselect_b64 exec, 0, -1
	s_cmp_lg_u32 s33, 0x100
	s_cselect_b64 exec, -1, exec
	global_load_lds_dwordx4 v164, s[98:99]
	s_add_i32 m0, s36, 0x2000
	s_add_u32 s34, s34, 0x40080
	s_addc_u32 s35, s35, 0
	s_add_i32 s36, s75, s7
	global_load_lds_dwordx4 v168, s[98:99]
	s_mov_b32 m0, s36
	s_nop 0
	global_load_lds_dwordx4 v164, s[34:35]
	s_add_i32 m0, s36, 0x2000
	s_nop 0
	global_load_lds_dwordx4 v168, s[34:35]
	s_mov_b32 m0, s47
	s_nop 0
	global_load_lds_dwordx4 v162, s[100:101]
	s_mov_b32 m0, s48
	s_nop 0
	global_load_lds_dwordx4 v166, s[100:101]
	s_mov_b64 exec, -1
	s_waitcnt vmcnt(8)
	s_waitcnt lgkmcnt(0)
	s_barrier
	v_mfma_f32_16x16x32_bf16 v[62:65], v[98:101], v[182:185], v[62:65]
	v_mfma_f32_16x16x32_bf16 v[58:61], v[106:109], v[182:185], v[58:61]
	v_mfma_f32_16x16x32_bf16 v[46:49], v[98:101], v[190:193], v[46:49]
	v_mfma_f32_16x16x32_bf16 v[42:45], v[106:109], v[190:193], v[42:45]
	v_mfma_f32_16x16x32_bf16 v[30:33], v[98:101], v[198:201], v[30:33]
	v_mfma_f32_16x16x32_bf16 v[26:29], v[106:109], v[198:201], v[26:29]
	v_mfma_f32_16x16x32_bf16 v[14:17], v[98:101], v[206:209], v[14:17]
	v_mfma_f32_16x16x32_bf16 v[10:13], v[106:109], v[206:209], v[10:13]
	v_mfma_f32_16x16x32_bf16 v[62:65], v[102:105], v[186:189], v[62:65]
	v_mfma_f32_16x16x32_bf16 v[58:61], v[110:113], v[186:189], v[58:61]
	v_mfma_f32_16x16x32_bf16 v[46:49], v[102:105], v[194:197], v[46:49]
	v_mfma_f32_16x16x32_bf16 v[42:45], v[110:113], v[194:197], v[42:45]
	v_mfma_f32_16x16x32_bf16 v[30:33], v[102:105], v[202:205], v[30:33]
	v_mfma_f32_16x16x32_bf16 v[26:29], v[110:113], v[202:205], v[26:29]
	v_mfma_f32_16x16x32_bf16 v[14:17], v[102:105], v[218:221], v[14:17]
	v_mfma_f32_16x16x32_bf16 v[10:13], v[110:113], v[218:221], v[10:13]
	v_mfma_f32_16x16x32_bf16 v[54:57], v[146:149], v[182:185], v[54:57]
	v_mfma_f32_16x16x32_bf16 v[50:53], v[154:157], v[182:185], v[50:53]
	v_mfma_f32_16x16x32_bf16 v[38:41], v[146:149], v[190:193], v[38:41]
	v_mfma_f32_16x16x32_bf16 v[34:37], v[154:157], v[190:193], v[34:37]
	v_mfma_f32_16x16x32_bf16 v[22:25], v[146:149], v[198:201], v[22:25]
	v_mfma_f32_16x16x32_bf16 v[18:21], v[154:157], v[198:201], v[18:21]
	v_mfma_f32_16x16x32_bf16 v[6:9], v[146:149], v[206:209], v[6:9]
	v_mfma_f32_16x16x32_bf16 v[2:5], v[154:157], v[206:209], v[2:5]
	v_mfma_f32_16x16x32_bf16 v[54:57], v[150:153], v[186:189], v[54:57]
	v_mfma_f32_16x16x32_bf16 v[50:53], v[158:161], v[186:189], v[50:53]
	v_mfma_f32_16x16x32_bf16 v[38:41], v[150:153], v[194:197], v[38:41]
	v_mfma_f32_16x16x32_bf16 v[34:37], v[158:161], v[194:197], v[34:37]
	v_mfma_f32_16x16x32_bf16 v[22:25], v[150:153], v[202:205], v[22:25]
	v_mfma_f32_16x16x32_bf16 v[18:21], v[158:161], v[202:205], v[18:21]
	v_mfma_f32_16x16x32_bf16 v[6:9], v[150:153], v[218:221], v[6:9]
	v_mfma_f32_16x16x32_bf16 v[2:5], v[158:161], v[218:221], v[2:5]
	s_barrier
	s_add_i32 s71, s71, 2
	s_add_u32 s30, s30, 0x100
	s_addc_u32 s31, s31, 0
	s_add_u32 s55, s55, 0x100
	s_addc_u32 s70, s70, 0
	s_cmp_gt_u32 s71, 13
.LBB0_450:
	ds_read_b128 v[98:101], v213
	ds_read_b128 v[102:105], v213 offset:1024
	ds_read_b128 v[106:109], v213 offset:2048
	ds_read_b128 v[110:113], v213 offset:3072
	ds_read_b128 v[146:149], v214
	ds_read_b128 v[150:153], v214 offset:1024
	ds_read_b128 v[154:157], v214 offset:2048
	ds_read_b128 v[158:161], v214 offset:3072
	s_add_u32 s34, s30, 0xfffc0080
	s_addc_u32 s35, s31, -1
	s_cmp_eq_u32 s71, 12
	s_cselect_b32 s37, s21, s35
	s_cselect_b32 s36, s27, s34
	s_cselect_b32 s35, s19, s70
	s_cselect_b32 s34, s29, s55
	s_add_i32 m0, s38, 0xc000
	ds_read_b128 v[182:185], v215
	ds_read_b128 v[186:189], v215 offset:1024
	ds_read_b128 v[190:193], v215 offset:2048
	ds_read_b128 v[194:197], v215 offset:3072
	ds_read_b128 v[198:201], v215 offset:4096
	ds_read_b128 v[202:205], v215 offset:5120
	ds_read_b128 v[206:209], v215 offset:6144
	ds_read_b128 v[218:221], v215 offset:7168
	global_load_lds_dwordx4 v174, s[30:31]
	s_add_i32 m0, s38, 0xe000
	s_nop 0
	global_load_lds_dwordx4 v176, s[30:31]
	s_waitcnt vmcnt(8)
	s_waitcnt lgkmcnt(0)
	s_barrier
	v_mfma_f32_16x16x32_bf16 v[142:145], v[98:101], v[182:185], v[142:145]
	v_mfma_f32_16x16x32_bf16 v[138:141], v[106:109], v[182:185], v[138:141]
	v_mfma_f32_16x16x32_bf16 v[126:129], v[98:101], v[190:193], v[126:129]
	v_mfma_f32_16x16x32_bf16 v[122:125], v[106:109], v[190:193], v[122:125]
	v_mfma_f32_16x16x32_bf16 v[94:97], v[98:101], v[198:201], v[94:97]
	v_mfma_f32_16x16x32_bf16 v[90:93], v[106:109], v[198:201], v[90:93]
	v_mfma_f32_16x16x32_bf16 v[78:81], v[98:101], v[206:209], v[78:81]
	v_mfma_f32_16x16x32_bf16 v[74:77], v[106:109], v[206:209], v[74:77]
	v_mfma_f32_16x16x32_bf16 v[142:145], v[102:105], v[186:189], v[142:145]
	v_mfma_f32_16x16x32_bf16 v[138:141], v[110:113], v[186:189], v[138:141]
	v_mfma_f32_16x16x32_bf16 v[126:129], v[102:105], v[194:197], v[126:129]
	v_mfma_f32_16x16x32_bf16 v[122:125], v[110:113], v[194:197], v[122:125]
	v_mfma_f32_16x16x32_bf16 v[94:97], v[102:105], v[202:205], v[94:97]
	v_mfma_f32_16x16x32_bf16 v[90:93], v[110:113], v[202:205], v[90:93]
	v_mfma_f32_16x16x32_bf16 v[78:81], v[102:105], v[218:221], v[78:81]
	v_mfma_f32_16x16x32_bf16 v[74:77], v[110:113], v[218:221], v[74:77]
	v_mfma_f32_16x16x32_bf16 v[134:137], v[146:149], v[182:185], v[134:137]
	v_mfma_f32_16x16x32_bf16 v[130:133], v[154:157], v[182:185], v[130:133]
	v_mfma_f32_16x16x32_bf16 v[118:121], v[146:149], v[190:193], v[118:121]
	v_mfma_f32_16x16x32_bf16 v[114:117], v[154:157], v[190:193], v[114:117]
	v_mfma_f32_16x16x32_bf16 v[86:89], v[146:149], v[198:201], v[86:89]
	v_mfma_f32_16x16x32_bf16 v[82:85], v[154:157], v[198:201], v[82:85]
	v_mfma_f32_16x16x32_bf16 v[70:73], v[146:149], v[206:209], v[70:73]
	v_mfma_f32_16x16x32_bf16 v[66:69], v[154:157], v[206:209], v[66:69]
	v_mfma_f32_16x16x32_bf16 v[134:137], v[150:153], v[186:189], v[134:137]
	v_mfma_f32_16x16x32_bf16 v[130:133], v[158:161], v[186:189], v[130:133]
	v_mfma_f32_16x16x32_bf16 v[118:121], v[150:153], v[194:197], v[118:121]
	v_mfma_f32_16x16x32_bf16 v[114:117], v[158:161], v[194:197], v[114:117]
	v_mfma_f32_16x16x32_bf16 v[86:89], v[150:153], v[202:205], v[86:89]
	v_mfma_f32_16x16x32_bf16 v[82:85], v[158:161], v[202:205], v[82:85]
	v_mfma_f32_16x16x32_bf16 v[70:73], v[150:153], v[218:221], v[70:73]
	v_mfma_f32_16x16x32_bf16 v[66:69], v[158:161], v[218:221], v[66:69]
	s_barrier
	s_add_u32 s98, s34, 0x80
	s_addc_u32 s99, s35, 0
	s_add_u32 s100, s36, 0x80
	s_addc_u32 s101, s37, 0
	s_add_i32 s74, s51, s7
	s_mov_b32 m0, s74
	ds_read_b128 v[182:185], v215 offset:16384
	ds_read_b128 v[186:189], v215 offset:17408
	ds_read_b128 v[190:193], v215 offset:18432
	ds_read_b128 v[194:197], v215 offset:19456
	ds_read_b128 v[198:201], v215 offset:20480
	ds_read_b128 v[202:205], v215 offset:21504
	ds_read_b128 v[206:209], v215 offset:22528
	ds_read_b128 v[218:221], v215 offset:23552
	s_cmp_eq_u32 s71, 12
	s_cselect_b64 exec, 0, -1
	s_cmp_lg_u32 s33, 0x100
	s_cselect_b64 exec, -1, exec
	global_load_lds_dwordx4 v164, s[34:35]
	s_add_i32 m0, s74, 0x2000
	s_add_u32 s74, s34, 0x40000
	s_addc_u32 s75, s35, 0
	s_add_i32 s76, s54, s7
	global_load_lds_dwordx4 v168, s[34:35]
	s_mov_b32 m0, s76
	s_nop 0
	global_load_lds_dwordx4 v164, s[74:75]
	s_add_i32 m0, s76, 0x2000
	s_nop 0
	global_load_lds_dwordx4 v168, s[74:75]
	s_mov_b32 m0, s38
	s_nop 0
	global_load_lds_dwordx4 v162, s[36:37]
	s_mov_b32 m0, s39
	s_nop 0
	global_load_lds_dwordx4 v166, s[36:37]
	s_mov_b64 exec, -1
	s_waitcnt vmcnt(8)
	s_waitcnt lgkmcnt(0)
	s_barrier
	v_mfma_f32_16x16x32_bf16 v[62:65], v[98:101], v[182:185], v[62:65]
	v_mfma_f32_16x16x32_bf16 v[58:61], v[106:109], v[182:185], v[58:61]
	v_mfma_f32_16x16x32_bf16 v[46:49], v[98:101], v[190:193], v[46:49]
	v_mfma_f32_16x16x32_bf16 v[42:45], v[106:109], v[190:193], v[42:45]
	v_mfma_f32_16x16x32_bf16 v[30:33], v[98:101], v[198:201], v[30:33]
	v_mfma_f32_16x16x32_bf16 v[26:29], v[106:109], v[198:201], v[26:29]
	v_mfma_f32_16x16x32_bf16 v[14:17], v[98:101], v[206:209], v[14:17]
	v_mfma_f32_16x16x32_bf16 v[10:13], v[106:109], v[206:209], v[10:13]
	v_mfma_f32_16x16x32_bf16 v[62:65], v[102:105], v[186:189], v[62:65]
	v_mfma_f32_16x16x32_bf16 v[58:61], v[110:113], v[186:189], v[58:61]
	v_mfma_f32_16x16x32_bf16 v[46:49], v[102:105], v[194:197], v[46:49]
	v_mfma_f32_16x16x32_bf16 v[42:45], v[110:113], v[194:197], v[42:45]
	v_mfma_f32_16x16x32_bf16 v[30:33], v[102:105], v[202:205], v[30:33]
	v_mfma_f32_16x16x32_bf16 v[26:29], v[110:113], v[202:205], v[26:29]
	v_mfma_f32_16x16x32_bf16 v[14:17], v[102:105], v[218:221], v[14:17]
	v_mfma_f32_16x16x32_bf16 v[10:13], v[110:113], v[218:221], v[10:13]
	v_mfma_f32_16x16x32_bf16 v[54:57], v[146:149], v[182:185], v[54:57]
	v_mfma_f32_16x16x32_bf16 v[50:53], v[154:157], v[182:185], v[50:53]
	v_mfma_f32_16x16x32_bf16 v[38:41], v[146:149], v[190:193], v[38:41]
	v_mfma_f32_16x16x32_bf16 v[34:37], v[154:157], v[190:193], v[34:37]
	v_mfma_f32_16x16x32_bf16 v[22:25], v[146:149], v[198:201], v[22:25]
	v_mfma_f32_16x16x32_bf16 v[18:21], v[154:157], v[198:201], v[18:21]
	v_mfma_f32_16x16x32_bf16 v[6:9], v[146:149], v[206:209], v[6:9]
	v_mfma_f32_16x16x32_bf16 v[2:5], v[154:157], v[206:209], v[2:5]
	v_mfma_f32_16x16x32_bf16 v[54:57], v[150:153], v[186:189], v[54:57]
	v_mfma_f32_16x16x32_bf16 v[50:53], v[158:161], v[186:189], v[50:53]
	v_mfma_f32_16x16x32_bf16 v[38:41], v[150:153], v[194:197], v[38:41]
	v_mfma_f32_16x16x32_bf16 v[34:37], v[158:161], v[194:197], v[34:37]
	v_mfma_f32_16x16x32_bf16 v[22:25], v[150:153], v[202:205], v[22:25]
	v_mfma_f32_16x16x32_bf16 v[18:21], v[158:161], v[202:205], v[18:21]
	v_mfma_f32_16x16x32_bf16 v[6:9], v[150:153], v[218:221], v[6:9]
	v_mfma_f32_16x16x32_bf16 v[2:5], v[158:161], v[218:221], v[2:5]
	s_barrier
	s_add_i32 s74, 0, 0x18000
	v_add_u32_e32 v1, s74, v173
	s_add_i32 s75, 0, 0x1c000
	ds_read_b128 v[98:101], v1
	ds_read_b128 v[102:105], v1 offset:1024
	ds_read_b128 v[106:109], v1 offset:2048
	ds_read_b128 v[110:113], v1 offset:3072
	v_add_u32_e32 v1, s75, v173
	ds_read_b128 v[146:149], v1
	ds_read_b128 v[150:153], v1 offset:1024
	ds_read_b128 v[154:157], v1 offset:2048
	ds_read_b128 v[158:161], v1 offset:3072
	s_add_u32 s36, s36, 0x40000
	s_addc_u32 s37, s37, 0
	s_mov_b32 m0, s40
	ds_read_b128 v[182:185], v215 offset:32768
	ds_read_b128 v[186:189], v215 offset:33792
	ds_read_b128 v[190:193], v215 offset:34816
	ds_read_b128 v[194:197], v215 offset:35840
	ds_read_b128 v[198:201], v215 offset:36864
	ds_read_b128 v[202:205], v215 offset:37888
	ds_read_b128 v[206:209], v215 offset:38912
	ds_read_b128 v[218:221], v215 offset:39936
	s_cmp_eq_u32 s71, 12
	s_cselect_b64 exec, 0, -1
	s_cmp_lg_u32 s33, 0x100
	s_cselect_b64 exec, -1, exec
	global_load_lds_dwordx4 v162, s[36:37]
	s_mov_b32 m0, s41
	s_nop 0
	global_load_lds_dwordx4 v166, s[36:37]
	s_mov_b64 exec, -1
	s_waitcnt vmcnt(8)
	s_waitcnt lgkmcnt(0)
	s_barrier
	v_mfma_f32_16x16x32_bf16 v[142:145], v[98:101], v[182:185], v[142:145]
	v_mfma_f32_16x16x32_bf16 v[138:141], v[106:109], v[182:185], v[138:141]
	v_mfma_f32_16x16x32_bf16 v[126:129], v[98:101], v[190:193], v[126:129]
	v_mfma_f32_16x16x32_bf16 v[122:125], v[106:109], v[190:193], v[122:125]
	v_mfma_f32_16x16x32_bf16 v[94:97], v[98:101], v[198:201], v[94:97]
	v_mfma_f32_16x16x32_bf16 v[90:93], v[106:109], v[198:201], v[90:93]
	v_mfma_f32_16x16x32_bf16 v[78:81], v[98:101], v[206:209], v[78:81]
	v_mfma_f32_16x16x32_bf16 v[74:77], v[106:109], v[206:209], v[74:77]
	v_mfma_f32_16x16x32_bf16 v[142:145], v[102:105], v[186:189], v[142:145]
	v_mfma_f32_16x16x32_bf16 v[138:141], v[110:113], v[186:189], v[138:141]
	v_mfma_f32_16x16x32_bf16 v[126:129], v[102:105], v[194:197], v[126:129]
	v_mfma_f32_16x16x32_bf16 v[122:125], v[110:113], v[194:197], v[122:125]
	v_mfma_f32_16x16x32_bf16 v[94:97], v[102:105], v[202:205], v[94:97]
	v_mfma_f32_16x16x32_bf16 v[90:93], v[110:113], v[202:205], v[90:93]
	v_mfma_f32_16x16x32_bf16 v[78:81], v[102:105], v[218:221], v[78:81]
	v_mfma_f32_16x16x32_bf16 v[74:77], v[110:113], v[218:221], v[74:77]
	v_mfma_f32_16x16x32_bf16 v[134:137], v[146:149], v[182:185], v[134:137]
	v_mfma_f32_16x16x32_bf16 v[130:133], v[154:157], v[182:185], v[130:133]
	v_mfma_f32_16x16x32_bf16 v[118:121], v[146:149], v[190:193], v[118:121]
	v_mfma_f32_16x16x32_bf16 v[114:117], v[154:157], v[190:193], v[114:117]
	v_mfma_f32_16x16x32_bf16 v[86:89], v[146:149], v[198:201], v[86:89]
	v_mfma_f32_16x16x32_bf16 v[82:85], v[154:157], v[198:201], v[82:85]
	v_mfma_f32_16x16x32_bf16 v[70:73], v[146:149], v[206:209], v[70:73]
	v_mfma_f32_16x16x32_bf16 v[66:69], v[154:157], v[206:209], v[66:69]
	v_mfma_f32_16x16x32_bf16 v[134:137], v[150:153], v[186:189], v[134:137]
	v_mfma_f32_16x16x32_bf16 v[130:133], v[158:161], v[186:189], v[130:133]
	v_mfma_f32_16x16x32_bf16 v[118:121], v[150:153], v[194:197], v[118:121]
	v_mfma_f32_16x16x32_bf16 v[114:117], v[158:161], v[194:197], v[114:117]
	v_mfma_f32_16x16x32_bf16 v[86:89], v[150:153], v[202:205], v[86:89]
	v_mfma_f32_16x16x32_bf16 v[82:85], v[158:161], v[202:205], v[82:85]
	v_mfma_f32_16x16x32_bf16 v[70:73], v[150:153], v[218:221], v[70:73]
	v_mfma_f32_16x16x32_bf16 v[66:69], v[158:161], v[218:221], v[66:69]
	s_barrier
	s_add_i32 s36, s74, s7
	s_mov_b32 m0, s36
	ds_read_b128 v[182:185], v215 offset:49152
	ds_read_b128 v[186:189], v215 offset:50176
	ds_read_b128 v[190:193], v215 offset:51200
	ds_read_b128 v[194:197], v215 offset:52224
	ds_read_b128 v[198:201], v215 offset:53248
	ds_read_b128 v[202:205], v215 offset:54272
	ds_read_b128 v[206:209], v215 offset:55296
	ds_read_b128 v[218:221], v215 offset:56320
	s_cmp_eq_u32 s71, 12
	s_cselect_b64 exec, 0, -1
	s_cmp_lg_u32 s33, 0x100
	s_cselect_b64 exec, -1, exec
	global_load_lds_dwordx4 v164, s[98:99]
	s_add_i32 m0, s36, 0x2000
	s_add_u32 s34, s34, 0x40080
	s_addc_u32 s35, s35, 0
	s_add_i32 s36, s75, s7
	global_load_lds_dwordx4 v168, s[98:99]
	s_mov_b32 m0, s36
	s_nop 0
	global_load_lds_dwordx4 v164, s[34:35]
	s_add_i32 m0, s36, 0x2000
	s_nop 0
	global_load_lds_dwordx4 v168, s[34:35]
	s_mov_b32 m0, s47
	s_nop 0
	global_load_lds_dwordx4 v162, s[100:101]
	s_mov_b32 m0, s48
	s_nop 0
	global_load_lds_dwordx4 v166, s[100:101]
	s_mov_b64 exec, -1
	s_waitcnt vmcnt(8)
	s_waitcnt lgkmcnt(0)
	s_barrier
	v_mfma_f32_16x16x32_bf16 v[62:65], v[98:101], v[182:185], v[62:65]
	v_mfma_f32_16x16x32_bf16 v[58:61], v[106:109], v[182:185], v[58:61]
	v_mfma_f32_16x16x32_bf16 v[46:49], v[98:101], v[190:193], v[46:49]
	v_mfma_f32_16x16x32_bf16 v[42:45], v[106:109], v[190:193], v[42:45]
	v_mfma_f32_16x16x32_bf16 v[30:33], v[98:101], v[198:201], v[30:33]
	v_mfma_f32_16x16x32_bf16 v[26:29], v[106:109], v[198:201], v[26:29]
	v_mfma_f32_16x16x32_bf16 v[14:17], v[98:101], v[206:209], v[14:17]
	v_mfma_f32_16x16x32_bf16 v[10:13], v[106:109], v[206:209], v[10:13]
	v_mfma_f32_16x16x32_bf16 v[62:65], v[102:105], v[186:189], v[62:65]
	v_mfma_f32_16x16x32_bf16 v[58:61], v[110:113], v[186:189], v[58:61]
	v_mfma_f32_16x16x32_bf16 v[46:49], v[102:105], v[194:197], v[46:49]
	v_mfma_f32_16x16x32_bf16 v[42:45], v[110:113], v[194:197], v[42:45]
	v_mfma_f32_16x16x32_bf16 v[30:33], v[102:105], v[202:205], v[30:33]
	v_mfma_f32_16x16x32_bf16 v[26:29], v[110:113], v[202:205], v[26:29]
	v_mfma_f32_16x16x32_bf16 v[14:17], v[102:105], v[218:221], v[14:17]
	v_mfma_f32_16x16x32_bf16 v[10:13], v[110:113], v[218:221], v[10:13]
	v_mfma_f32_16x16x32_bf16 v[54:57], v[146:149], v[182:185], v[54:57]
	v_mfma_f32_16x16x32_bf16 v[50:53], v[154:157], v[182:185], v[50:53]
	v_mfma_f32_16x16x32_bf16 v[38:41], v[146:149], v[190:193], v[38:41]
	v_mfma_f32_16x16x32_bf16 v[34:37], v[154:157], v[190:193], v[34:37]
	v_mfma_f32_16x16x32_bf16 v[22:25], v[146:149], v[198:201], v[22:25]
	v_mfma_f32_16x16x32_bf16 v[18:21], v[154:157], v[198:201], v[18:21]
	v_mfma_f32_16x16x32_bf16 v[6:9], v[146:149], v[206:209], v[6:9]
	v_mfma_f32_16x16x32_bf16 v[2:5], v[154:157], v[206:209], v[2:5]
	v_mfma_f32_16x16x32_bf16 v[54:57], v[150:153], v[186:189], v[54:57]
	v_mfma_f32_16x16x32_bf16 v[50:53], v[158:161], v[186:189], v[50:53]
	v_mfma_f32_16x16x32_bf16 v[38:41], v[150:153], v[194:197], v[38:41]
	v_mfma_f32_16x16x32_bf16 v[34:37], v[158:161], v[194:197], v[34:37]
	v_mfma_f32_16x16x32_bf16 v[22:25], v[150:153], v[202:205], v[22:25]
	v_mfma_f32_16x16x32_bf16 v[18:21], v[158:161], v[202:205], v[18:21]
	v_mfma_f32_16x16x32_bf16 v[6:9], v[150:153], v[218:221], v[6:9]
	v_mfma_f32_16x16x32_bf16 v[2:5], v[158:161], v[218:221], v[2:5]
	s_barrier
	s_add_i32 s71, s71, 2
	s_add_u32 s30, s30, 0x100
	s_addc_u32 s31, s31, 0
	s_add_u32 s55, s55, 0x100
	s_addc_u32 s70, s70, 0
	s_cmp_gt_u32 s71, 13
	s_cbranch_scc0 .LBB0_450
	s_and_b64 vcc, exec, s[16:17]
	s_cbranch_vccz .LBB0_453
	s_barrier

.LBB0_556:
	s_ashr_i32 s41, s40, 31
	s_lshl_b64 s[42:43], s[40:41], 19
	s_add_u32 s42, s68, s42
	s_addc_u32 s43, s69, s43
	s_and_b64 s[44:45], s[4:5], exec
	s_cselect_b32 s41, s43, s9
	s_cselect_b32 s47, s42, s8
	s_ashr_i32 s39, s38, 31
	s_lshl_b64 s[44:45], s[38:39], 19
	s_add_u32 s44, s54, s44
	s_addc_u32 s45, s55, s45
	s_and_b64 s[50:51], s[4:5], exec
	s_cselect_b32 s39, s45, s49
	s_cselect_b32 vcc_lo, s44, s48
	s_add_u32 s8, s8, 0x40080
	s_addc_u32 s9, s9, 0
	s_add_u32 vcc_hi, s48, 0x100
	s_addc_u32 s3, s49, 0
	s_mov_b32 s7, -2
	s_waitcnt lgkmcnt(0)
	ds_read_b128 v[30:33], v219
	ds_read_b128 v[54:57], v219 offset:1024
	ds_read_b128 v[118:121], v219 offset:2048
	ds_read_b128 v[122:125], v219 offset:3072
	ds_read_b128 v[146:149], v220
	ds_read_b128 v[150:153], v220 offset:1024
	ds_read_b128 v[154:157], v220 offset:2048
	ds_read_b128 v[158:161], v220 offset:3072
	s_add_u32 s48, s8, 0xfffc0080
	s_addc_u32 s49, s9, -1
	s_cmp_eq_u32 s7, 12
	s_cselect_b32 s51, s41, s49
	s_cselect_b32 s50, s47, s48
	s_cselect_b32 s49, s39, s3
	s_cselect_b32 s48, vcc_lo, vcc_hi
	s_add_i32 m0, s70, 0xc000
	ds_read_b128 v[162:165], v221
	ds_read_b128 v[166:169], v221 offset:1024
	ds_read_b128 v[194:197], v221 offset:2048
	ds_read_b128 v[198:201], v221 offset:3072
	ds_read_b128 v[202:205], v221 offset:4096
	ds_read_b128 v[206:209], v221 offset:5120
	ds_read_b128 v[224:227], v221 offset:6144
	ds_read_b128 v[228:231], v221 offset:7168
	global_load_lds_dwordx4 v186, s[8:9]
	s_add_i32 m0, s70, 0xe000
	s_nop 0
	global_load_lds_dwordx4 v188, s[8:9]
	s_waitcnt vmcnt(8)
	s_waitcnt lgkmcnt(0)
	s_barrier
	v_mfma_f32_16x16x32_bf16 v[62:65], v[30:33], v[162:165], 0
	v_mfma_f32_16x16x32_bf16 v[42:45], v[118:121], v[162:165], 0
	v_mfma_f32_16x16x32_bf16 v[50:53], v[30:33], v[194:197], 0
	v_mfma_f32_16x16x32_bf16 v[38:41], v[118:121], v[194:197], 0
	v_mfma_f32_16x16x32_bf16 v[46:49], v[30:33], v[202:205], 0
	v_mfma_f32_16x16x32_bf16 v[34:37], v[118:121], v[202:205], 0
	v_mfma_f32_16x16x32_bf16 v[142:145], v[30:33], v[224:227], 0
	v_mfma_f32_16x16x32_bf16 v[82:85], v[118:121], v[224:227], 0
	v_mfma_f32_16x16x32_bf16 v[62:65], v[54:57], v[166:169], v[62:65]
	v_mfma_f32_16x16x32_bf16 v[42:45], v[122:125], v[166:169], v[42:45]
	v_mfma_f32_16x16x32_bf16 v[50:53], v[54:57], v[198:201], v[50:53]
	v_mfma_f32_16x16x32_bf16 v[38:41], v[122:125], v[198:201], v[38:41]
	v_mfma_f32_16x16x32_bf16 v[46:49], v[54:57], v[206:209], v[46:49]
	v_mfma_f32_16x16x32_bf16 v[34:37], v[122:125], v[206:209], v[34:37]
	v_mfma_f32_16x16x32_bf16 v[142:145], v[54:57], v[228:231], v[142:145]
	v_mfma_f32_16x16x32_bf16 v[82:85], v[122:125], v[228:231], v[82:85]
	v_mfma_f32_16x16x32_bf16 v[134:137], v[146:149], v[162:165], 0
	v_mfma_f32_16x16x32_bf16 v[74:77], v[154:157], v[162:165], 0
	v_mfma_f32_16x16x32_bf16 v[130:133], v[146:149], v[194:197], 0
	v_mfma_f32_16x16x32_bf16 v[70:73], v[154:157], v[194:197], 0
	v_mfma_f32_16x16x32_bf16 v[78:81], v[146:149], v[202:205], 0
	v_mfma_f32_16x16x32_bf16 v[66:69], v[154:157], v[202:205], 0
	v_mfma_f32_16x16x32_bf16 v[138:141], v[146:149], v[224:227], 0
	v_mfma_f32_16x16x32_bf16 v[98:101], v[154:157], v[224:227], 0
	v_mfma_f32_16x16x32_bf16 v[134:137], v[150:153], v[166:169], v[134:137]
	v_mfma_f32_16x16x32_bf16 v[74:77], v[158:161], v[166:169], v[74:77]
	v_mfma_f32_16x16x32_bf16 v[130:133], v[150:153], v[198:201], v[130:133]
	v_mfma_f32_16x16x32_bf16 v[70:73], v[158:161], v[198:201], v[70:73]
	v_mfma_f32_16x16x32_bf16 v[78:81], v[150:153], v[206:209], v[78:81]
	v_mfma_f32_16x16x32_bf16 v[66:69], v[158:161], v[206:209], v[66:69]
	v_mfma_f32_16x16x32_bf16 v[138:141], v[150:153], v[228:231], v[138:141]
	v_mfma_f32_16x16x32_bf16 v[98:101], v[158:161], v[228:231], v[98:101]
	s_barrier
	s_add_u32 s98, s48, 0x80
	s_addc_u32 s99, s49, 0
	s_add_u32 s100, s50, 0x80
	s_addc_u32 s101, s51, 0
	s_add_i32 s84, s93, s64
	s_mov_b32 m0, s84
	ds_read_b128 v[162:165], v221 offset:16384
	ds_read_b128 v[166:169], v221 offset:17408
	ds_read_b128 v[194:197], v221 offset:18432
	ds_read_b128 v[198:201], v221 offset:19456
	ds_read_b128 v[202:205], v221 offset:20480
	ds_read_b128 v[206:209], v221 offset:21504
	ds_read_b128 v[224:227], v221 offset:22528
	ds_read_b128 v[228:231], v221 offset:23552
	global_load_lds_dwordx4 v176, s[48:49]
	s_add_i32 m0, s84, 0x2000
	s_add_u32 s84, s48, 0x40000
	s_addc_u32 s85, s49, 0
	s_add_i32 s86, s90, s64
	global_load_lds_dwordx4 v180, s[48:49]
	s_mov_b32 m0, s86
	s_nop 0
	global_load_lds_dwordx4 v176, s[84:85]
	s_add_i32 m0, s86, 0x2000
	s_nop 0
	global_load_lds_dwordx4 v180, s[84:85]
	s_mov_b32 m0, s70
	s_nop 0
	global_load_lds_dwordx4 v174, s[50:51]
	s_mov_b32 m0, s71
	s_nop 0
	global_load_lds_dwordx4 v178, s[50:51]
	s_waitcnt vmcnt(8)
	s_waitcnt lgkmcnt(0)
	s_barrier
	v_mfma_f32_16x16x32_bf16 v[94:97], v[30:33], v[162:165], 0
	v_mfma_f32_16x16x32_bf16 v[10:13], v[118:121], v[162:165], 0
	v_mfma_f32_16x16x32_bf16 v[90:93], v[30:33], v[194:197], 0
	v_mfma_f32_16x16x32_bf16 v[6:9], v[118:121], v[194:197], 0
	v_mfma_f32_16x16x32_bf16 v[86:89], v[30:33], v[202:205], 0
	v_mfma_f32_16x16x32_bf16 v[2:5], v[118:121], v[202:205], 0
	v_mfma_f32_16x16x32_bf16 v[26:29], v[118:121], v[224:227], 0
	v_mfma_f32_16x16x32_bf16 v[94:97], v[54:57], v[166:169], v[94:97]
	v_mfma_f32_16x16x32_bf16 v[10:13], v[122:125], v[166:169], v[10:13]
	v_mfma_f32_16x16x32_bf16 v[90:93], v[54:57], v[198:201], v[90:93]
	v_mfma_f32_16x16x32_bf16 v[6:9], v[122:125], v[198:201], v[6:9]
	v_mfma_f32_16x16x32_bf16 v[86:89], v[54:57], v[206:209], v[86:89]
	v_mfma_f32_16x16x32_bf16 v[2:5], v[122:125], v[206:209], v[2:5]
	v_mfma_f32_16x16x32_bf16 v[30:33], v[30:33], v[224:227], 0
	v_mfma_f32_16x16x32_bf16 v[26:29], v[122:125], v[228:231], v[26:29]
	v_mfma_f32_16x16x32_bf16 v[30:33], v[54:57], v[228:231], v[30:33]
	v_mfma_f32_16x16x32_bf16 v[22:25], v[154:157], v[162:165], 0
	v_mfma_f32_16x16x32_bf16 v[106:109], v[146:149], v[194:197], 0
	v_mfma_f32_16x16x32_bf16 v[18:21], v[154:157], v[194:197], 0
	v_mfma_f32_16x16x32_bf16 v[102:105], v[146:149], v[202:205], 0
	v_mfma_f32_16x16x32_bf16 v[14:17], v[154:157], v[202:205], 0
	v_mfma_f32_16x16x32_bf16 v[58:61], v[154:157], v[224:227], 0
	v_mfma_f32_16x16x32_bf16 v[54:57], v[146:149], v[162:165], 0
	v_mfma_f32_16x16x32_bf16 v[22:25], v[158:161], v[166:169], v[22:25]
	v_mfma_f32_16x16x32_bf16 v[106:109], v[150:153], v[198:201], v[106:109]
	v_mfma_f32_16x16x32_bf16 v[18:21], v[158:161], v[198:201], v[18:21]
	v_mfma_f32_16x16x32_bf16 v[102:105], v[150:153], v[206:209], v[102:105]
	v_mfma_f32_16x16x32_bf16 v[14:17], v[158:161], v[206:209], v[14:17]
	v_mfma_f32_16x16x32_bf16 v[110:113], v[146:149], v[224:227], 0
	v_mfma_f32_16x16x32_bf16 v[58:61], v[158:161], v[228:231], v[58:61]
	v_mfma_f32_16x16x32_bf16 v[54:57], v[150:153], v[166:169], v[54:57]
	v_mfma_f32_16x16x32_bf16 v[118:121], v[150:153], v[228:231], v[110:113]
	s_barrier
	s_add_i32 s84, 0, 0x18000
	v_add_u32_e32 v1, s84, v210
	s_add_i32 s85, 0, 0x1c000
	ds_read_b128 v[110:113], v1
	ds_read_b128 v[114:117], v1 offset:1024
	ds_read_b128 v[122:125], v1 offset:2048
	ds_read_b128 v[126:129], v1 offset:3072
	v_add_u32_e32 v1, s85, v210
	ds_read_b128 v[146:149], v1
	ds_read_b128 v[150:153], v1 offset:1024
	ds_read_b128 v[154:157], v1 offset:2048
	ds_read_b128 v[158:161], v1 offset:3072
	s_add_u32 s50, s50, 0x40000
	s_addc_u32 s51, s51, 0
	s_mov_b32 m0, s74
	ds_read_b128 v[162:165], v221 offset:32768
	ds_read_b128 v[166:169], v221 offset:33792
	ds_read_b128 v[194:197], v221 offset:34816
	ds_read_b128 v[198:201], v221 offset:35840
	ds_read_b128 v[202:205], v221 offset:36864
	ds_read_b128 v[206:209], v221 offset:37888
	ds_read_b128 v[224:227], v221 offset:38912
	ds_read_b128 v[228:231], v221 offset:39936
	global_load_lds_dwordx4 v174, s[50:51]
	s_mov_b32 m0, s75
	s_nop 0
	global_load_lds_dwordx4 v178, s[50:51]
	s_waitcnt vmcnt(8)
	s_waitcnt lgkmcnt(0)
	s_barrier
	v_mfma_f32_16x16x32_bf16 v[62:65], v[110:113], v[162:165], v[62:65]
	v_mfma_f32_16x16x32_bf16 v[42:45], v[122:125], v[162:165], v[42:45]
	v_mfma_f32_16x16x32_bf16 v[50:53], v[110:113], v[194:197], v[50:53]
	v_mfma_f32_16x16x32_bf16 v[38:41], v[122:125], v[194:197], v[38:41]
	v_mfma_f32_16x16x32_bf16 v[46:49], v[110:113], v[202:205], v[46:49]
	v_mfma_f32_16x16x32_bf16 v[34:37], v[122:125], v[202:205], v[34:37]
	v_mfma_f32_16x16x32_bf16 v[142:145], v[110:113], v[224:227], v[142:145]
	v_mfma_f32_16x16x32_bf16 v[82:85], v[122:125], v[224:227], v[82:85]
	v_mfma_f32_16x16x32_bf16 v[62:65], v[114:117], v[166:169], v[62:65]
	v_mfma_f32_16x16x32_bf16 v[42:45], v[126:129], v[166:169], v[42:45]
	v_mfma_f32_16x16x32_bf16 v[50:53], v[114:117], v[198:201], v[50:53]
	v_mfma_f32_16x16x32_bf16 v[38:41], v[126:129], v[198:201], v[38:41]
	v_mfma_f32_16x16x32_bf16 v[46:49], v[114:117], v[206:209], v[46:49]
	v_mfma_f32_16x16x32_bf16 v[34:37], v[126:129], v[206:209], v[34:37]
	v_mfma_f32_16x16x32_bf16 v[142:145], v[114:117], v[228:231], v[142:145]
	v_mfma_f32_16x16x32_bf16 v[82:85], v[126:129], v[228:231], v[82:85]
	v_mfma_f32_16x16x32_bf16 v[134:137], v[146:149], v[162:165], v[134:137]
	v_mfma_f32_16x16x32_bf16 v[74:77], v[154:157], v[162:165], v[74:77]
	v_mfma_f32_16x16x32_bf16 v[130:133], v[146:149], v[194:197], v[130:133]
	v_mfma_f32_16x16x32_bf16 v[70:73], v[154:157], v[194:197], v[70:73]
	v_mfma_f32_16x16x32_bf16 v[78:81], v[146:149], v[202:205], v[78:81]
	v_mfma_f32_16x16x32_bf16 v[66:69], v[154:157], v[202:205], v[66:69]
	v_mfma_f32_16x16x32_bf16 v[138:141], v[146:149], v[224:227], v[138:141]
	v_mfma_f32_16x16x32_bf16 v[98:101], v[154:157], v[224:227], v[98:101]
	v_mfma_f32_16x16x32_bf16 v[134:137], v[150:153], v[166:169], v[134:137]
	v_mfma_f32_16x16x32_bf16 v[74:77], v[158:161], v[166:169], v[74:77]
	v_mfma_f32_16x16x32_bf16 v[130:133], v[150:153], v[198:201], v[130:133]
	v_mfma_f32_16x16x32_bf16 v[70:73], v[158:161], v[198:201], v[70:73]
	v_mfma_f32_16x16x32_bf16 v[78:81], v[150:153], v[206:209], v[78:81]
	v_mfma_f32_16x16x32_bf16 v[66:69], v[158:161], v[206:209], v[66:69]
	v_mfma_f32_16x16x32_bf16 v[138:141], v[150:153], v[228:231], v[138:141]
	v_mfma_f32_16x16x32_bf16 v[98:101], v[158:161], v[228:231], v[98:101]
	s_barrier
	s_add_i32 s50, s84, s64
	s_mov_b32 m0, s50
	ds_read_b128 v[162:165], v221 offset:49152
	ds_read_b128 v[166:169], v221 offset:50176
	ds_read_b128 v[194:197], v221 offset:51200
	ds_read_b128 v[198:201], v221 offset:52224
	ds_read_b128 v[202:205], v221 offset:53248
	ds_read_b128 v[206:209], v221 offset:54272
	ds_read_b128 v[224:227], v221 offset:55296
	ds_read_b128 v[228:231], v221 offset:56320
	global_load_lds_dwordx4 v176, s[98:99]
	s_add_i32 m0, s50, 0x2000
	s_add_u32 s48, s48, 0x40080
	s_addc_u32 s49, s49, 0
	s_add_i32 s50, s85, s64
	global_load_lds_dwordx4 v180, s[98:99]
	s_mov_b32 m0, s50
	s_nop 0
	global_load_lds_dwordx4 v176, s[48:49]
	s_add_i32 m0, s50, 0x2000
	s_nop 0
	global_load_lds_dwordx4 v180, s[48:49]
	s_mov_b32 m0, s77
	s_nop 0
	global_load_lds_dwordx4 v174, s[100:101]
	s_mov_b32 m0, s78
	s_nop 0
	global_load_lds_dwordx4 v178, s[100:101]
	s_waitcnt vmcnt(8)
	s_waitcnt lgkmcnt(0)
	s_barrier
	v_mfma_f32_16x16x32_bf16 v[94:97], v[110:113], v[162:165], v[94:97]
	v_mfma_f32_16x16x32_bf16 v[10:13], v[122:125], v[162:165], v[10:13]
	v_mfma_f32_16x16x32_bf16 v[90:93], v[110:113], v[194:197], v[90:93]
	v_mfma_f32_16x16x32_bf16 v[6:9], v[122:125], v[194:197], v[6:9]
	v_mfma_f32_16x16x32_bf16 v[86:89], v[110:113], v[202:205], v[86:89]
	v_mfma_f32_16x16x32_bf16 v[2:5], v[122:125], v[202:205], v[2:5]
	v_mfma_f32_16x16x32_bf16 v[30:33], v[110:113], v[224:227], v[30:33]
	v_mfma_f32_16x16x32_bf16 v[26:29], v[122:125], v[224:227], v[26:29]
	v_mfma_f32_16x16x32_bf16 v[94:97], v[114:117], v[166:169], v[94:97]
	v_mfma_f32_16x16x32_bf16 v[10:13], v[126:129], v[166:169], v[10:13]
	v_mfma_f32_16x16x32_bf16 v[90:93], v[114:117], v[198:201], v[90:93]
	v_mfma_f32_16x16x32_bf16 v[6:9], v[126:129], v[198:201], v[6:9]
	v_mfma_f32_16x16x32_bf16 v[86:89], v[114:117], v[206:209], v[86:89]
	v_mfma_f32_16x16x32_bf16 v[2:5], v[126:129], v[206:209], v[2:5]
	v_mfma_f32_16x16x32_bf16 v[114:117], v[114:117], v[228:231], v[30:33]
	v_mfma_f32_16x16x32_bf16 v[26:29], v[126:129], v[228:231], v[26:29]
	v_mfma_f32_16x16x32_bf16 v[30:33], v[146:149], v[162:165], v[54:57]
	v_mfma_f32_16x16x32_bf16 v[110:113], v[150:153], v[166:169], v[30:33]
	v_mfma_f32_16x16x32_bf16 v[30:33], v[146:149], v[194:197], v[106:109]
	v_mfma_f32_16x16x32_bf16 v[106:109], v[150:153], v[198:201], v[30:33]
	v_mfma_f32_16x16x32_bf16 v[30:33], v[146:149], v[202:205], v[102:105]
	v_mfma_f32_16x16x32_bf16 v[102:105], v[150:153], v[206:209], v[30:33]
	v_mfma_f32_16x16x32_bf16 v[30:33], v[146:149], v[224:227], v[118:121]
	v_mfma_f32_16x16x32_bf16 v[22:25], v[154:157], v[162:165], v[22:25]
	v_mfma_f32_16x16x32_bf16 v[18:21], v[154:157], v[194:197], v[18:21]
	v_mfma_f32_16x16x32_bf16 v[14:17], v[154:157], v[202:205], v[14:17]
	v_mfma_f32_16x16x32_bf16 v[126:129], v[150:153], v[228:231], v[30:33]
	v_mfma_f32_16x16x32_bf16 v[30:33], v[154:157], v[224:227], v[58:61]
	v_mfma_f32_16x16x32_bf16 v[22:25], v[158:161], v[166:169], v[22:25]
	v_mfma_f32_16x16x32_bf16 v[18:21], v[158:161], v[198:201], v[18:21]
	v_mfma_f32_16x16x32_bf16 v[14:17], v[158:161], v[206:209], v[14:17]
	v_mfma_f32_16x16x32_bf16 v[58:61], v[158:161], v[228:231], v[30:33]
	s_barrier
	s_add_i32 s7, s7, 2
	s_add_u32 s8, s8, 0x100
	s_addc_u32 s9, s9, 0
	s_add_u32 vcc_hi, vcc_hi, 0x100
	s_addc_u32 s3, s3, 0
	s_cmp_gt_u32 s7, 13
.LBB0_557:
	ds_read_b128 v[30:33], v219
	ds_read_b128 v[54:57], v219 offset:1024
	ds_read_b128 v[118:121], v219 offset:2048
	ds_read_b128 v[122:125], v219 offset:3072
	ds_read_b128 v[146:149], v220
	ds_read_b128 v[150:153], v220 offset:1024
	ds_read_b128 v[154:157], v220 offset:2048
	ds_read_b128 v[158:161], v220 offset:3072
	s_add_u32 s48, s8, 0xfffc0080
	s_addc_u32 s49, s9, -1
	s_cmp_eq_u32 s7, 12
	s_cselect_b32 s51, s41, s49
	s_cselect_b32 s50, s47, s48
	s_cselect_b32 s49, s39, s3
	s_cselect_b32 s48, vcc_lo, vcc_hi
	s_add_i32 m0, s70, 0xc000
	ds_read_b128 v[162:165], v221
	ds_read_b128 v[166:169], v221 offset:1024
	ds_read_b128 v[194:197], v221 offset:2048
	ds_read_b128 v[198:201], v221 offset:3072
	ds_read_b128 v[202:205], v221 offset:4096
	ds_read_b128 v[206:209], v221 offset:5120
	ds_read_b128 v[224:227], v221 offset:6144
	ds_read_b128 v[228:231], v221 offset:7168
	global_load_lds_dwordx4 v186, s[8:9]
	s_add_i32 m0, s70, 0xe000
	s_nop 0
	global_load_lds_dwordx4 v188, s[8:9]
	s_waitcnt vmcnt(8)
	s_waitcnt lgkmcnt(0)
	s_barrier
	v_mfma_f32_16x16x32_bf16 v[62:65], v[30:33], v[162:165], v[62:65]
	v_mfma_f32_16x16x32_bf16 v[42:45], v[118:121], v[162:165], v[42:45]
	v_mfma_f32_16x16x32_bf16 v[50:53], v[30:33], v[194:197], v[50:53]
	v_mfma_f32_16x16x32_bf16 v[38:41], v[118:121], v[194:197], v[38:41]
	v_mfma_f32_16x16x32_bf16 v[46:49], v[30:33], v[202:205], v[46:49]
	v_mfma_f32_16x16x32_bf16 v[34:37], v[118:121], v[202:205], v[34:37]
	v_mfma_f32_16x16x32_bf16 v[142:145], v[30:33], v[224:227], v[142:145]
	v_mfma_f32_16x16x32_bf16 v[82:85], v[118:121], v[224:227], v[82:85]
	v_mfma_f32_16x16x32_bf16 v[62:65], v[54:57], v[166:169], v[62:65]
	v_mfma_f32_16x16x32_bf16 v[42:45], v[122:125], v[166:169], v[42:45]
	v_mfma_f32_16x16x32_bf16 v[50:53], v[54:57], v[198:201], v[50:53]
	v_mfma_f32_16x16x32_bf16 v[38:41], v[122:125], v[198:201], v[38:41]
	v_mfma_f32_16x16x32_bf16 v[46:49], v[54:57], v[206:209], v[46:49]
	v_mfma_f32_16x16x32_bf16 v[34:37], v[122:125], v[206:209], v[34:37]
	v_mfma_f32_16x16x32_bf16 v[142:145], v[54:57], v[228:231], v[142:145]
	v_mfma_f32_16x16x32_bf16 v[82:85], v[122:125], v[228:231], v[82:85]
	v_mfma_f32_16x16x32_bf16 v[134:137], v[146:149], v[162:165], v[134:137]
	v_mfma_f32_16x16x32_bf16 v[74:77], v[154:157], v[162:165], v[74:77]
	v_mfma_f32_16x16x32_bf16 v[130:133], v[146:149], v[194:197], v[130:133]
	v_mfma_f32_16x16x32_bf16 v[70:73], v[154:157], v[194:197], v[70:73]
	v_mfma_f32_16x16x32_bf16 v[78:81], v[146:149], v[202:205], v[78:81]
	v_mfma_f32_16x16x32_bf16 v[66:69], v[154:157], v[202:205], v[66:69]
	v_mfma_f32_16x16x32_bf16 v[138:141], v[146:149], v[224:227], v[138:141]
	v_mfma_f32_16x16x32_bf16 v[98:101], v[154:157], v[224:227], v[98:101]
	v_mfma_f32_16x16x32_bf16 v[134:137], v[150:153], v[166:169], v[134:137]
	v_mfma_f32_16x16x32_bf16 v[74:77], v[158:161], v[166:169], v[74:77]
	v_mfma_f32_16x16x32_bf16 v[130:133], v[150:153], v[198:201], v[130:133]
	v_mfma_f32_16x16x32_bf16 v[70:73], v[158:161], v[198:201], v[70:73]
	v_mfma_f32_16x16x32_bf16 v[78:81], v[150:153], v[206:209], v[78:81]
	v_mfma_f32_16x16x32_bf16 v[66:69], v[158:161], v[206:209], v[66:69]
	v_mfma_f32_16x16x32_bf16 v[138:141], v[150:153], v[228:231], v[138:141]
	v_mfma_f32_16x16x32_bf16 v[98:101], v[158:161], v[228:231], v[98:101]
	s_barrier
	s_add_u32 s98, s48, 0x80
	s_addc_u32 s99, s49, 0
	s_add_u32 s100, s50, 0x80
	s_addc_u32 s101, s51, 0
	s_add_i32 s84, s93, s64
	s_mov_b32 m0, s84
	ds_read_b128 v[162:165], v221 offset:16384
	ds_read_b128 v[166:169], v221 offset:17408
	ds_read_b128 v[194:197], v221 offset:18432
	ds_read_b128 v[198:201], v221 offset:19456
	ds_read_b128 v[202:205], v221 offset:20480
	ds_read_b128 v[206:209], v221 offset:21504
	ds_read_b128 v[224:227], v221 offset:22528
	ds_read_b128 v[228:231], v221 offset:23552
	global_load_lds_dwordx4 v176, s[48:49]
	s_add_i32 m0, s84, 0x2000
	s_add_u32 s84, s48, 0x40000
	s_addc_u32 s85, s49, 0
	s_add_i32 s86, s90, s64
	global_load_lds_dwordx4 v180, s[48:49]
	s_mov_b32 m0, s86
	s_nop 0
	global_load_lds_dwordx4 v176, s[84:85]
	s_add_i32 m0, s86, 0x2000
	s_nop 0
	global_load_lds_dwordx4 v180, s[84:85]
	s_mov_b32 m0, s70
	s_nop 0
	global_load_lds_dwordx4 v174, s[50:51]
	s_mov_b32 m0, s71
	s_nop 0
	global_load_lds_dwordx4 v178, s[50:51]
	s_waitcnt vmcnt(8)
	s_waitcnt lgkmcnt(0)
	s_barrier
	v_mfma_f32_16x16x32_bf16 v[94:97], v[30:33], v[162:165], v[94:97]
	v_mfma_f32_16x16x32_bf16 v[10:13], v[118:121], v[162:165], v[10:13]
	v_mfma_f32_16x16x32_bf16 v[90:93], v[30:33], v[194:197], v[90:93]
	v_mfma_f32_16x16x32_bf16 v[6:9], v[118:121], v[194:197], v[6:9]
	v_mfma_f32_16x16x32_bf16 v[86:89], v[30:33], v[202:205], v[86:89]
	v_mfma_f32_16x16x32_bf16 v[2:5], v[118:121], v[202:205], v[2:5]
	v_mfma_f32_16x16x32_bf16 v[26:29], v[118:121], v[224:227], v[26:29]
	v_mfma_f32_16x16x32_bf16 v[94:97], v[54:57], v[166:169], v[94:97]
	v_mfma_f32_16x16x32_bf16 v[10:13], v[122:125], v[166:169], v[10:13]
	v_mfma_f32_16x16x32_bf16 v[90:93], v[54:57], v[198:201], v[90:93]
	v_mfma_f32_16x16x32_bf16 v[6:9], v[122:125], v[198:201], v[6:9]
	v_mfma_f32_16x16x32_bf16 v[86:89], v[54:57], v[206:209], v[86:89]
	v_mfma_f32_16x16x32_bf16 v[2:5], v[122:125], v[206:209], v[2:5]
	v_mfma_f32_16x16x32_bf16 v[30:33], v[30:33], v[224:227], v[114:117]
	v_mfma_f32_16x16x32_bf16 v[26:29], v[122:125], v[228:231], v[26:29]
	v_mfma_f32_16x16x32_bf16 v[30:33], v[54:57], v[228:231], v[30:33]
	v_mfma_f32_16x16x32_bf16 v[22:25], v[154:157], v[162:165], v[22:25]
	v_mfma_f32_16x16x32_bf16 v[106:109], v[146:149], v[194:197], v[106:109]
	v_mfma_f32_16x16x32_bf16 v[18:21], v[154:157], v[194:197], v[18:21]
	v_mfma_f32_16x16x32_bf16 v[102:105], v[146:149], v[202:205], v[102:105]
	v_mfma_f32_16x16x32_bf16 v[14:17], v[154:157], v[202:205], v[14:17]
	v_mfma_f32_16x16x32_bf16 v[58:61], v[154:157], v[224:227], v[58:61]
	v_mfma_f32_16x16x32_bf16 v[54:57], v[146:149], v[162:165], v[110:113]
	v_mfma_f32_16x16x32_bf16 v[22:25], v[158:161], v[166:169], v[22:25]
	v_mfma_f32_16x16x32_bf16 v[106:109], v[150:153], v[198:201], v[106:109]
	v_mfma_f32_16x16x32_bf16 v[18:21], v[158:161], v[198:201], v[18:21]
	v_mfma_f32_16x16x32_bf16 v[102:105], v[150:153], v[206:209], v[102:105]
	v_mfma_f32_16x16x32_bf16 v[14:17], v[158:161], v[206:209], v[14:17]
	v_mfma_f32_16x16x32_bf16 v[110:113], v[146:149], v[224:227], v[126:129]
	v_mfma_f32_16x16x32_bf16 v[58:61], v[158:161], v[228:231], v[58:61]
	v_mfma_f32_16x16x32_bf16 v[54:57], v[150:153], v[166:169], v[54:57]
	v_mfma_f32_16x16x32_bf16 v[118:121], v[150:153], v[228:231], v[110:113]
	s_barrier
	s_add_i32 s84, 0, 0x18000
	v_add_u32_e32 v1, s84, v210
	s_add_i32 s85, 0, 0x1c000
	ds_read_b128 v[110:113], v1
	ds_read_b128 v[114:117], v1 offset:1024
	ds_read_b128 v[122:125], v1 offset:2048
	ds_read_b128 v[126:129], v1 offset:3072
	v_add_u32_e32 v1, s85, v210
	ds_read_b128 v[146:149], v1
	ds_read_b128 v[150:153], v1 offset:1024
	ds_read_b128 v[154:157], v1 offset:2048
	ds_read_b128 v[158:161], v1 offset:3072
	s_add_u32 s50, s50, 0x40000
	s_addc_u32 s51, s51, 0
	s_mov_b32 m0, s74
	ds_read_b128 v[162:165], v221 offset:32768
	ds_read_b128 v[166:169], v221 offset:33792
	ds_read_b128 v[194:197], v221 offset:34816
	ds_read_b128 v[198:201], v221 offset:35840
	ds_read_b128 v[202:205], v221 offset:36864
	ds_read_b128 v[206:209], v221 offset:37888
	ds_read_b128 v[224:227], v221 offset:38912
	ds_read_b128 v[228:231], v221 offset:39936
	global_load_lds_dwordx4 v174, s[50:51]
	s_mov_b32 m0, s75
	s_nop 0
	global_load_lds_dwordx4 v178, s[50:51]
	s_waitcnt vmcnt(8)
	s_waitcnt lgkmcnt(0)
	s_barrier
	v_mfma_f32_16x16x32_bf16 v[62:65], v[110:113], v[162:165], v[62:65]
	v_mfma_f32_16x16x32_bf16 v[42:45], v[122:125], v[162:165], v[42:45]
	v_mfma_f32_16x16x32_bf16 v[50:53], v[110:113], v[194:197], v[50:53]
	v_mfma_f32_16x16x32_bf16 v[38:41], v[122:125], v[194:197], v[38:41]
	v_mfma_f32_16x16x32_bf16 v[46:49], v[110:113], v[202:205], v[46:49]
	v_mfma_f32_16x16x32_bf16 v[34:37], v[122:125], v[202:205], v[34:37]
	v_mfma_f32_16x16x32_bf16 v[142:145], v[110:113], v[224:227], v[142:145]
	v_mfma_f32_16x16x32_bf16 v[82:85], v[122:125], v[224:227], v[82:85]
	v_mfma_f32_16x16x32_bf16 v[62:65], v[114:117], v[166:169], v[62:65]
	v_mfma_f32_16x16x32_bf16 v[42:45], v[126:129], v[166:169], v[42:45]
	v_mfma_f32_16x16x32_bf16 v[50:53], v[114:117], v[198:201], v[50:53]
	v_mfma_f32_16x16x32_bf16 v[38:41], v[126:129], v[198:201], v[38:41]
	v_mfma_f32_16x16x32_bf16 v[46:49], v[114:117], v[206:209], v[46:49]
	v_mfma_f32_16x16x32_bf16 v[34:37], v[126:129], v[206:209], v[34:37]
	v_mfma_f32_16x16x32_bf16 v[142:145], v[114:117], v[228:231], v[142:145]
	v_mfma_f32_16x16x32_bf16 v[82:85], v[126:129], v[228:231], v[82:85]
	v_mfma_f32_16x16x32_bf16 v[134:137], v[146:149], v[162:165], v[134:137]
	v_mfma_f32_16x16x32_bf16 v[74:77], v[154:157], v[162:165], v[74:77]
	v_mfma_f32_16x16x32_bf16 v[130:133], v[146:149], v[194:197], v[130:133]
	v_mfma_f32_16x16x32_bf16 v[70:73], v[154:157], v[194:197], v[70:73]
	v_mfma_f32_16x16x32_bf16 v[78:81], v[146:149], v[202:205], v[78:81]
	v_mfma_f32_16x16x32_bf16 v[66:69], v[154:157], v[202:205], v[66:69]
	v_mfma_f32_16x16x32_bf16 v[138:141], v[146:149], v[224:227], v[138:141]
	v_mfma_f32_16x16x32_bf16 v[98:101], v[154:157], v[224:227], v[98:101]
	v_mfma_f32_16x16x32_bf16 v[134:137], v[150:153], v[166:169], v[134:137]
	v_mfma_f32_16x16x32_bf16 v[74:77], v[158:161], v[166:169], v[74:77]
	v_mfma_f32_16x16x32_bf16 v[130:133], v[150:153], v[198:201], v[130:133]
	v_mfma_f32_16x16x32_bf16 v[70:73], v[158:161], v[198:201], v[70:73]
	v_mfma_f32_16x16x32_bf16 v[78:81], v[150:153], v[206:209], v[78:81]
	v_mfma_f32_16x16x32_bf16 v[66:69], v[158:161], v[206:209], v[66:69]
	v_mfma_f32_16x16x32_bf16 v[138:141], v[150:153], v[228:231], v[138:141]
	v_mfma_f32_16x16x32_bf16 v[98:101], v[158:161], v[228:231], v[98:101]
	s_barrier
	s_add_i32 s50, s84, s64
	s_mov_b32 m0, s50
	ds_read_b128 v[162:165], v221 offset:49152
	ds_read_b128 v[166:169], v221 offset:50176
	ds_read_b128 v[194:197], v221 offset:51200
	ds_read_b128 v[198:201], v221 offset:52224
	ds_read_b128 v[202:205], v221 offset:53248
	ds_read_b128 v[206:209], v221 offset:54272
	ds_read_b128 v[224:227], v221 offset:55296
	ds_read_b128 v[228:231], v221 offset:56320
	global_load_lds_dwordx4 v176, s[98:99]
	s_add_i32 m0, s50, 0x2000
	s_add_u32 s48, s48, 0x40080
	s_addc_u32 s49, s49, 0
	s_add_i32 s50, s85, s64
	global_load_lds_dwordx4 v180, s[98:99]
	s_mov_b32 m0, s50
	s_nop 0
	global_load_lds_dwordx4 v176, s[48:49]
	s_add_i32 m0, s50, 0x2000
	s_nop 0
	global_load_lds_dwordx4 v180, s[48:49]
	s_mov_b32 m0, s77
	s_nop 0
	global_load_lds_dwordx4 v174, s[100:101]
	s_mov_b32 m0, s78
	s_nop 0
	global_load_lds_dwordx4 v178, s[100:101]
	s_waitcnt vmcnt(8)
	s_waitcnt lgkmcnt(0)
	s_barrier
	v_mfma_f32_16x16x32_bf16 v[94:97], v[110:113], v[162:165], v[94:97]
	v_mfma_f32_16x16x32_bf16 v[10:13], v[122:125], v[162:165], v[10:13]
	v_mfma_f32_16x16x32_bf16 v[90:93], v[110:113], v[194:197], v[90:93]
	v_mfma_f32_16x16x32_bf16 v[6:9], v[122:125], v[194:197], v[6:9]
	v_mfma_f32_16x16x32_bf16 v[86:89], v[110:113], v[202:205], v[86:89]
	v_mfma_f32_16x16x32_bf16 v[2:5], v[122:125], v[202:205], v[2:5]
	v_mfma_f32_16x16x32_bf16 v[30:33], v[110:113], v[224:227], v[30:33]
	v_mfma_f32_16x16x32_bf16 v[26:29], v[122:125], v[224:227], v[26:29]
	v_mfma_f32_16x16x32_bf16 v[94:97], v[114:117], v[166:169], v[94:97]
	v_mfma_f32_16x16x32_bf16 v[10:13], v[126:129], v[166:169], v[10:13]
	v_mfma_f32_16x16x32_bf16 v[90:93], v[114:117], v[198:201], v[90:93]
	v_mfma_f32_16x16x32_bf16 v[6:9], v[126:129], v[198:201], v[6:9]
	v_mfma_f32_16x16x32_bf16 v[86:89], v[114:117], v[206:209], v[86:89]
	v_mfma_f32_16x16x32_bf16 v[2:5], v[126:129], v[206:209], v[2:5]
	v_mfma_f32_16x16x32_bf16 v[114:117], v[114:117], v[228:231], v[30:33]
	v_mfma_f32_16x16x32_bf16 v[26:29], v[126:129], v[228:231], v[26:29]
	v_mfma_f32_16x16x32_bf16 v[30:33], v[146:149], v[162:165], v[54:57]
	v_mfma_f32_16x16x32_bf16 v[110:113], v[150:153], v[166:169], v[30:33]
	v_mfma_f32_16x16x32_bf16 v[30:33], v[146:149], v[194:197], v[106:109]
	v_mfma_f32_16x16x32_bf16 v[106:109], v[150:153], v[198:201], v[30:33]
	v_mfma_f32_16x16x32_bf16 v[30:33], v[146:149], v[202:205], v[102:105]
	v_mfma_f32_16x16x32_bf16 v[102:105], v[150:153], v[206:209], v[30:33]
	v_mfma_f32_16x16x32_bf16 v[30:33], v[146:149], v[224:227], v[118:121]
	v_mfma_f32_16x16x32_bf16 v[22:25], v[154:157], v[162:165], v[22:25]
	v_mfma_f32_16x16x32_bf16 v[18:21], v[154:157], v[194:197], v[18:21]
	v_mfma_f32_16x16x32_bf16 v[14:17], v[154:157], v[202:205], v[14:17]
	v_mfma_f32_16x16x32_bf16 v[126:129], v[150:153], v[228:231], v[30:33]
	v_mfma_f32_16x16x32_bf16 v[30:33], v[154:157], v[224:227], v[58:61]
	v_mfma_f32_16x16x32_bf16 v[22:25], v[158:161], v[166:169], v[22:25]
	v_mfma_f32_16x16x32_bf16 v[18:21], v[158:161], v[198:201], v[18:21]
	v_mfma_f32_16x16x32_bf16 v[14:17], v[158:161], v[206:209], v[14:17]
	v_mfma_f32_16x16x32_bf16 v[58:61], v[158:161], v[228:231], v[30:33]
	s_barrier
	s_add_i32 s7, s7, 2
	s_add_u32 s8, s8, 0x100
	s_addc_u32 s9, s9, 0
	s_add_u32 vcc_hi, vcc_hi, 0x100
	s_addc_u32 s3, s3, 0
	s_cmp_gt_u32 s7, 13
	s_cbranch_scc0 .LBB0_557
	s_and_b64 vcc, exec, s[14:15]
	s_cbranch_vccz .LBB0_560
	s_barrier

.LBB0_732:
	s_add_u32 s24, s24, 0xb0080
	s_addc_u32 s25, s25, 0
	s_add_u32 s49, s26, 0x100
	s_addc_u32 s50, s27, 0
	s_mov_b32 s51, -2
	s_waitcnt lgkmcnt(0)
	ds_read_b128 v[78:81], v184
	ds_read_b128 v[86:89], v184 offset:1024
	ds_read_b128 v[90:93], v184 offset:2048
	ds_read_b128 v[94:97], v184 offset:3072
	ds_read_b128 v[146:149], v185
	ds_read_b128 v[150:153], v185 offset:1024
	ds_read_b128 v[176:179], v185 offset:2048
	ds_read_b128 v[180:183], v185 offset:3072
	s_add_u32 s26, s24, 0xfff50080
	s_addc_u32 s27, s25, -1
	s_cmp_eq_u32 s51, 40
	s_cselect_b32 s29, s9, s27
	s_cselect_b32 s28, s8, s26
	s_cselect_b32 s27, s23, s50
	s_cselect_b32 s26, s22, s49
	s_add_i32 m0, s34, 0xc000
	ds_read_b128 v[188:191], v186
	ds_read_b128 v[192:195], v186 offset:1024
	ds_read_b128 v[196:199], v186 offset:2048
	ds_read_b128 v[200:203], v186 offset:3072
	ds_read_b128 v[204:207], v186 offset:4096
	ds_read_b128 v[208:211], v186 offset:5120
	ds_read_b128 v[212:215], v186 offset:6144
	ds_read_b128 v[216:219], v186 offset:7168
	global_load_lds_dwordx4 v162, s[24:25]
	s_add_i32 m0, s34, 0xe000
	s_nop 0
	global_load_lds_dwordx4 v164, s[24:25]
	s_waitcnt vmcnt(8)
	s_waitcnt lgkmcnt(0)
	s_barrier
	v_mfma_f32_16x16x32_bf16 v[142:145], v[78:81], v[188:191], 0
	v_mfma_f32_16x16x32_bf16 v[138:141], v[90:93], v[188:191], 0
	v_mfma_f32_16x16x32_bf16 v[126:129], v[78:81], v[196:199], 0
	v_mfma_f32_16x16x32_bf16 v[122:125], v[90:93], v[196:199], 0
	v_mfma_f32_16x16x32_bf16 v[110:113], v[78:81], v[204:207], 0
	v_mfma_f32_16x16x32_bf16 v[106:109], v[90:93], v[204:207], 0
	v_mfma_f32_16x16x32_bf16 v[82:85], v[78:81], v[212:215], 0
	v_mfma_f32_16x16x32_bf16 v[74:77], v[90:93], v[212:215], 0
	v_mfma_f32_16x16x32_bf16 v[142:145], v[86:89], v[192:195], v[142:145]
	v_mfma_f32_16x16x32_bf16 v[138:141], v[94:97], v[192:195], v[138:141]
	v_mfma_f32_16x16x32_bf16 v[126:129], v[86:89], v[200:203], v[126:129]
	v_mfma_f32_16x16x32_bf16 v[122:125], v[94:97], v[200:203], v[122:125]
	v_mfma_f32_16x16x32_bf16 v[110:113], v[86:89], v[208:211], v[110:113]
	v_mfma_f32_16x16x32_bf16 v[106:109], v[94:97], v[208:211], v[106:109]
	v_mfma_f32_16x16x32_bf16 v[82:85], v[86:89], v[216:219], v[82:85]
	v_mfma_f32_16x16x32_bf16 v[74:77], v[94:97], v[216:219], v[74:77]
	v_mfma_f32_16x16x32_bf16 v[134:137], v[146:149], v[188:191], 0
	v_mfma_f32_16x16x32_bf16 v[130:133], v[176:179], v[188:191], 0
	v_mfma_f32_16x16x32_bf16 v[118:121], v[146:149], v[196:199], 0
	v_mfma_f32_16x16x32_bf16 v[114:117], v[176:179], v[196:199], 0
	v_mfma_f32_16x16x32_bf16 v[102:105], v[146:149], v[204:207], 0
	v_mfma_f32_16x16x32_bf16 v[98:101], v[176:179], v[204:207], 0
	v_mfma_f32_16x16x32_bf16 v[70:73], v[146:149], v[212:215], 0
	v_mfma_f32_16x16x32_bf16 v[66:69], v[176:179], v[212:215], 0
	v_mfma_f32_16x16x32_bf16 v[134:137], v[150:153], v[192:195], v[134:137]
	v_mfma_f32_16x16x32_bf16 v[130:133], v[180:183], v[192:195], v[130:133]
	v_mfma_f32_16x16x32_bf16 v[118:121], v[150:153], v[200:203], v[118:121]
	v_mfma_f32_16x16x32_bf16 v[114:117], v[180:183], v[200:203], v[114:117]
	v_mfma_f32_16x16x32_bf16 v[102:105], v[150:153], v[208:211], v[102:105]
	v_mfma_f32_16x16x32_bf16 v[98:101], v[180:183], v[208:211], v[98:101]
	v_mfma_f32_16x16x32_bf16 v[70:73], v[150:153], v[216:219], v[70:73]
	v_mfma_f32_16x16x32_bf16 v[66:69], v[180:183], v[216:219], v[66:69]
	s_barrier
	s_add_u32 s98, s26, 0x80
	s_addc_u32 s99, s27, 0
	s_add_u32 s100, s28, 0x80
	s_addc_u32 s101, s29, 0
	s_add_i32 s54, s43, s31
	s_mov_b32 m0, s54
	ds_read_b128 v[188:191], v186 offset:16384
	ds_read_b128 v[192:195], v186 offset:17408
	ds_read_b128 v[196:199], v186 offset:18432
	ds_read_b128 v[200:203], v186 offset:19456
	ds_read_b128 v[204:207], v186 offset:20480
	ds_read_b128 v[208:211], v186 offset:21504
	ds_read_b128 v[212:215], v186 offset:22528
	ds_read_b128 v[216:219], v186 offset:23552
	s_cmp_eq_u32 s51, 40
	s_cselect_b64 exec, 0, -1
	s_cmp_lg_u32 s33, 0x100
	s_cselect_b64 exec, -1, exec
	global_load_lds_dwordx4 v156, s[26:27]
	s_add_i32 m0, s54, 0x2000
	s_add_u32 s54, s26, 0xb0000
	s_addc_u32 s55, s27, 0
	s_add_i32 s58, s44, s31
	global_load_lds_dwordx4 v160, s[26:27]
	s_mov_b32 m0, s58
	s_nop 0
	global_load_lds_dwordx4 v156, s[54:55]
	s_add_i32 m0, s58, 0x2000
	s_nop 0
	global_load_lds_dwordx4 v160, s[54:55]
	s_mov_b32 m0, s34
	s_nop 0
	global_load_lds_dwordx4 v154, s[28:29]
	s_mov_b32 m0, s35
	s_nop 0
	global_load_lds_dwordx4 v158, s[28:29]
	s_mov_b64 exec, -1
	s_waitcnt vmcnt(8)
	s_waitcnt lgkmcnt(0)
	s_barrier
	v_mfma_f32_16x16x32_bf16 v[62:65], v[78:81], v[188:191], 0
	v_mfma_f32_16x16x32_bf16 v[58:61], v[90:93], v[188:191], 0
	v_mfma_f32_16x16x32_bf16 v[46:49], v[78:81], v[196:199], 0
	v_mfma_f32_16x16x32_bf16 v[42:45], v[90:93], v[196:199], 0
	v_mfma_f32_16x16x32_bf16 v[30:33], v[78:81], v[204:207], 0
	v_mfma_f32_16x16x32_bf16 v[26:29], v[90:93], v[204:207], 0
	v_mfma_f32_16x16x32_bf16 v[14:17], v[78:81], v[212:215], 0
	v_mfma_f32_16x16x32_bf16 v[10:13], v[90:93], v[212:215], 0
	v_mfma_f32_16x16x32_bf16 v[62:65], v[86:89], v[192:195], v[62:65]
	v_mfma_f32_16x16x32_bf16 v[58:61], v[94:97], v[192:195], v[58:61]
	v_mfma_f32_16x16x32_bf16 v[46:49], v[86:89], v[200:203], v[46:49]
	v_mfma_f32_16x16x32_bf16 v[42:45], v[94:97], v[200:203], v[42:45]
	v_mfma_f32_16x16x32_bf16 v[30:33], v[86:89], v[208:211], v[30:33]
	v_mfma_f32_16x16x32_bf16 v[26:29], v[94:97], v[208:211], v[26:29]
	v_mfma_f32_16x16x32_bf16 v[14:17], v[86:89], v[216:219], v[14:17]
	v_mfma_f32_16x16x32_bf16 v[10:13], v[94:97], v[216:219], v[10:13]
	v_mfma_f32_16x16x32_bf16 v[54:57], v[146:149], v[188:191], 0
	v_mfma_f32_16x16x32_bf16 v[50:53], v[176:179], v[188:191], 0
	v_mfma_f32_16x16x32_bf16 v[38:41], v[146:149], v[196:199], 0
	v_mfma_f32_16x16x32_bf16 v[34:37], v[176:179], v[196:199], 0
	v_mfma_f32_16x16x32_bf16 v[22:25], v[146:149], v[204:207], 0
	v_mfma_f32_16x16x32_bf16 v[18:21], v[176:179], v[204:207], 0
	v_mfma_f32_16x16x32_bf16 v[6:9], v[146:149], v[212:215], 0
	v_mfma_f32_16x16x32_bf16 v[2:5], v[176:179], v[212:215], 0
	v_mfma_f32_16x16x32_bf16 v[54:57], v[150:153], v[192:195], v[54:57]
	v_mfma_f32_16x16x32_bf16 v[50:53], v[180:183], v[192:195], v[50:53]
	v_mfma_f32_16x16x32_bf16 v[38:41], v[150:153], v[200:203], v[38:41]
	v_mfma_f32_16x16x32_bf16 v[34:37], v[180:183], v[200:203], v[34:37]
	v_mfma_f32_16x16x32_bf16 v[22:25], v[150:153], v[208:211], v[22:25]
	v_mfma_f32_16x16x32_bf16 v[18:21], v[180:183], v[208:211], v[18:21]
	v_mfma_f32_16x16x32_bf16 v[6:9], v[150:153], v[216:219], v[6:9]
	v_mfma_f32_16x16x32_bf16 v[2:5], v[180:183], v[216:219], v[2:5]
	s_barrier
	s_add_i32 s54, 0, 0x18000
	v_add_u32_e32 v1, s54, v173
	s_add_i32 s55, 0, 0x1c000
	ds_read_b128 v[78:81], v1
	ds_read_b128 v[86:89], v1 offset:1024
	ds_read_b128 v[90:93], v1 offset:2048
	ds_read_b128 v[94:97], v1 offset:3072
	v_add_u32_e32 v1, s55, v173
	ds_read_b128 v[146:149], v1
	ds_read_b128 v[150:153], v1 offset:1024
	ds_read_b128 v[176:179], v1 offset:2048
	ds_read_b128 v[180:183], v1 offset:3072
	s_add_u32 s28, s28, 0xb0000
	s_addc_u32 s29, s29, 0
	s_mov_b32 m0, s36
	ds_read_b128 v[188:191], v186 offset:32768
	ds_read_b128 v[192:195], v186 offset:33792
	ds_read_b128 v[196:199], v186 offset:34816
	ds_read_b128 v[200:203], v186 offset:35840
	ds_read_b128 v[204:207], v186 offset:36864
	ds_read_b128 v[208:211], v186 offset:37888
	ds_read_b128 v[212:215], v186 offset:38912
	ds_read_b128 v[216:219], v186 offset:39936
	s_cmp_eq_u32 s51, 40
	s_cselect_b64 exec, 0, -1
	s_cmp_lg_u32 s33, 0x100
	s_cselect_b64 exec, -1, exec
	global_load_lds_dwordx4 v154, s[28:29]
	s_mov_b32 m0, s37
	s_nop 0
	global_load_lds_dwordx4 v158, s[28:29]
	s_mov_b64 exec, -1
	s_waitcnt vmcnt(8)
	s_waitcnt lgkmcnt(0)
	s_barrier
	v_mfma_f32_16x16x32_bf16 v[142:145], v[78:81], v[188:191], v[142:145]
	v_mfma_f32_16x16x32_bf16 v[138:141], v[90:93], v[188:191], v[138:141]
	v_mfma_f32_16x16x32_bf16 v[126:129], v[78:81], v[196:199], v[126:129]
	v_mfma_f32_16x16x32_bf16 v[122:125], v[90:93], v[196:199], v[122:125]
	v_mfma_f32_16x16x32_bf16 v[110:113], v[78:81], v[204:207], v[110:113]
	v_mfma_f32_16x16x32_bf16 v[106:109], v[90:93], v[204:207], v[106:109]
	v_mfma_f32_16x16x32_bf16 v[82:85], v[78:81], v[212:215], v[82:85]
	v_mfma_f32_16x16x32_bf16 v[74:77], v[90:93], v[212:215], v[74:77]
	v_mfma_f32_16x16x32_bf16 v[142:145], v[86:89], v[192:195], v[142:145]
	v_mfma_f32_16x16x32_bf16 v[138:141], v[94:97], v[192:195], v[138:141]
	v_mfma_f32_16x16x32_bf16 v[126:129], v[86:89], v[200:203], v[126:129]
	v_mfma_f32_16x16x32_bf16 v[122:125], v[94:97], v[200:203], v[122:125]
	v_mfma_f32_16x16x32_bf16 v[110:113], v[86:89], v[208:211], v[110:113]
	v_mfma_f32_16x16x32_bf16 v[106:109], v[94:97], v[208:211], v[106:109]
	v_mfma_f32_16x16x32_bf16 v[82:85], v[86:89], v[216:219], v[82:85]
	v_mfma_f32_16x16x32_bf16 v[74:77], v[94:97], v[216:219], v[74:77]
	v_mfma_f32_16x16x32_bf16 v[134:137], v[146:149], v[188:191], v[134:137]
	v_mfma_f32_16x16x32_bf16 v[130:133], v[176:179], v[188:191], v[130:133]
	v_mfma_f32_16x16x32_bf16 v[118:121], v[146:149], v[196:199], v[118:121]
	v_mfma_f32_16x16x32_bf16 v[114:117], v[176:179], v[196:199], v[114:117]
	v_mfma_f32_16x16x32_bf16 v[102:105], v[146:149], v[204:207], v[102:105]
	v_mfma_f32_16x16x32_bf16 v[98:101], v[176:179], v[204:207], v[98:101]
	v_mfma_f32_16x16x32_bf16 v[70:73], v[146:149], v[212:215], v[70:73]
	v_mfma_f32_16x16x32_bf16 v[66:69], v[176:179], v[212:215], v[66:69]
	v_mfma_f32_16x16x32_bf16 v[134:137], v[150:153], v[192:195], v[134:137]
	v_mfma_f32_16x16x32_bf16 v[130:133], v[180:183], v[192:195], v[130:133]
	v_mfma_f32_16x16x32_bf16 v[118:121], v[150:153], v[200:203], v[118:121]
	v_mfma_f32_16x16x32_bf16 v[114:117], v[180:183], v[200:203], v[114:117]
	v_mfma_f32_16x16x32_bf16 v[102:105], v[150:153], v[208:211], v[102:105]
	v_mfma_f32_16x16x32_bf16 v[98:101], v[180:183], v[208:211], v[98:101]
	v_mfma_f32_16x16x32_bf16 v[70:73], v[150:153], v[216:219], v[70:73]
	v_mfma_f32_16x16x32_bf16 v[66:69], v[180:183], v[216:219], v[66:69]
	s_barrier
	s_add_i32 s28, s54, s31
	s_mov_b32 m0, s28
	ds_read_b128 v[188:191], v186 offset:49152
	ds_read_b128 v[192:195], v186 offset:50176
	ds_read_b128 v[196:199], v186 offset:51200
	ds_read_b128 v[200:203], v186 offset:52224
	ds_read_b128 v[204:207], v186 offset:53248
	ds_read_b128 v[208:211], v186 offset:54272
	ds_read_b128 v[212:215], v186 offset:55296
	ds_read_b128 v[216:219], v186 offset:56320
	s_cmp_eq_u32 s51, 40
	s_cselect_b64 exec, 0, -1
	s_cmp_lg_u32 s33, 0x100
	s_cselect_b64 exec, -1, exec
	global_load_lds_dwordx4 v156, s[98:99]
	s_add_i32 m0, s28, 0x2000
	s_add_u32 s26, s26, 0xb0080
	s_addc_u32 s27, s27, 0
	s_add_i32 s28, s55, s31
	global_load_lds_dwordx4 v160, s[98:99]
	s_mov_b32 m0, s28
	s_nop 0
	global_load_lds_dwordx4 v156, s[26:27]
	s_add_i32 m0, s28, 0x2000
	s_nop 0
	global_load_lds_dwordx4 v160, s[26:27]
	s_mov_b32 m0, s41
	s_nop 0
	global_load_lds_dwordx4 v154, s[100:101]
	s_mov_b32 m0, s42
	s_nop 0
	global_load_lds_dwordx4 v158, s[100:101]
	s_mov_b64 exec, -1
	s_waitcnt vmcnt(8)
	s_waitcnt lgkmcnt(0)
	s_barrier
	v_mfma_f32_16x16x32_bf16 v[62:65], v[78:81], v[188:191], v[62:65]
	v_mfma_f32_16x16x32_bf16 v[58:61], v[90:93], v[188:191], v[58:61]
	v_mfma_f32_16x16x32_bf16 v[46:49], v[78:81], v[196:199], v[46:49]
	v_mfma_f32_16x16x32_bf16 v[42:45], v[90:93], v[196:199], v[42:45]
	v_mfma_f32_16x16x32_bf16 v[30:33], v[78:81], v[204:207], v[30:33]
	v_mfma_f32_16x16x32_bf16 v[26:29], v[90:93], v[204:207], v[26:29]
	v_mfma_f32_16x16x32_bf16 v[14:17], v[78:81], v[212:215], v[14:17]
	v_mfma_f32_16x16x32_bf16 v[10:13], v[90:93], v[212:215], v[10:13]
	v_mfma_f32_16x16x32_bf16 v[62:65], v[86:89], v[192:195], v[62:65]
	v_mfma_f32_16x16x32_bf16 v[58:61], v[94:97], v[192:195], v[58:61]
	v_mfma_f32_16x16x32_bf16 v[46:49], v[86:89], v[200:203], v[46:49]
	v_mfma_f32_16x16x32_bf16 v[42:45], v[94:97], v[200:203], v[42:45]
	v_mfma_f32_16x16x32_bf16 v[30:33], v[86:89], v[208:211], v[30:33]
	v_mfma_f32_16x16x32_bf16 v[26:29], v[94:97], v[208:211], v[26:29]
	v_mfma_f32_16x16x32_bf16 v[14:17], v[86:89], v[216:219], v[14:17]
	v_mfma_f32_16x16x32_bf16 v[10:13], v[94:97], v[216:219], v[10:13]
	v_mfma_f32_16x16x32_bf16 v[54:57], v[146:149], v[188:191], v[54:57]
	v_mfma_f32_16x16x32_bf16 v[50:53], v[176:179], v[188:191], v[50:53]
	v_mfma_f32_16x16x32_bf16 v[38:41], v[146:149], v[196:199], v[38:41]
	v_mfma_f32_16x16x32_bf16 v[34:37], v[176:179], v[196:199], v[34:37]
	v_mfma_f32_16x16x32_bf16 v[22:25], v[146:149], v[204:207], v[22:25]
	v_mfma_f32_16x16x32_bf16 v[18:21], v[176:179], v[204:207], v[18:21]
	v_mfma_f32_16x16x32_bf16 v[6:9], v[146:149], v[212:215], v[6:9]
	v_mfma_f32_16x16x32_bf16 v[2:5], v[176:179], v[212:215], v[2:5]
	v_mfma_f32_16x16x32_bf16 v[54:57], v[150:153], v[192:195], v[54:57]
	v_mfma_f32_16x16x32_bf16 v[50:53], v[180:183], v[192:195], v[50:53]
	v_mfma_f32_16x16x32_bf16 v[38:41], v[150:153], v[200:203], v[38:41]
	v_mfma_f32_16x16x32_bf16 v[34:37], v[180:183], v[200:203], v[34:37]
	v_mfma_f32_16x16x32_bf16 v[22:25], v[150:153], v[208:211], v[22:25]
	v_mfma_f32_16x16x32_bf16 v[18:21], v[180:183], v[208:211], v[18:21]
	v_mfma_f32_16x16x32_bf16 v[6:9], v[150:153], v[216:219], v[6:9]
	v_mfma_f32_16x16x32_bf16 v[2:5], v[180:183], v[216:219], v[2:5]
	s_barrier
	s_add_i32 s51, s51, 2
	s_add_u32 s24, s24, 0x100
	s_addc_u32 s25, s25, 0
	s_add_u32 s49, s49, 0x100
	s_addc_u32 s50, s50, 0
	s_cmp_gt_u32 s51, 41
.LBB0_733:
	ds_read_b128 v[78:81], v184
	ds_read_b128 v[86:89], v184 offset:1024
	ds_read_b128 v[90:93], v184 offset:2048
	ds_read_b128 v[94:97], v184 offset:3072
	ds_read_b128 v[146:149], v185
	ds_read_b128 v[150:153], v185 offset:1024
	ds_read_b128 v[176:179], v185 offset:2048
	ds_read_b128 v[180:183], v185 offset:3072
	s_add_u32 s26, s24, 0xfff50080
	s_addc_u32 s27, s25, -1
	s_cmp_eq_u32 s51, 40
	s_cselect_b32 s29, s9, s27
	s_cselect_b32 s28, s8, s26
	s_cselect_b32 s27, s23, s50
	s_cselect_b32 s26, s22, s49
	s_add_i32 m0, s34, 0xc000
	ds_read_b128 v[188:191], v186
	ds_read_b128 v[192:195], v186 offset:1024
	ds_read_b128 v[196:199], v186 offset:2048
	ds_read_b128 v[200:203], v186 offset:3072
	ds_read_b128 v[204:207], v186 offset:4096
	ds_read_b128 v[208:211], v186 offset:5120
	ds_read_b128 v[212:215], v186 offset:6144
	ds_read_b128 v[216:219], v186 offset:7168
	global_load_lds_dwordx4 v162, s[24:25]
	s_add_i32 m0, s34, 0xe000
	s_nop 0
	global_load_lds_dwordx4 v164, s[24:25]
	s_waitcnt vmcnt(8)
	s_waitcnt lgkmcnt(0)
	s_barrier
	v_mfma_f32_16x16x32_bf16 v[142:145], v[78:81], v[188:191], v[142:145]
	v_mfma_f32_16x16x32_bf16 v[138:141], v[90:93], v[188:191], v[138:141]
	v_mfma_f32_16x16x32_bf16 v[126:129], v[78:81], v[196:199], v[126:129]
	v_mfma_f32_16x16x32_bf16 v[122:125], v[90:93], v[196:199], v[122:125]
	v_mfma_f32_16x16x32_bf16 v[110:113], v[78:81], v[204:207], v[110:113]
	v_mfma_f32_16x16x32_bf16 v[106:109], v[90:93], v[204:207], v[106:109]
	v_mfma_f32_16x16x32_bf16 v[82:85], v[78:81], v[212:215], v[82:85]
	v_mfma_f32_16x16x32_bf16 v[74:77], v[90:93], v[212:215], v[74:77]
	v_mfma_f32_16x16x32_bf16 v[142:145], v[86:89], v[192:195], v[142:145]
	v_mfma_f32_16x16x32_bf16 v[138:141], v[94:97], v[192:195], v[138:141]
	v_mfma_f32_16x16x32_bf16 v[126:129], v[86:89], v[200:203], v[126:129]
	v_mfma_f32_16x16x32_bf16 v[122:125], v[94:97], v[200:203], v[122:125]
	v_mfma_f32_16x16x32_bf16 v[110:113], v[86:89], v[208:211], v[110:113]
	v_mfma_f32_16x16x32_bf16 v[106:109], v[94:97], v[208:211], v[106:109]
	v_mfma_f32_16x16x32_bf16 v[82:85], v[86:89], v[216:219], v[82:85]
	v_mfma_f32_16x16x32_bf16 v[74:77], v[94:97], v[216:219], v[74:77]
	v_mfma_f32_16x16x32_bf16 v[134:137], v[146:149], v[188:191], v[134:137]
	v_mfma_f32_16x16x32_bf16 v[130:133], v[176:179], v[188:191], v[130:133]
	v_mfma_f32_16x16x32_bf16 v[118:121], v[146:149], v[196:199], v[118:121]
	v_mfma_f32_16x16x32_bf16 v[114:117], v[176:179], v[196:199], v[114:117]
	v_mfma_f32_16x16x32_bf16 v[102:105], v[146:149], v[204:207], v[102:105]
	v_mfma_f32_16x16x32_bf16 v[98:101], v[176:179], v[204:207], v[98:101]
	v_mfma_f32_16x16x32_bf16 v[70:73], v[146:149], v[212:215], v[70:73]
	v_mfma_f32_16x16x32_bf16 v[66:69], v[176:179], v[212:215], v[66:69]
	v_mfma_f32_16x16x32_bf16 v[134:137], v[150:153], v[192:195], v[134:137]
	v_mfma_f32_16x16x32_bf16 v[130:133], v[180:183], v[192:195], v[130:133]
	v_mfma_f32_16x16x32_bf16 v[118:121], v[150:153], v[200:203], v[118:121]
	v_mfma_f32_16x16x32_bf16 v[114:117], v[180:183], v[200:203], v[114:117]
	v_mfma_f32_16x16x32_bf16 v[102:105], v[150:153], v[208:211], v[102:105]
	v_mfma_f32_16x16x32_bf16 v[98:101], v[180:183], v[208:211], v[98:101]
	v_mfma_f32_16x16x32_bf16 v[70:73], v[150:153], v[216:219], v[70:73]
	v_mfma_f32_16x16x32_bf16 v[66:69], v[180:183], v[216:219], v[66:69]
	s_barrier
	s_add_u32 s98, s26, 0x80
	s_addc_u32 s99, s27, 0
	s_add_u32 s100, s28, 0x80
	s_addc_u32 s101, s29, 0
	s_add_i32 s54, s43, s31
	s_mov_b32 m0, s54
	ds_read_b128 v[188:191], v186 offset:16384
	ds_read_b128 v[192:195], v186 offset:17408
	ds_read_b128 v[196:199], v186 offset:18432
	ds_read_b128 v[200:203], v186 offset:19456
	ds_read_b128 v[204:207], v186 offset:20480
	ds_read_b128 v[208:211], v186 offset:21504
	ds_read_b128 v[212:215], v186 offset:22528
	ds_read_b128 v[216:219], v186 offset:23552
	s_cmp_eq_u32 s51, 40
	s_cselect_b64 exec, 0, -1
	s_cmp_lg_u32 s33, 0x100
	s_cselect_b64 exec, -1, exec
	global_load_lds_dwordx4 v156, s[26:27]
	s_add_i32 m0, s54, 0x2000
	s_add_u32 s54, s26, 0xb0000
	s_addc_u32 s55, s27, 0
	s_add_i32 s58, s44, s31
	global_load_lds_dwordx4 v160, s[26:27]
	s_mov_b32 m0, s58
	s_nop 0
	global_load_lds_dwordx4 v156, s[54:55]
	s_add_i32 m0, s58, 0x2000
	s_nop 0
	global_load_lds_dwordx4 v160, s[54:55]
	s_mov_b32 m0, s34
	s_nop 0
	global_load_lds_dwordx4 v154, s[28:29]
	s_mov_b32 m0, s35
	s_nop 0
	global_load_lds_dwordx4 v158, s[28:29]
	s_mov_b64 exec, -1
	s_waitcnt vmcnt(8)
	s_waitcnt lgkmcnt(0)
	s_barrier
	v_mfma_f32_16x16x32_bf16 v[62:65], v[78:81], v[188:191], v[62:65]
	v_mfma_f32_16x16x32_bf16 v[58:61], v[90:93], v[188:191], v[58:61]
	v_mfma_f32_16x16x32_bf16 v[46:49], v[78:81], v[196:199], v[46:49]
	v_mfma_f32_16x16x32_bf16 v[42:45], v[90:93], v[196:199], v[42:45]
	v_mfma_f32_16x16x32_bf16 v[30:33], v[78:81], v[204:207], v[30:33]
	v_mfma_f32_16x16x32_bf16 v[26:29], v[90:93], v[204:207], v[26:29]
	v_mfma_f32_16x16x32_bf16 v[14:17], v[78:81], v[212:215], v[14:17]
	v_mfma_f32_16x16x32_bf16 v[10:13], v[90:93], v[212:215], v[10:13]
	v_mfma_f32_16x16x32_bf16 v[62:65], v[86:89], v[192:195], v[62:65]
	v_mfma_f32_16x16x32_bf16 v[58:61], v[94:97], v[192:195], v[58:61]
	v_mfma_f32_16x16x32_bf16 v[46:49], v[86:89], v[200:203], v[46:49]
	v_mfma_f32_16x16x32_bf16 v[42:45], v[94:97], v[200:203], v[42:45]
	v_mfma_f32_16x16x32_bf16 v[30:33], v[86:89], v[208:211], v[30:33]
	v_mfma_f32_16x16x32_bf16 v[26:29], v[94:97], v[208:211], v[26:29]
	v_mfma_f32_16x16x32_bf16 v[14:17], v[86:89], v[216:219], v[14:17]
	v_mfma_f32_16x16x32_bf16 v[10:13], v[94:97], v[216:219], v[10:13]
	v_mfma_f32_16x16x32_bf16 v[54:57], v[146:149], v[188:191], v[54:57]
	v_mfma_f32_16x16x32_bf16 v[50:53], v[176:179], v[188:191], v[50:53]
	v_mfma_f32_16x16x32_bf16 v[38:41], v[146:149], v[196:199], v[38:41]
	v_mfma_f32_16x16x32_bf16 v[34:37], v[176:179], v[196:199], v[34:37]
	v_mfma_f32_16x16x32_bf16 v[22:25], v[146:149], v[204:207], v[22:25]
	v_mfma_f32_16x16x32_bf16 v[18:21], v[176:179], v[204:207], v[18:21]
	v_mfma_f32_16x16x32_bf16 v[6:9], v[146:149], v[212:215], v[6:9]
	v_mfma_f32_16x16x32_bf16 v[2:5], v[176:179], v[212:215], v[2:5]
	v_mfma_f32_16x16x32_bf16 v[54:57], v[150:153], v[192:195], v[54:57]
	v_mfma_f32_16x16x32_bf16 v[50:53], v[180:183], v[192:195], v[50:53]
	v_mfma_f32_16x16x32_bf16 v[38:41], v[150:153], v[200:203], v[38:41]
	v_mfma_f32_16x16x32_bf16 v[34:37], v[180:183], v[200:203], v[34:37]
	v_mfma_f32_16x16x32_bf16 v[22:25], v[150:153], v[208:211], v[22:25]
	v_mfma_f32_16x16x32_bf16 v[18:21], v[180:183], v[208:211], v[18:21]
	v_mfma_f32_16x16x32_bf16 v[6:9], v[150:153], v[216:219], v[6:9]
	v_mfma_f32_16x16x32_bf16 v[2:5], v[180:183], v[216:219], v[2:5]
	s_barrier
	s_add_i32 s54, 0, 0x18000
	v_add_u32_e32 v1, s54, v173
	s_add_i32 s55, 0, 0x1c000
	ds_read_b128 v[78:81], v1
	ds_read_b128 v[86:89], v1 offset:1024
	ds_read_b128 v[90:93], v1 offset:2048
	ds_read_b128 v[94:97], v1 offset:3072
	v_add_u32_e32 v1, s55, v173
	ds_read_b128 v[146:149], v1
	ds_read_b128 v[150:153], v1 offset:1024
	ds_read_b128 v[176:179], v1 offset:2048
	ds_read_b128 v[180:183], v1 offset:3072
	s_add_u32 s28, s28, 0xb0000
	s_addc_u32 s29, s29, 0
	s_mov_b32 m0, s36
	ds_read_b128 v[188:191], v186 offset:32768
	ds_read_b128 v[192:195], v186 offset:33792
	ds_read_b128 v[196:199], v186 offset:34816
	ds_read_b128 v[200:203], v186 offset:35840
	ds_read_b128 v[204:207], v186 offset:36864
	ds_read_b128 v[208:211], v186 offset:37888
	ds_read_b128 v[212:215], v186 offset:38912
	ds_read_b128 v[216:219], v186 offset:39936
	s_cmp_eq_u32 s51, 40
	s_cselect_b64 exec, 0, -1
	s_cmp_lg_u32 s33, 0x100
	s_cselect_b64 exec, -1, exec
	global_load_lds_dwordx4 v154, s[28:29]
	s_mov_b32 m0, s37
	s_nop 0
	global_load_lds_dwordx4 v158, s[28:29]
	s_mov_b64 exec, -1
	s_waitcnt vmcnt(8)
	s_waitcnt lgkmcnt(0)
	s_barrier
	v_mfma_f32_16x16x32_bf16 v[142:145], v[78:81], v[188:191], v[142:145]
	v_mfma_f32_16x16x32_bf16 v[138:141], v[90:93], v[188:191], v[138:141]
	v_mfma_f32_16x16x32_bf16 v[126:129], v[78:81], v[196:199], v[126:129]
	v_mfma_f32_16x16x32_bf16 v[122:125], v[90:93], v[196:199], v[122:125]
	v_mfma_f32_16x16x32_bf16 v[110:113], v[78:81], v[204:207], v[110:113]
	v_mfma_f32_16x16x32_bf16 v[106:109], v[90:93], v[204:207], v[106:109]
	v_mfma_f32_16x16x32_bf16 v[82:85], v[78:81], v[212:215], v[82:85]
	v_mfma_f32_16x16x32_bf16 v[74:77], v[90:93], v[212:215], v[74:77]
	v_mfma_f32_16x16x32_bf16 v[142:145], v[86:89], v[192:195], v[142:145]
	v_mfma_f32_16x16x32_bf16 v[138:141], v[94:97], v[192:195], v[138:141]
	v_mfma_f32_16x16x32_bf16 v[126:129], v[86:89], v[200:203], v[126:129]
	v_mfma_f32_16x16x32_bf16 v[122:125], v[94:97], v[200:203], v[122:125]
	v_mfma_f32_16x16x32_bf16 v[110:113], v[86:89], v[208:211], v[110:113]
	v_mfma_f32_16x16x32_bf16 v[106:109], v[94:97], v[208:211], v[106:109]
	v_mfma_f32_16x16x32_bf16 v[82:85], v[86:89], v[216:219], v[82:85]
	v_mfma_f32_16x16x32_bf16 v[74:77], v[94:97], v[216:219], v[74:77]
	v_mfma_f32_16x16x32_bf16 v[134:137], v[146:149], v[188:191], v[134:137]
	v_mfma_f32_16x16x32_bf16 v[130:133], v[176:179], v[188:191], v[130:133]
	v_mfma_f32_16x16x32_bf16 v[118:121], v[146:149], v[196:199], v[118:121]
	v_mfma_f32_16x16x32_bf16 v[114:117], v[176:179], v[196:199], v[114:117]
	v_mfma_f32_16x16x32_bf16 v[102:105], v[146:149], v[204:207], v[102:105]
	v_mfma_f32_16x16x32_bf16 v[98:101], v[176:179], v[204:207], v[98:101]
	v_mfma_f32_16x16x32_bf16 v[70:73], v[146:149], v[212:215], v[70:73]
	v_mfma_f32_16x16x32_bf16 v[66:69], v[176:179], v[212:215], v[66:69]
	v_mfma_f32_16x16x32_bf16 v[134:137], v[150:153], v[192:195], v[134:137]
	v_mfma_f32_16x16x32_bf16 v[130:133], v[180:183], v[192:195], v[130:133]
	v_mfma_f32_16x16x32_bf16 v[118:121], v[150:153], v[200:203], v[118:121]
	v_mfma_f32_16x16x32_bf16 v[114:117], v[180:183], v[200:203], v[114:117]
	v_mfma_f32_16x16x32_bf16 v[102:105], v[150:153], v[208:211], v[102:105]
	v_mfma_f32_16x16x32_bf16 v[98:101], v[180:183], v[208:211], v[98:101]
	v_mfma_f32_16x16x32_bf16 v[70:73], v[150:153], v[216:219], v[70:73]
	v_mfma_f32_16x16x32_bf16 v[66:69], v[180:183], v[216:219], v[66:69]
	s_barrier
	s_add_i32 s28, s54, s31
	s_mov_b32 m0, s28
	ds_read_b128 v[188:191], v186 offset:49152
	ds_read_b128 v[192:195], v186 offset:50176
	ds_read_b128 v[196:199], v186 offset:51200
	ds_read_b128 v[200:203], v186 offset:52224
	ds_read_b128 v[204:207], v186 offset:53248
	ds_read_b128 v[208:211], v186 offset:54272
	ds_read_b128 v[212:215], v186 offset:55296
	ds_read_b128 v[216:219], v186 offset:56320
	s_cmp_eq_u32 s51, 40
	s_cselect_b64 exec, 0, -1
	s_cmp_lg_u32 s33, 0x100
	s_cselect_b64 exec, -1, exec
	global_load_lds_dwordx4 v156, s[98:99]
	s_add_i32 m0, s28, 0x2000
	s_add_u32 s26, s26, 0xb0080
	s_addc_u32 s27, s27, 0
	s_add_i32 s28, s55, s31
	global_load_lds_dwordx4 v160, s[98:99]
	s_mov_b32 m0, s28
	s_nop 0
	global_load_lds_dwordx4 v156, s[26:27]
	s_add_i32 m0, s28, 0x2000
	s_nop 0
	global_load_lds_dwordx4 v160, s[26:27]
	s_mov_b32 m0, s41
	s_nop 0
	global_load_lds_dwordx4 v154, s[100:101]
	s_mov_b32 m0, s42
	s_nop 0
	global_load_lds_dwordx4 v158, s[100:101]
	s_mov_b64 exec, -1
	s_waitcnt vmcnt(8)
	s_waitcnt lgkmcnt(0)
	s_barrier
	v_mfma_f32_16x16x32_bf16 v[62:65], v[78:81], v[188:191], v[62:65]
	v_mfma_f32_16x16x32_bf16 v[58:61], v[90:93], v[188:191], v[58:61]
	v_mfma_f32_16x16x32_bf16 v[46:49], v[78:81], v[196:199], v[46:49]
	v_mfma_f32_16x16x32_bf16 v[42:45], v[90:93], v[196:199], v[42:45]
	v_mfma_f32_16x16x32_bf16 v[30:33], v[78:81], v[204:207], v[30:33]
	v_mfma_f32_16x16x32_bf16 v[26:29], v[90:93], v[204:207], v[26:29]
	v_mfma_f32_16x16x32_bf16 v[14:17], v[78:81], v[212:215], v[14:17]
	v_mfma_f32_16x16x32_bf16 v[10:13], v[90:93], v[212:215], v[10:13]
	v_mfma_f32_16x16x32_bf16 v[62:65], v[86:89], v[192:195], v[62:65]
	v_mfma_f32_16x16x32_bf16 v[58:61], v[94:97], v[192:195], v[58:61]
	v_mfma_f32_16x16x32_bf16 v[46:49], v[86:89], v[200:203], v[46:49]
	v_mfma_f32_16x16x32_bf16 v[42:45], v[94:97], v[200:203], v[42:45]
	v_mfma_f32_16x16x32_bf16 v[30:33], v[86:89], v[208:211], v[30:33]
	v_mfma_f32_16x16x32_bf16 v[26:29], v[94:97], v[208:211], v[26:29]
	v_mfma_f32_16x16x32_bf16 v[14:17], v[86:89], v[216:219], v[14:17]
	v_mfma_f32_16x16x32_bf16 v[10:13], v[94:97], v[216:219], v[10:13]
	v_mfma_f32_16x16x32_bf16 v[54:57], v[146:149], v[188:191], v[54:57]
	v_mfma_f32_16x16x32_bf16 v[50:53], v[176:179], v[188:191], v[50:53]
	v_mfma_f32_16x16x32_bf16 v[38:41], v[146:149], v[196:199], v[38:41]
	v_mfma_f32_16x16x32_bf16 v[34:37], v[176:179], v[196:199], v[34:37]
	v_mfma_f32_16x16x32_bf16 v[22:25], v[146:149], v[204:207], v[22:25]
	v_mfma_f32_16x16x32_bf16 v[18:21], v[176:179], v[204:207], v[18:21]
	v_mfma_f32_16x16x32_bf16 v[6:9], v[146:149], v[212:215], v[6:9]
	v_mfma_f32_16x16x32_bf16 v[2:5], v[176:179], v[212:215], v[2:5]
	v_mfma_f32_16x16x32_bf16 v[54:57], v[150:153], v[192:195], v[54:57]
	v_mfma_f32_16x16x32_bf16 v[50:53], v[180:183], v[192:195], v[50:53]
	v_mfma_f32_16x16x32_bf16 v[38:41], v[150:153], v[200:203], v[38:41]
	v_mfma_f32_16x16x32_bf16 v[34:37], v[180:183], v[200:203], v[34:37]
	v_mfma_f32_16x16x32_bf16 v[22:25], v[150:153], v[208:211], v[22:25]
	v_mfma_f32_16x16x32_bf16 v[18:21], v[180:183], v[208:211], v[18:21]
	v_mfma_f32_16x16x32_bf16 v[6:9], v[150:153], v[216:219], v[6:9]
	v_mfma_f32_16x16x32_bf16 v[2:5], v[180:183], v[216:219], v[2:5]
	s_barrier
	s_add_i32 s51, s51, 2
	s_add_u32 s24, s24, 0x100
	s_addc_u32 s25, s25, 0
	s_add_u32 s49, s49, 0x100
	s_addc_u32 s50, s50, 0
	s_cmp_gt_u32 s51, 41
	s_cbranch_scc0 .LBB0_733
	s_and_b64 vcc, exec, s[20:21]
	s_cbranch_vccz .LBB0_736
	s_barrier

.LBB0_1203:
	s_ashr_i32 s35, s34, 31
	s_lshl_b64 s[36:37], s[34:35], 19
	ds_read_b128 v[2:5], v190
	ds_read_b128 v[6:9], v190 offset:1024
	ds_read_b128 v[10:13], v190 offset:2048
	ds_read_b128 v[14:17], v190 offset:3072
	ds_read_b128 v[18:21], v191
	ds_read_b128 v[22:25], v191 offset:1024
	ds_read_b128 v[26:29], v191 offset:2048
	ds_read_b128 v[30:33], v191 offset:3072
	s_add_u32 s9, s52, s36
	s_addc_u32 s35, s53, s37
	s_ashr_i32 s31, s30, 31
	s_lshl_b64 s[36:37], s[30:31], 9
	s_add_u32 s36, s9, s36
	s_addc_u32 s37, s35, s37
	s_and_b64 s[38:39], s[4:5], exec
	s_cselect_b32 s49, s37, s41
	s_cselect_b32 s48, s36, s40
	s_lshl_b64 s[38:39], s[30:31], 17
	s_add_u32 s38, s3, s38
	s_addc_u32 s39, s6, s39
	s_and_b64 s[46:47], s[4:5], exec
	s_cselect_b32 s47, s39, s45
	s_cselect_b32 s46, s38, s44
	s_add_u32 s74, s40, 0x40080
	s_addc_u32 s75, s41, 0
	s_add_i32 s77, s43, 0xc000
	v_lshl_add_u64 v[66:67], s[74:75], 0, v[146:147]
	s_mov_b32 m0, s77
	s_add_i32 s9, s43, 0xe000
	ds_read_b128 v[34:37], v192
	ds_read_b128 v[38:41], v192 offset:1024
	ds_read_b128 v[42:45], v192 offset:2048
	ds_read_b128 v[46:49], v192 offset:3072
	ds_read_b128 v[50:53], v192 offset:4096
	ds_read_b128 v[54:57], v192 offset:5120
	ds_read_b128 v[58:61], v192 offset:6144
	ds_read_b128 v[62:65], v192 offset:7168
	global_load_lds_dwordx4 v[66:67], off
	v_lshl_add_u64 v[66:67], s[74:75], 0, v[150:151]
	s_mov_b32 m0, s9
	s_nop 0
	global_load_lds_dwordx4 v[66:67], off
	s_waitcnt vmcnt(8)
	s_waitcnt lgkmcnt(0)
	s_barrier
	v_mfma_f32_16x16x32_bf16 v[66:69], v[2:5], v[34:37], 0
	v_mfma_f32_16x16x32_bf16 v[70:73], v[10:13], v[34:37], 0
	v_mfma_f32_16x16x32_bf16 v[74:77], v[2:5], v[42:45], 0
	v_mfma_f32_16x16x32_bf16 v[78:81], v[10:13], v[42:45], 0
	v_mfma_f32_16x16x32_bf16 v[82:85], v[2:5], v[50:53], 0
	v_mfma_f32_16x16x32_bf16 v[86:89], v[10:13], v[50:53], 0
	v_mfma_f32_16x16x32_bf16 v[90:93], v[2:5], v[58:61], 0
	v_mfma_f32_16x16x32_bf16 v[94:97], v[10:13], v[58:61], 0
	v_mfma_f32_16x16x32_bf16 v[66:69], v[6:9], v[38:41], v[66:69]
	v_mfma_f32_16x16x32_bf16 v[70:73], v[14:17], v[38:41], v[70:73]
	v_mfma_f32_16x16x32_bf16 v[74:77], v[6:9], v[46:49], v[74:77]
	v_mfma_f32_16x16x32_bf16 v[78:81], v[14:17], v[46:49], v[78:81]
	v_mfma_f32_16x16x32_bf16 v[82:85], v[6:9], v[54:57], v[82:85]
	v_mfma_f32_16x16x32_bf16 v[86:89], v[14:17], v[54:57], v[86:89]
	v_mfma_f32_16x16x32_bf16 v[90:93], v[6:9], v[62:65], v[90:93]
	v_mfma_f32_16x16x32_bf16 v[94:97], v[14:17], v[62:65], v[94:97]
	v_mfma_f32_16x16x32_bf16 v[98:101], v[18:21], v[34:37], 0
	v_mfma_f32_16x16x32_bf16 v[34:37], v[26:29], v[34:37], 0
	v_mfma_f32_16x16x32_bf16 v[98:101], v[22:25], v[38:41], v[98:101]
	v_mfma_f32_16x16x32_bf16 v[34:37], v[30:33], v[38:41], v[34:37]
	v_mfma_f32_16x16x32_bf16 v[38:41], v[18:21], v[42:45], 0
	v_mfma_f32_16x16x32_bf16 v[42:45], v[26:29], v[42:45], 0
	v_mfma_f32_16x16x32_bf16 v[38:41], v[22:25], v[46:49], v[38:41]
	v_mfma_f32_16x16x32_bf16 v[42:45], v[30:33], v[46:49], v[42:45]
	v_mfma_f32_16x16x32_bf16 v[46:49], v[18:21], v[50:53], 0
	v_mfma_f32_16x16x32_bf16 v[50:53], v[26:29], v[50:53], 0
	v_mfma_f32_16x16x32_bf16 v[46:49], v[22:25], v[54:57], v[46:49]
	v_mfma_f32_16x16x32_bf16 v[50:53], v[30:33], v[54:57], v[50:53]
	v_mfma_f32_16x16x32_bf16 v[54:57], v[18:21], v[58:61], 0
	v_mfma_f32_16x16x32_bf16 v[58:61], v[26:29], v[58:61], 0
	v_mfma_f32_16x16x32_bf16 v[54:57], v[22:25], v[62:65], v[54:57]
	v_mfma_f32_16x16x32_bf16 v[58:61], v[30:33], v[62:65], v[58:61]
	s_barrier
	s_add_i32 s75, s72, s7
	v_lshl_add_u64 v[188:189], s[44:45], 0, v[148:149]
	s_add_i32 s31, s75, 0x2000
	v_lshl_add_u64 v[130:131], v[188:189], 0, s[26:27]
	s_mov_b32 m0, s75
	v_lshl_add_u64 v[218:219], s[44:45], 0, v[152:153]
	s_add_u32 s78, s44, 0x10100
	ds_read_b128 v[62:65], v192 offset:16384
	ds_read_b128 v[102:105], v192 offset:17408
	ds_read_b128 v[106:109], v192 offset:18432
	ds_read_b128 v[110:113], v192 offset:19456
	ds_read_b128 v[114:117], v192 offset:20480
	ds_read_b128 v[118:121], v192 offset:21504
	ds_read_b128 v[122:125], v192 offset:22528
	ds_read_b128 v[126:129], v192 offset:23552
	global_load_lds_dwordx4 v[130:131], off
	v_lshl_add_u64 v[130:131], v[218:219], 0, s[26:27]
	s_mov_b32 m0, s31
	s_addc_u32 s79, s45, 0
	s_add_i32 s35, s73, s7
	global_load_lds_dwordx4 v[130:131], off
	v_lshl_add_u64 v[130:131], s[78:79], 0, v[148:149]
	s_mov_b32 m0, s35
	s_add_i32 s74, s35, 0x2000
	global_load_lds_dwordx4 v[130:131], off
	v_lshl_add_u64 v[130:131], s[78:79], 0, v[152:153]
	s_mov_b32 m0, s74
	v_lshl_add_u64 v[220:221], s[40:41], 0, v[146:147]
	global_load_lds_dwordx4 v[130:131], off
	v_lshl_add_u64 v[130:131], v[220:221], 0, s[26:27]
	s_mov_b32 m0, s43
	v_lshl_add_u64 v[222:223], s[40:41], 0, v[150:151]
	global_load_lds_dwordx4 v[130:131], off
	v_lshl_add_u64 v[130:131], v[222:223], 0, s[26:27]
	s_mov_b32 m0, s50
	s_nop 0
	global_load_lds_dwordx4 v[130:131], off
	s_waitcnt vmcnt(8)
	s_waitcnt lgkmcnt(0)
	s_barrier
	v_mfma_f32_16x16x32_bf16 v[130:133], v[2:5], v[62:65], 0
	v_mfma_f32_16x16x32_bf16 v[138:141], v[2:5], v[106:109], 0
	v_mfma_f32_16x16x32_bf16 v[158:161], v[2:5], v[114:117], 0
	v_mfma_f32_16x16x32_bf16 v[2:5], v[2:5], v[122:125], 0
	v_mfma_f32_16x16x32_bf16 v[130:133], v[6:9], v[102:105], v[130:133]
	v_mfma_f32_16x16x32_bf16 v[134:137], v[10:13], v[62:65], 0
	v_mfma_f32_16x16x32_bf16 v[138:141], v[6:9], v[110:113], v[138:141]
	v_mfma_f32_16x16x32_bf16 v[142:145], v[10:13], v[106:109], 0
	v_mfma_f32_16x16x32_bf16 v[158:161], v[6:9], v[118:121], v[158:161]
	v_mfma_f32_16x16x32_bf16 v[2:5], v[6:9], v[126:129], v[2:5]
	v_mfma_f32_16x16x32_bf16 v[6:9], v[10:13], v[122:125], 0
	v_mfma_f32_16x16x32_bf16 v[134:137], v[14:17], v[102:105], v[134:137]
	v_mfma_f32_16x16x32_bf16 v[142:145], v[14:17], v[110:113], v[142:145]
	v_mfma_f32_16x16x32_bf16 v[162:165], v[10:13], v[114:117], 0
	v_mfma_f32_16x16x32_bf16 v[6:9], v[14:17], v[126:129], v[6:9]
	v_mfma_f32_16x16x32_bf16 v[162:165], v[14:17], v[118:121], v[162:165]
	v_mfma_f32_16x16x32_bf16 v[10:13], v[18:21], v[62:65], 0
	v_mfma_f32_16x16x32_bf16 v[14:17], v[26:29], v[62:65], 0
	v_mfma_f32_16x16x32_bf16 v[10:13], v[22:25], v[102:105], v[10:13]
	v_mfma_f32_16x16x32_bf16 v[14:17], v[30:33], v[102:105], v[14:17]
	v_mfma_f32_16x16x32_bf16 v[62:65], v[18:21], v[106:109], 0
	v_mfma_f32_16x16x32_bf16 v[102:105], v[26:29], v[106:109], 0
	v_mfma_f32_16x16x32_bf16 v[62:65], v[22:25], v[110:113], v[62:65]
	v_mfma_f32_16x16x32_bf16 v[102:105], v[30:33], v[110:113], v[102:105]
	v_mfma_f32_16x16x32_bf16 v[106:109], v[18:21], v[114:117], 0
	v_mfma_f32_16x16x32_bf16 v[110:113], v[26:29], v[114:117], 0
	v_mfma_f32_16x16x32_bf16 v[18:21], v[18:21], v[122:125], 0
	v_mfma_f32_16x16x32_bf16 v[106:109], v[22:25], v[118:121], v[106:109]
	v_mfma_f32_16x16x32_bf16 v[110:113], v[30:33], v[118:121], v[110:113]
	v_mfma_f32_16x16x32_bf16 v[18:21], v[22:25], v[126:129], v[18:21]
	v_mfma_f32_16x16x32_bf16 v[22:25], v[26:29], v[122:125], 0
	v_mfma_f32_16x16x32_bf16 v[22:25], v[30:33], v[126:129], v[22:25]
	s_barrier
	s_add_i32 s76, 0, 0x18000
	s_add_i32 s84, 0, 0x1c000
	v_add_u32_e32 v234, s76, v173
	v_add_u32_e32 v235, s84, v173
	ds_read_b128 v[26:29], v234
	ds_read_b128 v[30:33], v234 offset:1024
	ds_read_b128 v[114:117], v234 offset:2048
	ds_read_b128 v[118:121], v234 offset:3072
	ds_read_b128 v[122:125], v235
	ds_read_b128 v[126:129], v235 offset:1024
	ds_read_b128 v[166:169], v235 offset:2048
	ds_read_b128 v[176:179], v235 offset:3072
	s_add_u32 s78, s40, 0x40100
	s_addc_u32 s79, s41, 0
	s_mov_b32 m0, s51
	v_lshl_add_u64 v[224:225], s[78:79], 0, v[146:147]
	ds_read_b128 v[180:183], v192 offset:32768
	ds_read_b128 v[184:187], v192 offset:33792
	ds_read_b128 v[194:197], v192 offset:34816
	ds_read_b128 v[198:201], v192 offset:35840
	ds_read_b128 v[202:205], v192 offset:36864
	ds_read_b128 v[206:209], v192 offset:37888
	ds_read_b128 v[210:213], v192 offset:38912
	ds_read_b128 v[214:217], v192 offset:39936
	global_load_lds_dwordx4 v[224:225], off
	v_lshl_add_u64 v[224:225], s[78:79], 0, v[150:151]
	s_mov_b32 m0, s54
	s_nop 0
	global_load_lds_dwordx4 v[224:225], off
	s_waitcnt vmcnt(8)
	s_waitcnt lgkmcnt(0)
	s_barrier
	v_mfma_f32_16x16x32_bf16 v[66:69], v[26:29], v[180:183], v[66:69]
	v_mfma_f32_16x16x32_bf16 v[70:73], v[114:117], v[180:183], v[70:73]
	v_mfma_f32_16x16x32_bf16 v[74:77], v[26:29], v[194:197], v[74:77]
	v_mfma_f32_16x16x32_bf16 v[78:81], v[114:117], v[194:197], v[78:81]
	v_mfma_f32_16x16x32_bf16 v[82:85], v[26:29], v[202:205], v[82:85]
	v_mfma_f32_16x16x32_bf16 v[86:89], v[114:117], v[202:205], v[86:89]
	v_mfma_f32_16x16x32_bf16 v[90:93], v[26:29], v[210:213], v[90:93]
	v_mfma_f32_16x16x32_bf16 v[94:97], v[114:117], v[210:213], v[94:97]
	v_mfma_f32_16x16x32_bf16 v[66:69], v[30:33], v[184:187], v[66:69]
	v_mfma_f32_16x16x32_bf16 v[70:73], v[118:121], v[184:187], v[70:73]
	v_mfma_f32_16x16x32_bf16 v[74:77], v[30:33], v[198:201], v[74:77]
	v_mfma_f32_16x16x32_bf16 v[78:81], v[118:121], v[198:201], v[78:81]
	v_mfma_f32_16x16x32_bf16 v[82:85], v[30:33], v[206:209], v[82:85]
	v_mfma_f32_16x16x32_bf16 v[86:89], v[118:121], v[206:209], v[86:89]
	v_mfma_f32_16x16x32_bf16 v[90:93], v[30:33], v[214:217], v[90:93]
	v_mfma_f32_16x16x32_bf16 v[94:97], v[118:121], v[214:217], v[94:97]
	v_mfma_f32_16x16x32_bf16 v[98:101], v[122:125], v[180:183], v[98:101]
	v_mfma_f32_16x16x32_bf16 v[34:37], v[166:169], v[180:183], v[34:37]
	v_mfma_f32_16x16x32_bf16 v[38:41], v[122:125], v[194:197], v[38:41]
	v_mfma_f32_16x16x32_bf16 v[42:45], v[166:169], v[194:197], v[42:45]
	v_mfma_f32_16x16x32_bf16 v[46:49], v[122:125], v[202:205], v[46:49]
	v_mfma_f32_16x16x32_bf16 v[50:53], v[166:169], v[202:205], v[50:53]
	v_mfma_f32_16x16x32_bf16 v[54:57], v[122:125], v[210:213], v[54:57]
	v_mfma_f32_16x16x32_bf16 v[58:61], v[166:169], v[210:213], v[58:61]
	v_mfma_f32_16x16x32_bf16 v[98:101], v[126:129], v[184:187], v[98:101]
	v_mfma_f32_16x16x32_bf16 v[34:37], v[176:179], v[184:187], v[34:37]
	v_mfma_f32_16x16x32_bf16 v[38:41], v[126:129], v[198:201], v[38:41]
	v_mfma_f32_16x16x32_bf16 v[42:45], v[176:179], v[198:201], v[42:45]
	v_mfma_f32_16x16x32_bf16 v[46:49], v[126:129], v[206:209], v[46:49]
	v_mfma_f32_16x16x32_bf16 v[50:53], v[176:179], v[206:209], v[50:53]
	v_mfma_f32_16x16x32_bf16 v[54:57], v[126:129], v[214:217], v[54:57]
	v_mfma_f32_16x16x32_bf16 v[58:61], v[176:179], v[214:217], v[58:61]
	s_barrier
	s_add_i32 s78, s76, s7
	s_add_i32 s76, s78, 0x2000
	v_lshl_add_u64 v[188:189], v[188:189], 0, s[28:29]
	s_mov_b32 m0, s78
	s_add_u32 s80, s44, 0x10180
	ds_read_b128 v[180:183], v192 offset:49152
	ds_read_b128 v[184:187], v192 offset:50176
	ds_read_b128 v[194:197], v192 offset:51200
	ds_read_b128 v[198:201], v192 offset:52224
	ds_read_b128 v[202:205], v192 offset:53248
	ds_read_b128 v[206:209], v192 offset:54272
	ds_read_b128 v[210:213], v192 offset:55296
	ds_read_b128 v[214:217], v192 offset:56320
	global_load_lds_dwordx4 v[188:189], off
	v_lshl_add_u64 v[188:189], v[218:219], 0, s[28:29]
	s_mov_b32 m0, s76
	s_addc_u32 s81, s45, 0
	s_add_i32 s44, s84, s7
	global_load_lds_dwordx4 v[188:189], off
	v_lshl_add_u64 v[188:189], s[80:81], 0, v[148:149]
	s_mov_b32 m0, s44
	s_add_i32 s45, s44, 0x2000
	global_load_lds_dwordx4 v[188:189], off
	v_lshl_add_u64 v[188:189], s[80:81], 0, v[152:153]
	s_mov_b32 m0, s45
	s_nop 0
	global_load_lds_dwordx4 v[188:189], off
	v_lshl_add_u64 v[188:189], v[220:221], 0, s[28:29]
	s_mov_b32 m0, s65
	s_nop 0
	global_load_lds_dwordx4 v[188:189], off
	v_lshl_add_u64 v[188:189], v[222:223], 0, s[28:29]
	s_mov_b32 m0, s70
	s_nop 0
	global_load_lds_dwordx4 v[188:189], off
	s_waitcnt vmcnt(8)
	s_waitcnt lgkmcnt(0)
	s_barrier
	v_mfma_f32_16x16x32_bf16 v[130:133], v[26:29], v[180:183], v[130:133]
	v_mfma_f32_16x16x32_bf16 v[134:137], v[114:117], v[180:183], v[134:137]
	v_mfma_f32_16x16x32_bf16 v[138:141], v[26:29], v[194:197], v[138:141]
	v_mfma_f32_16x16x32_bf16 v[142:145], v[114:117], v[194:197], v[142:145]
	v_mfma_f32_16x16x32_bf16 v[2:5], v[26:29], v[210:213], v[2:5]
	v_mfma_f32_16x16x32_bf16 v[6:9], v[114:117], v[210:213], v[6:9]
	v_mfma_f32_16x16x32_bf16 v[130:133], v[30:33], v[184:187], v[130:133]
	v_mfma_f32_16x16x32_bf16 v[134:137], v[118:121], v[184:187], v[134:137]
	v_mfma_f32_16x16x32_bf16 v[138:141], v[30:33], v[198:201], v[138:141]
	v_mfma_f32_16x16x32_bf16 v[142:145], v[118:121], v[198:201], v[142:145]
	v_mfma_f32_16x16x32_bf16 v[158:161], v[26:29], v[202:205], v[158:161]
	v_mfma_f32_16x16x32_bf16 v[162:165], v[114:117], v[202:205], v[162:165]
	v_mfma_f32_16x16x32_bf16 v[2:5], v[30:33], v[214:217], v[2:5]
	v_mfma_f32_16x16x32_bf16 v[6:9], v[118:121], v[214:217], v[6:9]
	v_mfma_f32_16x16x32_bf16 v[158:161], v[30:33], v[206:209], v[158:161]
	v_mfma_f32_16x16x32_bf16 v[162:165], v[118:121], v[206:209], v[162:165]
	v_mfma_f32_16x16x32_bf16 v[10:13], v[122:125], v[180:183], v[10:13]
	v_mfma_f32_16x16x32_bf16 v[14:17], v[166:169], v[180:183], v[14:17]
	v_mfma_f32_16x16x32_bf16 v[26:29], v[122:125], v[194:197], v[62:65]
	v_mfma_f32_16x16x32_bf16 v[30:33], v[166:169], v[194:197], v[102:105]
	v_mfma_f32_16x16x32_bf16 v[62:65], v[122:125], v[202:205], v[106:109]
	v_mfma_f32_16x16x32_bf16 v[102:105], v[166:169], v[202:205], v[110:113]
	v_mfma_f32_16x16x32_bf16 v[10:13], v[126:129], v[184:187], v[10:13]
	v_mfma_f32_16x16x32_bf16 v[14:17], v[176:179], v[184:187], v[14:17]
	v_mfma_f32_16x16x32_bf16 v[62:65], v[126:129], v[206:209], v[62:65]
	v_mfma_f32_16x16x32_bf16 v[102:105], v[176:179], v[206:209], v[102:105]
	v_mfma_f32_16x16x32_bf16 v[18:21], v[122:125], v[210:213], v[18:21]
	v_mfma_f32_16x16x32_bf16 v[22:25], v[166:169], v[210:213], v[22:25]
	v_mfma_f32_16x16x32_bf16 v[26:29], v[126:129], v[198:201], v[26:29]
	v_mfma_f32_16x16x32_bf16 v[30:33], v[176:179], v[198:201], v[30:33]
	v_mfma_f32_16x16x32_bf16 v[18:21], v[126:129], v[214:217], v[18:21]
	v_mfma_f32_16x16x32_bf16 v[22:25], v[176:179], v[214:217], v[22:25]
	s_barrier
	ds_read_b128 v[106:109], v190
	ds_read_b128 v[110:113], v190 offset:1024
	ds_read_b128 v[114:117], v190 offset:2048
	ds_read_b128 v[118:121], v190 offset:3072
	ds_read_b128 v[122:125], v191
	ds_read_b128 v[126:129], v191 offset:1024
	ds_read_b128 v[166:169], v191 offset:2048
	ds_read_b128 v[176:179], v191 offset:3072
	s_add_u32 s40, s40, 0x40180
	s_addc_u32 s41, s41, 0
	s_mov_b32 m0, s77
	v_lshl_add_u64 v[188:189], s[40:41], 0, v[146:147]
	ds_read_b128 v[180:183], v192
	ds_read_b128 v[184:187], v192 offset:1024
	ds_read_b128 v[194:197], v192 offset:2048
	ds_read_b128 v[198:201], v192 offset:3072
	ds_read_b128 v[202:205], v192 offset:4096
	ds_read_b128 v[206:209], v192 offset:5120
	ds_read_b128 v[210:213], v192 offset:6144
	ds_read_b128 v[214:217], v192 offset:7168
	global_load_lds_dwordx4 v[188:189], off
	v_lshl_add_u64 v[188:189], s[40:41], 0, v[150:151]
	s_mov_b32 m0, s9
	s_nop 0
	global_load_lds_dwordx4 v[188:189], off
	s_waitcnt vmcnt(8)
	s_waitcnt lgkmcnt(0)
	s_barrier
	v_mfma_f32_16x16x32_bf16 v[66:69], v[106:109], v[180:183], v[66:69]
	v_mfma_f32_16x16x32_bf16 v[70:73], v[114:117], v[180:183], v[70:73]
	v_mfma_f32_16x16x32_bf16 v[74:77], v[106:109], v[194:197], v[74:77]
	v_mfma_f32_16x16x32_bf16 v[78:81], v[114:117], v[194:197], v[78:81]
	v_mfma_f32_16x16x32_bf16 v[82:85], v[106:109], v[202:205], v[82:85]
	v_mfma_f32_16x16x32_bf16 v[86:89], v[114:117], v[202:205], v[86:89]
	v_mfma_f32_16x16x32_bf16 v[90:93], v[106:109], v[210:213], v[90:93]
	v_mfma_f32_16x16x32_bf16 v[94:97], v[114:117], v[210:213], v[94:97]
	v_mfma_f32_16x16x32_bf16 v[66:69], v[110:113], v[184:187], v[66:69]
	v_mfma_f32_16x16x32_bf16 v[70:73], v[118:121], v[184:187], v[70:73]
	v_mfma_f32_16x16x32_bf16 v[74:77], v[110:113], v[198:201], v[74:77]
	v_mfma_f32_16x16x32_bf16 v[78:81], v[118:121], v[198:201], v[78:81]
	v_mfma_f32_16x16x32_bf16 v[82:85], v[110:113], v[206:209], v[82:85]
	v_mfma_f32_16x16x32_bf16 v[86:89], v[118:121], v[206:209], v[86:89]
	v_mfma_f32_16x16x32_bf16 v[90:93], v[110:113], v[214:217], v[90:93]
	v_mfma_f32_16x16x32_bf16 v[94:97], v[118:121], v[214:217], v[94:97]
	v_mfma_f32_16x16x32_bf16 v[34:37], v[166:169], v[180:183], v[34:37]
	v_mfma_f32_16x16x32_bf16 v[38:41], v[122:125], v[194:197], v[38:41]
	v_mfma_f32_16x16x32_bf16 v[42:45], v[166:169], v[194:197], v[42:45]
	v_mfma_f32_16x16x32_bf16 v[46:49], v[122:125], v[202:205], v[46:49]
	v_mfma_f32_16x16x32_bf16 v[50:53], v[166:169], v[202:205], v[50:53]
	v_mfma_f32_16x16x32_bf16 v[54:57], v[122:125], v[210:213], v[54:57]
	v_mfma_f32_16x16x32_bf16 v[58:61], v[166:169], v[210:213], v[58:61]
	v_mfma_f32_16x16x32_bf16 v[98:101], v[122:125], v[180:183], v[98:101]
	v_mfma_f32_16x16x32_bf16 v[34:37], v[176:179], v[184:187], v[34:37]
	v_mfma_f32_16x16x32_bf16 v[38:41], v[126:129], v[198:201], v[38:41]
	v_mfma_f32_16x16x32_bf16 v[42:45], v[176:179], v[198:201], v[42:45]
	v_mfma_f32_16x16x32_bf16 v[46:49], v[126:129], v[206:209], v[46:49]
	v_mfma_f32_16x16x32_bf16 v[50:53], v[176:179], v[206:209], v[50:53]
	v_mfma_f32_16x16x32_bf16 v[54:57], v[126:129], v[214:217], v[54:57]
	v_mfma_f32_16x16x32_bf16 v[58:61], v[176:179], v[214:217], v[58:61]
	v_mfma_f32_16x16x32_bf16 v[218:221], v[126:129], v[184:187], v[98:101]
	s_barrier
	s_mov_b32 m0, s75
	v_lshl_add_u64 v[188:189], s[46:47], 0, v[148:149]
	s_add_u32 s40, s46, 0x10000
	ds_read_b128 v[98:101], v192 offset:16384
	ds_read_b128 v[180:183], v192 offset:17408
	ds_read_b128 v[184:187], v192 offset:18432
	ds_read_b128 v[194:197], v192 offset:19456
	ds_read_b128 v[198:201], v192 offset:20480
	ds_read_b128 v[202:205], v192 offset:21504
	ds_read_b128 v[206:209], v192 offset:22528
	ds_read_b128 v[210:213], v192 offset:23552
	s_cmp_lg_u32 s33, 0x100
	s_cselect_b64 exec, -1, 0
	global_load_lds_dwordx4 v[188:189], off
	v_lshl_add_u64 v[154:155], s[46:47], 0, v[152:153]
	s_mov_b32 m0, s31
	s_addc_u32 s41, s47, 0
	global_load_lds_dwordx4 v[154:155], off
	v_lshl_add_u64 v[214:215], s[40:41], 0, v[148:149]
	s_mov_b32 m0, s35
	v_lshl_add_u64 v[0:1], s[48:49], 0, v[146:147]
	global_load_lds_dwordx4 v[214:215], off
	v_lshl_add_u64 v[214:215], s[40:41], 0, v[152:153]
	s_mov_b32 m0, s74
	v_lshl_add_u64 v[156:157], s[48:49], 0, v[150:151]
	global_load_lds_dwordx4 v[214:215], off
	s_mov_b32 m0, s43
	s_nop 0
	global_load_lds_dwordx4 v[0:1], off
	s_mov_b32 m0, s50
	s_nop 0
	global_load_lds_dwordx4 v[156:157], off
	s_mov_b64 exec, -1
	s_waitcnt vmcnt(8)
	s_waitcnt lgkmcnt(0)
	s_barrier
	v_mfma_f32_16x16x32_bf16 v[130:133], v[106:109], v[98:101], v[130:133]
	v_mfma_f32_16x16x32_bf16 v[214:217], v[110:113], v[180:183], v[130:133]
	v_mfma_f32_16x16x32_bf16 v[130:133], v[114:117], v[98:101], v[134:137]
	v_mfma_f32_16x16x32_bf16 v[222:225], v[118:121], v[180:183], v[130:133]
	v_mfma_f32_16x16x32_bf16 v[130:133], v[106:109], v[184:187], v[138:141]
	v_mfma_f32_16x16x32_bf16 v[226:229], v[110:113], v[194:197], v[130:133]
	v_mfma_f32_16x16x32_bf16 v[130:133], v[114:117], v[184:187], v[142:145]
	v_mfma_f32_16x16x32_bf16 v[230:233], v[118:121], v[194:197], v[130:133]
	v_mfma_f32_16x16x32_bf16 v[130:133], v[106:109], v[198:201], v[158:161]
	v_mfma_f32_16x16x32_bf16 v[2:5], v[106:109], v[206:209], v[2:5]
	v_mfma_f32_16x16x32_bf16 v[6:9], v[114:117], v[206:209], v[6:9]
	v_mfma_f32_16x16x32_bf16 v[158:161], v[110:113], v[202:205], v[130:133]
	v_mfma_f32_16x16x32_bf16 v[130:133], v[114:117], v[198:201], v[162:165]
	v_mfma_f32_16x16x32_bf16 v[2:5], v[110:113], v[210:213], v[2:5]
	v_mfma_f32_16x16x32_bf16 v[6:9], v[118:121], v[210:213], v[6:9]
	v_mfma_f32_16x16x32_bf16 v[162:165], v[118:121], v[202:205], v[130:133]
	v_mfma_f32_16x16x32_bf16 v[10:13], v[122:125], v[98:101], v[10:13]
	v_mfma_f32_16x16x32_bf16 v[14:17], v[166:169], v[98:101], v[14:17]
	v_mfma_f32_16x16x32_bf16 v[62:65], v[122:125], v[198:201], v[62:65]
	v_mfma_f32_16x16x32_bf16 v[10:13], v[126:129], v[180:183], v[10:13]
	v_mfma_f32_16x16x32_bf16 v[14:17], v[176:179], v[180:183], v[14:17]
	v_mfma_f32_16x16x32_bf16 v[26:29], v[122:125], v[184:187], v[26:29]
	v_mfma_f32_16x16x32_bf16 v[30:33], v[166:169], v[184:187], v[30:33]
	v_mfma_f32_16x16x32_bf16 v[180:183], v[126:129], v[202:205], v[62:65]
	v_mfma_f32_16x16x32_bf16 v[62:65], v[166:169], v[198:201], v[102:105]
	v_mfma_f32_16x16x32_bf16 v[18:21], v[122:125], v[206:209], v[18:21]
	v_mfma_f32_16x16x32_bf16 v[22:25], v[166:169], v[206:209], v[22:25]
	v_mfma_f32_16x16x32_bf16 v[26:29], v[126:129], v[194:197], v[26:29]
	v_mfma_f32_16x16x32_bf16 v[30:33], v[176:179], v[194:197], v[30:33]
	v_mfma_f32_16x16x32_bf16 v[184:187], v[176:179], v[202:205], v[62:65]
	v_mfma_f32_16x16x32_bf16 v[18:21], v[126:129], v[210:213], v[18:21]
	v_mfma_f32_16x16x32_bf16 v[22:25], v[176:179], v[210:213], v[22:25]
	s_barrier
	ds_read_b128 v[62:65], v234
	ds_read_b128 v[166:169], v234 offset:1024
	ds_read_b128 v[176:179], v234 offset:2048
	ds_read_b128 v[194:197], v234 offset:3072
	ds_read_b128 v[198:201], v235
	ds_read_b128 v[202:205], v235 offset:1024
	ds_read_b128 v[206:209], v235 offset:2048
	ds_read_b128 v[210:213], v235 offset:3072
	s_add_u32 s40, s48, 0x40000
	s_addc_u32 s41, s49, 0
	s_mov_b32 m0, s51
	v_lshl_add_u64 v[98:99], s[40:41], 0, v[146:147]
	ds_read_b128 v[106:109], v192 offset:32768
	ds_read_b128 v[110:113], v192 offset:33792
	ds_read_b128 v[126:129], v192 offset:34816
	ds_read_b128 v[234:237], v192 offset:35840
	ds_read_b128 v[238:241], v192 offset:36864
	ds_read_b128 v[242:245], v192 offset:37888
	ds_read_b128 v[246:249], v192 offset:38912
	ds_read_b128 v[250:253], v192 offset:39936
	s_cmp_lg_u32 s33, 0x100
	s_cselect_b64 exec, -1, 0
	global_load_lds_dwordx4 v[98:99], off
	v_lshl_add_u64 v[98:99], s[40:41], 0, v[150:151]
	s_mov_b32 m0, s54
	s_nop 0
	global_load_lds_dwordx4 v[98:99], off
	s_mov_b64 exec, -1
	s_waitcnt vmcnt(8)
	s_waitcnt lgkmcnt(0)
	s_barrier
	v_mfma_f32_16x16x32_bf16 v[66:69], v[62:65], v[106:109], v[66:69]
	v_mfma_f32_16x16x32_bf16 v[130:133], v[166:169], v[110:113], v[66:69]
	v_mfma_f32_16x16x32_bf16 v[66:69], v[176:179], v[106:109], v[70:73]
	v_mfma_f32_16x16x32_bf16 v[134:137], v[194:197], v[110:113], v[66:69]
	v_mfma_f32_16x16x32_bf16 v[66:69], v[62:65], v[126:129], v[74:77]
	v_mfma_f32_16x16x32_bf16 v[114:117], v[166:169], v[234:237], v[66:69]
	v_mfma_f32_16x16x32_bf16 v[66:69], v[176:179], v[126:129], v[78:81]
	v_mfma_f32_16x16x32_bf16 v[118:121], v[194:197], v[234:237], v[66:69]
	v_mfma_f32_16x16x32_bf16 v[66:69], v[62:65], v[238:241], v[82:85]
	v_mfma_f32_16x16x32_bf16 v[98:101], v[166:169], v[242:245], v[66:69]
	v_mfma_f32_16x16x32_bf16 v[66:69], v[176:179], v[238:241], v[86:89]
	v_mfma_f32_16x16x32_bf16 v[102:105], v[194:197], v[242:245], v[66:69]
	v_mfma_f32_16x16x32_bf16 v[66:69], v[62:65], v[246:249], v[90:93]
	v_mfma_f32_16x16x32_bf16 v[82:85], v[166:169], v[250:253], v[66:69]
	v_mfma_f32_16x16x32_bf16 v[66:69], v[176:179], v[246:249], v[94:97]
	v_mfma_f32_16x16x32_bf16 v[86:89], v[194:197], v[250:253], v[66:69]
	v_mfma_f32_16x16x32_bf16 v[34:37], v[206:209], v[106:109], v[34:37]
	v_mfma_f32_16x16x32_bf16 v[142:145], v[210:213], v[110:113], v[34:37]
	v_mfma_f32_16x16x32_bf16 v[34:37], v[198:201], v[126:129], v[38:41]
	v_mfma_f32_16x16x32_bf16 v[122:125], v[202:205], v[234:237], v[34:37]
	v_mfma_f32_16x16x32_bf16 v[34:37], v[206:209], v[126:129], v[42:45]
	v_mfma_f32_16x16x32_bf16 v[126:129], v[210:213], v[234:237], v[34:37]
	v_mfma_f32_16x16x32_bf16 v[34:37], v[198:201], v[238:241], v[46:49]
	v_mfma_f32_16x16x32_bf16 v[66:69], v[198:201], v[106:109], v[218:221]
	v_mfma_f32_16x16x32_bf16 v[106:109], v[202:205], v[242:245], v[34:37]
	v_mfma_f32_16x16x32_bf16 v[34:37], v[206:209], v[238:241], v[50:53]
	v_mfma_f32_16x16x32_bf16 v[138:141], v[202:205], v[110:113], v[66:69]
	v_mfma_f32_16x16x32_bf16 v[110:113], v[210:213], v[242:245], v[34:37]
	v_mfma_f32_16x16x32_bf16 v[34:37], v[198:201], v[246:249], v[54:57]
	v_mfma_f32_16x16x32_bf16 v[90:93], v[202:205], v[250:253], v[34:37]
	v_mfma_f32_16x16x32_bf16 v[34:37], v[206:209], v[246:249], v[58:61]
	v_mfma_f32_16x16x32_bf16 v[94:97], v[210:213], v[250:253], v[34:37]
	s_barrier
	s_mov_b32 m0, s78
	s_nop 3
	v_lshl_add_u64 v[34:35], v[188:189], 0, s[18:19]
	s_add_u32 s40, s46, 0x10080
	ds_read_b128 v[42:45], v192 offset:49152
	ds_read_b128 v[46:49], v192 offset:50176
	ds_read_b128 v[218:221], v192 offset:51200
	ds_read_b128 v[234:237], v192 offset:52224
	ds_read_b128 v[238:241], v192 offset:53248
	ds_read_b128 v[242:245], v192 offset:54272
	ds_read_b128 v[246:249], v192 offset:55296
	ds_read_b128 v[250:253], v192 offset:56320
	s_cmp_lg_u32 s33, 0x100
	s_cselect_b64 exec, -1, 0
	global_load_lds_dwordx4 v[34:35], off
	v_lshl_add_u64 v[34:35], v[154:155], 0, s[18:19]
	s_mov_b32 m0, s76
	s_addc_u32 s41, s47, 0
	global_load_lds_dwordx4 v[34:35], off
	v_lshl_add_u64 v[34:35], s[40:41], 0, v[148:149]
	s_mov_b32 m0, s44
	v_lshl_add_u64 v[0:1], v[0:1], 0, s[18:19]
	global_load_lds_dwordx4 v[34:35], off
	v_lshl_add_u64 v[34:35], s[40:41], 0, v[152:153]
	s_mov_b32 m0, s45
	s_nop 0
	global_load_lds_dwordx4 v[34:35], off
	s_mov_b32 m0, s65
	s_nop 0
	global_load_lds_dwordx4 v[0:1], off
	v_lshl_add_u64 v[0:1], v[156:157], 0, s[18:19]
	s_mov_b32 m0, s70
	s_nop 0
	global_load_lds_dwordx4 v[0:1], off
	s_mov_b64 exec, -1
	s_waitcnt vmcnt(8)
	s_waitcnt lgkmcnt(0)
	s_barrier
	v_mfma_f32_16x16x32_bf16 v[34:37], v[62:65], v[42:45], v[214:217]
	v_mfma_f32_16x16x32_bf16 v[66:69], v[166:169], v[46:49], v[34:37]
	v_mfma_f32_16x16x32_bf16 v[34:37], v[176:179], v[42:45], v[222:225]
	v_mfma_f32_16x16x32_bf16 v[70:73], v[194:197], v[46:49], v[34:37]
	v_mfma_f32_16x16x32_bf16 v[34:37], v[62:65], v[218:221], v[226:229]
	v_mfma_f32_16x16x32_bf16 v[50:53], v[166:169], v[234:237], v[34:37]
	v_mfma_f32_16x16x32_bf16 v[34:37], v[176:179], v[218:221], v[230:233]
	v_mfma_f32_16x16x32_bf16 v[54:57], v[194:197], v[234:237], v[34:37]
	v_mfma_f32_16x16x32_bf16 v[34:37], v[62:65], v[238:241], v[158:161]
	v_mfma_f32_16x16x32_bf16 v[38:41], v[176:179], v[238:241], v[162:165]
	v_mfma_f32_16x16x32_bf16 v[2:5], v[62:65], v[246:249], v[2:5]
	v_mfma_f32_16x16x32_bf16 v[6:9], v[176:179], v[246:249], v[6:9]
	v_mfma_f32_16x16x32_bf16 v[34:37], v[166:169], v[242:245], v[34:37]
	v_mfma_f32_16x16x32_bf16 v[38:41], v[194:197], v[242:245], v[38:41]
	v_mfma_f32_16x16x32_bf16 v[2:5], v[166:169], v[250:253], v[2:5]
	v_mfma_f32_16x16x32_bf16 v[6:9], v[194:197], v[250:253], v[6:9]
	v_mfma_f32_16x16x32_bf16 v[10:13], v[198:201], v[42:45], v[10:13]
	v_mfma_f32_16x16x32_bf16 v[74:77], v[202:205], v[46:49], v[10:13]
	v_mfma_f32_16x16x32_bf16 v[10:13], v[206:209], v[42:45], v[14:17]
	v_mfma_f32_16x16x32_bf16 v[78:81], v[210:213], v[46:49], v[10:13]
	v_mfma_f32_16x16x32_bf16 v[10:13], v[198:201], v[218:221], v[26:29]
	v_mfma_f32_16x16x32_bf16 v[58:61], v[202:205], v[234:237], v[10:13]
	v_mfma_f32_16x16x32_bf16 v[10:13], v[206:209], v[218:221], v[30:33]
	v_mfma_f32_16x16x32_bf16 v[62:65], v[210:213], v[234:237], v[10:13]
	v_mfma_f32_16x16x32_bf16 v[10:13], v[198:201], v[238:241], v[180:183]
	v_mfma_f32_16x16x32_bf16 v[42:45], v[202:205], v[242:245], v[10:13]
	v_mfma_f32_16x16x32_bf16 v[10:13], v[206:209], v[238:241], v[184:187]
	v_mfma_f32_16x16x32_bf16 v[46:49], v[210:213], v[242:245], v[10:13]
	v_mfma_f32_16x16x32_bf16 v[10:13], v[198:201], v[246:249], v[18:21]
	v_mfma_f32_16x16x32_bf16 v[14:17], v[206:209], v[246:249], v[22:25]
	v_mfma_f32_16x16x32_bf16 v[10:13], v[202:205], v[250:253], v[10:13]
	v_mfma_f32_16x16x32_bf16 v[14:17], v[210:213], v[250:253], v[14:17]
	s_barrier
	s_andn2_b64 vcc, exec, s[20:21]
	s_cbranch_vccnz .LBB0_1205
	s_barrier

.LBB0_1316:
	s_ashr_i32 s45, s44, 31
	s_lshl_b64 s[46:47], s[44:45], 19
	s_add_u32 s46, s68, s46
	s_addc_u32 s47, s69, s47
	s_and_b64 s[48:49], s[4:5], exec
	s_cselect_b32 s45, s47, s9
	s_cselect_b32 s51, s46, s8
	s_ashr_i32 s43, s42, 31
	s_lshl_b64 s[48:49], s[42:43], 19
	s_add_u32 s48, s7, s48
	s_addc_u32 s49, s56, s49
	s_and_b64 s[54:55], s[4:5], exec
	s_cselect_b32 s43, s49, s53
	s_cselect_b32 s90, s48, s52
	s_add_u32 s8, s8, 0x40080
	s_addc_u32 s9, s9, 0
	s_add_u32 s91, s52, 0x100
	s_addc_u32 s92, s53, 0
	s_mov_b32 s93, -2
	ds_read_b128 v[30:33], v219
	ds_read_b128 v[54:57], v219 offset:1024
	ds_read_b128 v[118:121], v219 offset:2048
	ds_read_b128 v[122:125], v219 offset:3072
	ds_read_b128 v[146:149], v220
	ds_read_b128 v[150:153], v220 offset:1024
	ds_read_b128 v[154:157], v220 offset:2048
	ds_read_b128 v[158:161], v220 offset:3072
	s_add_u32 s52, s8, 0xfffc0080
	s_addc_u32 s53, s9, -1
	s_cmp_eq_u32 s93, 12
	s_cselect_b32 s55, s45, s53
	s_cselect_b32 s54, s51, s52
	s_cselect_b32 s53, s43, s92
	s_cselect_b32 s52, s90, s91
	s_add_i32 m0, s59, 0xc000
	ds_read_b128 v[162:165], v221
	ds_read_b128 v[166:169], v221 offset:1024
	ds_read_b128 v[196:199], v221 offset:2048
	ds_read_b128 v[200:203], v221 offset:3072
	ds_read_b128 v[204:207], v221 offset:4096
	ds_read_b128 v[208:211], v221 offset:5120
	ds_read_b128 v[224:227], v221 offset:6144
	ds_read_b128 v[228:231], v221 offset:7168
	global_load_lds_dwordx4 v188, s[8:9]
	s_add_i32 m0, s59, 0xe000
	s_nop 0
	global_load_lds_dwordx4 v190, s[8:9]
	s_waitcnt vmcnt(8)
	s_waitcnt lgkmcnt(0)
	s_barrier
	v_mfma_f32_16x16x32_bf16 v[62:65], v[30:33], v[162:165], 0
	v_mfma_f32_16x16x32_bf16 v[42:45], v[118:121], v[162:165], 0
	v_mfma_f32_16x16x32_bf16 v[50:53], v[30:33], v[196:199], 0
	v_mfma_f32_16x16x32_bf16 v[38:41], v[118:121], v[196:199], 0
	v_mfma_f32_16x16x32_bf16 v[46:49], v[30:33], v[204:207], 0
	v_mfma_f32_16x16x32_bf16 v[34:37], v[118:121], v[204:207], 0
	v_mfma_f32_16x16x32_bf16 v[142:145], v[30:33], v[224:227], 0
	v_mfma_f32_16x16x32_bf16 v[82:85], v[118:121], v[224:227], 0
	v_mfma_f32_16x16x32_bf16 v[62:65], v[54:57], v[166:169], v[62:65]
	v_mfma_f32_16x16x32_bf16 v[42:45], v[122:125], v[166:169], v[42:45]
	v_mfma_f32_16x16x32_bf16 v[50:53], v[54:57], v[200:203], v[50:53]
	v_mfma_f32_16x16x32_bf16 v[38:41], v[122:125], v[200:203], v[38:41]
	v_mfma_f32_16x16x32_bf16 v[46:49], v[54:57], v[208:211], v[46:49]
	v_mfma_f32_16x16x32_bf16 v[34:37], v[122:125], v[208:211], v[34:37]
	v_mfma_f32_16x16x32_bf16 v[142:145], v[54:57], v[228:231], v[142:145]
	v_mfma_f32_16x16x32_bf16 v[82:85], v[122:125], v[228:231], v[82:85]
	v_mfma_f32_16x16x32_bf16 v[134:137], v[146:149], v[162:165], 0
	v_mfma_f32_16x16x32_bf16 v[74:77], v[154:157], v[162:165], 0
	v_mfma_f32_16x16x32_bf16 v[130:133], v[146:149], v[196:199], 0
	v_mfma_f32_16x16x32_bf16 v[70:73], v[154:157], v[196:199], 0
	v_mfma_f32_16x16x32_bf16 v[78:81], v[146:149], v[204:207], 0
	v_mfma_f32_16x16x32_bf16 v[66:69], v[154:157], v[204:207], 0
	v_mfma_f32_16x16x32_bf16 v[138:141], v[146:149], v[224:227], 0
	v_mfma_f32_16x16x32_bf16 v[98:101], v[154:157], v[224:227], 0
	v_mfma_f32_16x16x32_bf16 v[134:137], v[150:153], v[166:169], v[134:137]
	v_mfma_f32_16x16x32_bf16 v[74:77], v[158:161], v[166:169], v[74:77]
	v_mfma_f32_16x16x32_bf16 v[130:133], v[150:153], v[200:203], v[130:133]
	v_mfma_f32_16x16x32_bf16 v[70:73], v[158:161], v[200:203], v[70:73]
	v_mfma_f32_16x16x32_bf16 v[78:81], v[150:153], v[208:211], v[78:81]
	v_mfma_f32_16x16x32_bf16 v[66:69], v[158:161], v[208:211], v[66:69]
	v_mfma_f32_16x16x32_bf16 v[138:141], v[150:153], v[228:231], v[138:141]
	v_mfma_f32_16x16x32_bf16 v[98:101], v[158:161], v[228:231], v[98:101]
	s_barrier
	s_add_u32 s98, s52, 0x80
	s_addc_u32 s99, s53, 0
	s_add_u32 s100, s54, 0x80
	s_addc_u32 s101, s55, 0
	s_add_i32 s84, s75, s57
	s_mov_b32 m0, s84
	ds_read_b128 v[162:165], v221 offset:16384
	ds_read_b128 v[166:169], v221 offset:17408
	ds_read_b128 v[196:199], v221 offset:18432
	ds_read_b128 v[200:203], v221 offset:19456
	ds_read_b128 v[204:207], v221 offset:20480
	ds_read_b128 v[208:211], v221 offset:21504
	ds_read_b128 v[224:227], v221 offset:22528
	ds_read_b128 v[228:231], v221 offset:23552
	global_load_lds_dwordx4 v178, s[52:53]
	s_add_i32 m0, s84, 0x2000
	s_add_u32 s84, s52, 0x40000
	s_addc_u32 s85, s53, 0
	s_add_i32 s86, s76, s57
	global_load_lds_dwordx4 v182, s[52:53]
	s_mov_b32 m0, s86
	s_nop 0
	global_load_lds_dwordx4 v178, s[84:85]
	s_add_i32 m0, s86, 0x2000
	s_nop 0
	global_load_lds_dwordx4 v182, s[84:85]
	s_mov_b32 m0, s59
	s_nop 0
	global_load_lds_dwordx4 v176, s[54:55]
	s_mov_b32 m0, s62
	s_nop 0
	global_load_lds_dwordx4 v180, s[54:55]
	s_waitcnt vmcnt(8)
	s_waitcnt lgkmcnt(0)
	s_barrier
	v_mfma_f32_16x16x32_bf16 v[94:97], v[30:33], v[162:165], 0
	v_mfma_f32_16x16x32_bf16 v[10:13], v[118:121], v[162:165], 0
	v_mfma_f32_16x16x32_bf16 v[90:93], v[30:33], v[196:199], 0
	v_mfma_f32_16x16x32_bf16 v[6:9], v[118:121], v[196:199], 0
	v_mfma_f32_16x16x32_bf16 v[86:89], v[30:33], v[204:207], 0
	v_mfma_f32_16x16x32_bf16 v[2:5], v[118:121], v[204:207], 0
	v_mfma_f32_16x16x32_bf16 v[26:29], v[118:121], v[224:227], 0
	v_mfma_f32_16x16x32_bf16 v[94:97], v[54:57], v[166:169], v[94:97]
	v_mfma_f32_16x16x32_bf16 v[10:13], v[122:125], v[166:169], v[10:13]
	v_mfma_f32_16x16x32_bf16 v[90:93], v[54:57], v[200:203], v[90:93]
	v_mfma_f32_16x16x32_bf16 v[6:9], v[122:125], v[200:203], v[6:9]
	v_mfma_f32_16x16x32_bf16 v[86:89], v[54:57], v[208:211], v[86:89]
	v_mfma_f32_16x16x32_bf16 v[2:5], v[122:125], v[208:211], v[2:5]
	v_mfma_f32_16x16x32_bf16 v[30:33], v[30:33], v[224:227], 0
	v_mfma_f32_16x16x32_bf16 v[26:29], v[122:125], v[228:231], v[26:29]
	v_mfma_f32_16x16x32_bf16 v[30:33], v[54:57], v[228:231], v[30:33]
	v_mfma_f32_16x16x32_bf16 v[22:25], v[154:157], v[162:165], 0
	v_mfma_f32_16x16x32_bf16 v[106:109], v[146:149], v[196:199], 0
	v_mfma_f32_16x16x32_bf16 v[18:21], v[154:157], v[196:199], 0
	v_mfma_f32_16x16x32_bf16 v[102:105], v[146:149], v[204:207], 0
	v_mfma_f32_16x16x32_bf16 v[14:17], v[154:157], v[204:207], 0
	v_mfma_f32_16x16x32_bf16 v[58:61], v[154:157], v[224:227], 0
	v_mfma_f32_16x16x32_bf16 v[54:57], v[146:149], v[162:165], 0
	v_mfma_f32_16x16x32_bf16 v[22:25], v[158:161], v[166:169], v[22:25]
	v_mfma_f32_16x16x32_bf16 v[106:109], v[150:153], v[200:203], v[106:109]
	v_mfma_f32_16x16x32_bf16 v[18:21], v[158:161], v[200:203], v[18:21]
	v_mfma_f32_16x16x32_bf16 v[102:105], v[150:153], v[208:211], v[102:105]
	v_mfma_f32_16x16x32_bf16 v[14:17], v[158:161], v[208:211], v[14:17]
	v_mfma_f32_16x16x32_bf16 v[110:113], v[146:149], v[224:227], 0
	v_mfma_f32_16x16x32_bf16 v[58:61], v[158:161], v[228:231], v[58:61]
	v_mfma_f32_16x16x32_bf16 v[54:57], v[150:153], v[166:169], v[54:57]
	v_mfma_f32_16x16x32_bf16 v[118:121], v[150:153], v[228:231], v[110:113]
	s_barrier
	s_add_i32 s84, 0, 0x18000
	s_add_i32 s85, 0, 0x1c000
	v_add_u32_e32 v126, s84, v175
	v_add_u32_e32 v158, s85, v175
	ds_read_b128 v[110:113], v126
	ds_read_b128 v[114:117], v126 offset:1024
	ds_read_b128 v[122:125], v126 offset:2048
	ds_read_b128 v[126:129], v126 offset:3072
	ds_read_b128 v[146:149], v158
	ds_read_b128 v[150:153], v158 offset:1024
	ds_read_b128 v[154:157], v158 offset:2048
	ds_read_b128 v[158:161], v158 offset:3072
	s_add_u32 s54, s54, 0x40000
	s_addc_u32 s55, s55, 0
	s_mov_b32 m0, s63
	ds_read_b128 v[162:165], v221 offset:32768
	ds_read_b128 v[166:169], v221 offset:33792
	ds_read_b128 v[196:199], v221 offset:34816
	ds_read_b128 v[200:203], v221 offset:35840
	ds_read_b128 v[204:207], v221 offset:36864
	ds_read_b128 v[208:211], v221 offset:37888
	ds_read_b128 v[224:227], v221 offset:38912
	ds_read_b128 v[228:231], v221 offset:39936
	global_load_lds_dwordx4 v176, s[54:55]
	s_mov_b32 m0, s64
	s_nop 0
	global_load_lds_dwordx4 v180, s[54:55]
	s_waitcnt vmcnt(8)
	s_waitcnt lgkmcnt(0)
	s_barrier
	v_mfma_f32_16x16x32_bf16 v[62:65], v[110:113], v[162:165], v[62:65]
	v_mfma_f32_16x16x32_bf16 v[42:45], v[122:125], v[162:165], v[42:45]
	v_mfma_f32_16x16x32_bf16 v[50:53], v[110:113], v[196:199], v[50:53]
	v_mfma_f32_16x16x32_bf16 v[38:41], v[122:125], v[196:199], v[38:41]
	v_mfma_f32_16x16x32_bf16 v[46:49], v[110:113], v[204:207], v[46:49]
	v_mfma_f32_16x16x32_bf16 v[34:37], v[122:125], v[204:207], v[34:37]
	v_mfma_f32_16x16x32_bf16 v[142:145], v[110:113], v[224:227], v[142:145]
	v_mfma_f32_16x16x32_bf16 v[82:85], v[122:125], v[224:227], v[82:85]
	v_mfma_f32_16x16x32_bf16 v[62:65], v[114:117], v[166:169], v[62:65]
	v_mfma_f32_16x16x32_bf16 v[42:45], v[126:129], v[166:169], v[42:45]
	v_mfma_f32_16x16x32_bf16 v[50:53], v[114:117], v[200:203], v[50:53]
	v_mfma_f32_16x16x32_bf16 v[38:41], v[126:129], v[200:203], v[38:41]
	v_mfma_f32_16x16x32_bf16 v[46:49], v[114:117], v[208:211], v[46:49]
	v_mfma_f32_16x16x32_bf16 v[34:37], v[126:129], v[208:211], v[34:37]
	v_mfma_f32_16x16x32_bf16 v[142:145], v[114:117], v[228:231], v[142:145]
	v_mfma_f32_16x16x32_bf16 v[82:85], v[126:129], v[228:231], v[82:85]
	v_mfma_f32_16x16x32_bf16 v[134:137], v[146:149], v[162:165], v[134:137]
	v_mfma_f32_16x16x32_bf16 v[74:77], v[154:157], v[162:165], v[74:77]
	v_mfma_f32_16x16x32_bf16 v[130:133], v[146:149], v[196:199], v[130:133]
	v_mfma_f32_16x16x32_bf16 v[70:73], v[154:157], v[196:199], v[70:73]
	v_mfma_f32_16x16x32_bf16 v[78:81], v[146:149], v[204:207], v[78:81]
	v_mfma_f32_16x16x32_bf16 v[66:69], v[154:157], v[204:207], v[66:69]
	v_mfma_f32_16x16x32_bf16 v[138:141], v[146:149], v[224:227], v[138:141]
	v_mfma_f32_16x16x32_bf16 v[98:101], v[154:157], v[224:227], v[98:101]
	v_mfma_f32_16x16x32_bf16 v[134:137], v[150:153], v[166:169], v[134:137]
	v_mfma_f32_16x16x32_bf16 v[74:77], v[158:161], v[166:169], v[74:77]
	v_mfma_f32_16x16x32_bf16 v[130:133], v[150:153], v[200:203], v[130:133]
	v_mfma_f32_16x16x32_bf16 v[70:73], v[158:161], v[200:203], v[70:73]
	v_mfma_f32_16x16x32_bf16 v[78:81], v[150:153], v[208:211], v[78:81]
	v_mfma_f32_16x16x32_bf16 v[66:69], v[158:161], v[208:211], v[66:69]
	v_mfma_f32_16x16x32_bf16 v[138:141], v[150:153], v[228:231], v[138:141]
	v_mfma_f32_16x16x32_bf16 v[98:101], v[158:161], v[228:231], v[98:101]
	s_barrier
	s_add_i32 s54, s84, s57
	s_mov_b32 m0, s54
	ds_read_b128 v[162:165], v221 offset:49152
	ds_read_b128 v[166:169], v221 offset:50176
	ds_read_b128 v[196:199], v221 offset:51200
	ds_read_b128 v[200:203], v221 offset:52224
	ds_read_b128 v[204:207], v221 offset:53248
	ds_read_b128 v[208:211], v221 offset:54272
	ds_read_b128 v[224:227], v221 offset:55296
	ds_read_b128 v[228:231], v221 offset:56320
	global_load_lds_dwordx4 v178, s[98:99]
	s_add_i32 m0, s54, 0x2000
	s_add_u32 s52, s52, 0x40080
	s_addc_u32 s53, s53, 0
	s_add_i32 s54, s85, s57
	global_load_lds_dwordx4 v182, s[98:99]
	s_mov_b32 m0, s54
	s_nop 0
	global_load_lds_dwordx4 v178, s[52:53]
	s_add_i32 m0, s54, 0x2000
	s_nop 0
	global_load_lds_dwordx4 v182, s[52:53]
	s_mov_b32 m0, s70
	s_nop 0
	global_load_lds_dwordx4 v176, s[100:101]
	s_mov_b32 m0, s71
	s_nop 0
	global_load_lds_dwordx4 v180, s[100:101]
	s_waitcnt vmcnt(8)
	s_waitcnt lgkmcnt(0)
	s_barrier
	v_mfma_f32_16x16x32_bf16 v[94:97], v[110:113], v[162:165], v[94:97]
	v_mfma_f32_16x16x32_bf16 v[10:13], v[122:125], v[162:165], v[10:13]
	v_mfma_f32_16x16x32_bf16 v[90:93], v[110:113], v[196:199], v[90:93]
	v_mfma_f32_16x16x32_bf16 v[6:9], v[122:125], v[196:199], v[6:9]
	v_mfma_f32_16x16x32_bf16 v[86:89], v[110:113], v[204:207], v[86:89]
	v_mfma_f32_16x16x32_bf16 v[2:5], v[122:125], v[204:207], v[2:5]
	v_mfma_f32_16x16x32_bf16 v[30:33], v[110:113], v[224:227], v[30:33]
	v_mfma_f32_16x16x32_bf16 v[26:29], v[122:125], v[224:227], v[26:29]
	v_mfma_f32_16x16x32_bf16 v[94:97], v[114:117], v[166:169], v[94:97]
	v_mfma_f32_16x16x32_bf16 v[10:13], v[126:129], v[166:169], v[10:13]
	v_mfma_f32_16x16x32_bf16 v[90:93], v[114:117], v[200:203], v[90:93]
	v_mfma_f32_16x16x32_bf16 v[6:9], v[126:129], v[200:203], v[6:9]
	v_mfma_f32_16x16x32_bf16 v[86:89], v[114:117], v[208:211], v[86:89]
	v_mfma_f32_16x16x32_bf16 v[2:5], v[126:129], v[208:211], v[2:5]
	v_mfma_f32_16x16x32_bf16 v[114:117], v[114:117], v[228:231], v[30:33]
	v_mfma_f32_16x16x32_bf16 v[26:29], v[126:129], v[228:231], v[26:29]
	v_mfma_f32_16x16x32_bf16 v[30:33], v[146:149], v[162:165], v[54:57]
	v_mfma_f32_16x16x32_bf16 v[110:113], v[150:153], v[166:169], v[30:33]
	v_mfma_f32_16x16x32_bf16 v[30:33], v[146:149], v[196:199], v[106:109]
	v_mfma_f32_16x16x32_bf16 v[106:109], v[150:153], v[200:203], v[30:33]
	v_mfma_f32_16x16x32_bf16 v[30:33], v[146:149], v[204:207], v[102:105]
	v_mfma_f32_16x16x32_bf16 v[102:105], v[150:153], v[208:211], v[30:33]
	v_mfma_f32_16x16x32_bf16 v[30:33], v[146:149], v[224:227], v[118:121]
	v_mfma_f32_16x16x32_bf16 v[22:25], v[154:157], v[162:165], v[22:25]
	v_mfma_f32_16x16x32_bf16 v[18:21], v[154:157], v[196:199], v[18:21]
	v_mfma_f32_16x16x32_bf16 v[14:17], v[154:157], v[204:207], v[14:17]
	v_mfma_f32_16x16x32_bf16 v[126:129], v[150:153], v[228:231], v[30:33]
	v_mfma_f32_16x16x32_bf16 v[30:33], v[154:157], v[224:227], v[58:61]
	v_mfma_f32_16x16x32_bf16 v[22:25], v[158:161], v[166:169], v[22:25]
	v_mfma_f32_16x16x32_bf16 v[18:21], v[158:161], v[200:203], v[18:21]
	v_mfma_f32_16x16x32_bf16 v[14:17], v[158:161], v[208:211], v[14:17]
	v_mfma_f32_16x16x32_bf16 v[58:61], v[158:161], v[228:231], v[30:33]
	s_barrier
	s_add_i32 s93, s93, 2
	s_add_u32 s8, s8, 0x100
	s_addc_u32 s9, s9, 0
	s_add_u32 s91, s91, 0x100
	s_addc_u32 s92, s92, 0
	s_cmp_gt_u32 s93, 13
.LBB0_1317:
	ds_read_b128 v[30:33], v219
	ds_read_b128 v[54:57], v219 offset:1024
	ds_read_b128 v[118:121], v219 offset:2048
	ds_read_b128 v[122:125], v219 offset:3072
	ds_read_b128 v[146:149], v220
	ds_read_b128 v[150:153], v220 offset:1024
	ds_read_b128 v[154:157], v220 offset:2048
	ds_read_b128 v[158:161], v220 offset:3072
	s_add_u32 s52, s8, 0xfffc0080
	s_addc_u32 s53, s9, -1
	s_cmp_eq_u32 s93, 12
	s_cselect_b32 s55, s45, s53
	s_cselect_b32 s54, s51, s52
	s_cselect_b32 s53, s43, s92
	s_cselect_b32 s52, s90, s91
	s_add_i32 m0, s59, 0xc000
	ds_read_b128 v[162:165], v221
	ds_read_b128 v[166:169], v221 offset:1024
	ds_read_b128 v[196:199], v221 offset:2048
	ds_read_b128 v[200:203], v221 offset:3072
	ds_read_b128 v[204:207], v221 offset:4096
	ds_read_b128 v[208:211], v221 offset:5120
	ds_read_b128 v[224:227], v221 offset:6144
	ds_read_b128 v[228:231], v221 offset:7168
	global_load_lds_dwordx4 v188, s[8:9]
	s_add_i32 m0, s59, 0xe000
	s_nop 0
	global_load_lds_dwordx4 v190, s[8:9]
	s_waitcnt vmcnt(8)
	s_waitcnt lgkmcnt(0)
	s_barrier
	v_mfma_f32_16x16x32_bf16 v[62:65], v[30:33], v[162:165], v[62:65]
	v_mfma_f32_16x16x32_bf16 v[42:45], v[118:121], v[162:165], v[42:45]
	v_mfma_f32_16x16x32_bf16 v[50:53], v[30:33], v[196:199], v[50:53]
	v_mfma_f32_16x16x32_bf16 v[38:41], v[118:121], v[196:199], v[38:41]
	v_mfma_f32_16x16x32_bf16 v[46:49], v[30:33], v[204:207], v[46:49]
	v_mfma_f32_16x16x32_bf16 v[34:37], v[118:121], v[204:207], v[34:37]
	v_mfma_f32_16x16x32_bf16 v[142:145], v[30:33], v[224:227], v[142:145]
	v_mfma_f32_16x16x32_bf16 v[82:85], v[118:121], v[224:227], v[82:85]
	v_mfma_f32_16x16x32_bf16 v[62:65], v[54:57], v[166:169], v[62:65]
	v_mfma_f32_16x16x32_bf16 v[42:45], v[122:125], v[166:169], v[42:45]
	v_mfma_f32_16x16x32_bf16 v[50:53], v[54:57], v[200:203], v[50:53]
	v_mfma_f32_16x16x32_bf16 v[38:41], v[122:125], v[200:203], v[38:41]
	v_mfma_f32_16x16x32_bf16 v[46:49], v[54:57], v[208:211], v[46:49]
	v_mfma_f32_16x16x32_bf16 v[34:37], v[122:125], v[208:211], v[34:37]
	v_mfma_f32_16x16x32_bf16 v[142:145], v[54:57], v[228:231], v[142:145]
	v_mfma_f32_16x16x32_bf16 v[82:85], v[122:125], v[228:231], v[82:85]
	v_mfma_f32_16x16x32_bf16 v[134:137], v[146:149], v[162:165], v[134:137]
	v_mfma_f32_16x16x32_bf16 v[74:77], v[154:157], v[162:165], v[74:77]
	v_mfma_f32_16x16x32_bf16 v[130:133], v[146:149], v[196:199], v[130:133]
	v_mfma_f32_16x16x32_bf16 v[70:73], v[154:157], v[196:199], v[70:73]
	v_mfma_f32_16x16x32_bf16 v[78:81], v[146:149], v[204:207], v[78:81]
	v_mfma_f32_16x16x32_bf16 v[66:69], v[154:157], v[204:207], v[66:69]
	v_mfma_f32_16x16x32_bf16 v[138:141], v[146:149], v[224:227], v[138:141]
	v_mfma_f32_16x16x32_bf16 v[98:101], v[154:157], v[224:227], v[98:101]
	v_mfma_f32_16x16x32_bf16 v[134:137], v[150:153], v[166:169], v[134:137]
	v_mfma_f32_16x16x32_bf16 v[74:77], v[158:161], v[166:169], v[74:77]
	v_mfma_f32_16x16x32_bf16 v[130:133], v[150:153], v[200:203], v[130:133]
	v_mfma_f32_16x16x32_bf16 v[70:73], v[158:161], v[200:203], v[70:73]
	v_mfma_f32_16x16x32_bf16 v[78:81], v[150:153], v[208:211], v[78:81]
	v_mfma_f32_16x16x32_bf16 v[66:69], v[158:161], v[208:211], v[66:69]
	v_mfma_f32_16x16x32_bf16 v[138:141], v[150:153], v[228:231], v[138:141]
	v_mfma_f32_16x16x32_bf16 v[98:101], v[158:161], v[228:231], v[98:101]
	s_barrier
	s_add_u32 s98, s52, 0x80
	s_addc_u32 s99, s53, 0
	s_add_u32 s100, s54, 0x80
	s_addc_u32 s101, s55, 0
	s_add_i32 s84, s75, s57
	s_mov_b32 m0, s84
	ds_read_b128 v[162:165], v221 offset:16384
	ds_read_b128 v[166:169], v221 offset:17408
	ds_read_b128 v[196:199], v221 offset:18432
	ds_read_b128 v[200:203], v221 offset:19456
	ds_read_b128 v[204:207], v221 offset:20480
	ds_read_b128 v[208:211], v221 offset:21504
	ds_read_b128 v[224:227], v221 offset:22528
	ds_read_b128 v[228:231], v221 offset:23552
	global_load_lds_dwordx4 v178, s[52:53]
	s_add_i32 m0, s84, 0x2000
	s_add_u32 s84, s52, 0x40000
	s_addc_u32 s85, s53, 0
	s_add_i32 s86, s76, s57
	global_load_lds_dwordx4 v182, s[52:53]
	s_mov_b32 m0, s86
	s_nop 0
	global_load_lds_dwordx4 v178, s[84:85]
	s_add_i32 m0, s86, 0x2000
	s_nop 0
	global_load_lds_dwordx4 v182, s[84:85]
	s_mov_b32 m0, s59
	s_nop 0
	global_load_lds_dwordx4 v176, s[54:55]
	s_mov_b32 m0, s62
	s_nop 0
	global_load_lds_dwordx4 v180, s[54:55]
	s_waitcnt vmcnt(8)
	s_waitcnt lgkmcnt(0)
	s_barrier
	v_mfma_f32_16x16x32_bf16 v[94:97], v[30:33], v[162:165], v[94:97]
	v_mfma_f32_16x16x32_bf16 v[10:13], v[118:121], v[162:165], v[10:13]
	v_mfma_f32_16x16x32_bf16 v[90:93], v[30:33], v[196:199], v[90:93]
	v_mfma_f32_16x16x32_bf16 v[6:9], v[118:121], v[196:199], v[6:9]
	v_mfma_f32_16x16x32_bf16 v[86:89], v[30:33], v[204:207], v[86:89]
	v_mfma_f32_16x16x32_bf16 v[2:5], v[118:121], v[204:207], v[2:5]
	v_mfma_f32_16x16x32_bf16 v[26:29], v[118:121], v[224:227], v[26:29]
	v_mfma_f32_16x16x32_bf16 v[94:97], v[54:57], v[166:169], v[94:97]
	v_mfma_f32_16x16x32_bf16 v[10:13], v[122:125], v[166:169], v[10:13]
	v_mfma_f32_16x16x32_bf16 v[90:93], v[54:57], v[200:203], v[90:93]
	v_mfma_f32_16x16x32_bf16 v[6:9], v[122:125], v[200:203], v[6:9]
	v_mfma_f32_16x16x32_bf16 v[86:89], v[54:57], v[208:211], v[86:89]
	v_mfma_f32_16x16x32_bf16 v[2:5], v[122:125], v[208:211], v[2:5]
	v_mfma_f32_16x16x32_bf16 v[30:33], v[30:33], v[224:227], v[114:117]
	v_mfma_f32_16x16x32_bf16 v[26:29], v[122:125], v[228:231], v[26:29]
	v_mfma_f32_16x16x32_bf16 v[30:33], v[54:57], v[228:231], v[30:33]
	v_mfma_f32_16x16x32_bf16 v[22:25], v[154:157], v[162:165], v[22:25]
	v_mfma_f32_16x16x32_bf16 v[106:109], v[146:149], v[196:199], v[106:109]
	v_mfma_f32_16x16x32_bf16 v[18:21], v[154:157], v[196:199], v[18:21]
	v_mfma_f32_16x16x32_bf16 v[102:105], v[146:149], v[204:207], v[102:105]
	v_mfma_f32_16x16x32_bf16 v[14:17], v[154:157], v[204:207], v[14:17]
	v_mfma_f32_16x16x32_bf16 v[58:61], v[154:157], v[224:227], v[58:61]
	v_mfma_f32_16x16x32_bf16 v[54:57], v[146:149], v[162:165], v[110:113]
	v_mfma_f32_16x16x32_bf16 v[22:25], v[158:161], v[166:169], v[22:25]
	v_mfma_f32_16x16x32_bf16 v[106:109], v[150:153], v[200:203], v[106:109]
	v_mfma_f32_16x16x32_bf16 v[18:21], v[158:161], v[200:203], v[18:21]
	v_mfma_f32_16x16x32_bf16 v[102:105], v[150:153], v[208:211], v[102:105]
	v_mfma_f32_16x16x32_bf16 v[14:17], v[158:161], v[208:211], v[14:17]
	v_mfma_f32_16x16x32_bf16 v[110:113], v[146:149], v[224:227], v[126:129]
	v_mfma_f32_16x16x32_bf16 v[58:61], v[158:161], v[228:231], v[58:61]
	v_mfma_f32_16x16x32_bf16 v[54:57], v[150:153], v[166:169], v[54:57]
	v_mfma_f32_16x16x32_bf16 v[118:121], v[150:153], v[228:231], v[110:113]
	s_barrier
	s_add_i32 s84, 0, 0x18000
	s_add_i32 s85, 0, 0x1c000
	v_add_u32_e32 v126, s84, v175
	v_add_u32_e32 v158, s85, v175
	ds_read_b128 v[110:113], v126
	ds_read_b128 v[114:117], v126 offset:1024
	ds_read_b128 v[122:125], v126 offset:2048
	ds_read_b128 v[126:129], v126 offset:3072
	ds_read_b128 v[146:149], v158
	ds_read_b128 v[150:153], v158 offset:1024
	ds_read_b128 v[154:157], v158 offset:2048
	ds_read_b128 v[158:161], v158 offset:3072
	s_add_u32 s54, s54, 0x40000
	s_addc_u32 s55, s55, 0
	s_mov_b32 m0, s63
	ds_read_b128 v[162:165], v221 offset:32768
	ds_read_b128 v[166:169], v221 offset:33792
	ds_read_b128 v[196:199], v221 offset:34816
	ds_read_b128 v[200:203], v221 offset:35840
	ds_read_b128 v[204:207], v221 offset:36864
	ds_read_b128 v[208:211], v221 offset:37888
	ds_read_b128 v[224:227], v221 offset:38912
	ds_read_b128 v[228:231], v221 offset:39936
	global_load_lds_dwordx4 v176, s[54:55]
	s_mov_b32 m0, s64
	s_nop 0
	global_load_lds_dwordx4 v180, s[54:55]
	s_waitcnt vmcnt(8)
	s_waitcnt lgkmcnt(0)
	s_barrier
	v_mfma_f32_16x16x32_bf16 v[62:65], v[110:113], v[162:165], v[62:65]
	v_mfma_f32_16x16x32_bf16 v[42:45], v[122:125], v[162:165], v[42:45]
	v_mfma_f32_16x16x32_bf16 v[50:53], v[110:113], v[196:199], v[50:53]
	v_mfma_f32_16x16x32_bf16 v[38:41], v[122:125], v[196:199], v[38:41]
	v_mfma_f32_16x16x32_bf16 v[46:49], v[110:113], v[204:207], v[46:49]
	v_mfma_f32_16x16x32_bf16 v[34:37], v[122:125], v[204:207], v[34:37]
	v_mfma_f32_16x16x32_bf16 v[142:145], v[110:113], v[224:227], v[142:145]
	v_mfma_f32_16x16x32_bf16 v[82:85], v[122:125], v[224:227], v[82:85]
	v_mfma_f32_16x16x32_bf16 v[62:65], v[114:117], v[166:169], v[62:65]
	v_mfma_f32_16x16x32_bf16 v[42:45], v[126:129], v[166:169], v[42:45]
	v_mfma_f32_16x16x32_bf16 v[50:53], v[114:117], v[200:203], v[50:53]
	v_mfma_f32_16x16x32_bf16 v[38:41], v[126:129], v[200:203], v[38:41]
	v_mfma_f32_16x16x32_bf16 v[46:49], v[114:117], v[208:211], v[46:49]
	v_mfma_f32_16x16x32_bf16 v[34:37], v[126:129], v[208:211], v[34:37]
	v_mfma_f32_16x16x32_bf16 v[142:145], v[114:117], v[228:231], v[142:145]
	v_mfma_f32_16x16x32_bf16 v[82:85], v[126:129], v[228:231], v[82:85]
	v_mfma_f32_16x16x32_bf16 v[134:137], v[146:149], v[162:165], v[134:137]
	v_mfma_f32_16x16x32_bf16 v[74:77], v[154:157], v[162:165], v[74:77]
	v_mfma_f32_16x16x32_bf16 v[130:133], v[146:149], v[196:199], v[130:133]
	v_mfma_f32_16x16x32_bf16 v[70:73], v[154:157], v[196:199], v[70:73]
	v_mfma_f32_16x16x32_bf16 v[78:81], v[146:149], v[204:207], v[78:81]
	v_mfma_f32_16x16x32_bf16 v[66:69], v[154:157], v[204:207], v[66:69]
	v_mfma_f32_16x16x32_bf16 v[138:141], v[146:149], v[224:227], v[138:141]
	v_mfma_f32_16x16x32_bf16 v[98:101], v[154:157], v[224:227], v[98:101]
	v_mfma_f32_16x16x32_bf16 v[134:137], v[150:153], v[166:169], v[134:137]
	v_mfma_f32_16x16x32_bf16 v[74:77], v[158:161], v[166:169], v[74:77]
	v_mfma_f32_16x16x32_bf16 v[130:133], v[150:153], v[200:203], v[130:133]
	v_mfma_f32_16x16x32_bf16 v[70:73], v[158:161], v[200:203], v[70:73]
	v_mfma_f32_16x16x32_bf16 v[78:81], v[150:153], v[208:211], v[78:81]
	v_mfma_f32_16x16x32_bf16 v[66:69], v[158:161], v[208:211], v[66:69]
	v_mfma_f32_16x16x32_bf16 v[138:141], v[150:153], v[228:231], v[138:141]
	v_mfma_f32_16x16x32_bf16 v[98:101], v[158:161], v[228:231], v[98:101]
	s_barrier
	s_add_i32 s54, s84, s57
	s_mov_b32 m0, s54
	ds_read_b128 v[162:165], v221 offset:49152
	ds_read_b128 v[166:169], v221 offset:50176
	ds_read_b128 v[196:199], v221 offset:51200
	ds_read_b128 v[200:203], v221 offset:52224
	ds_read_b128 v[204:207], v221 offset:53248
	ds_read_b128 v[208:211], v221 offset:54272
	ds_read_b128 v[224:227], v221 offset:55296
	ds_read_b128 v[228:231], v221 offset:56320
	global_load_lds_dwordx4 v178, s[98:99]
	s_add_i32 m0, s54, 0x2000
	s_add_u32 s52, s52, 0x40080
	s_addc_u32 s53, s53, 0
	s_add_i32 s54, s85, s57
	global_load_lds_dwordx4 v182, s[98:99]
	s_mov_b32 m0, s54
	s_nop 0
	global_load_lds_dwordx4 v178, s[52:53]
	s_add_i32 m0, s54, 0x2000
	s_nop 0
	global_load_lds_dwordx4 v182, s[52:53]
	s_mov_b32 m0, s70
	s_nop 0
	global_load_lds_dwordx4 v176, s[100:101]
	s_mov_b32 m0, s71
	s_nop 0
	global_load_lds_dwordx4 v180, s[100:101]
	s_waitcnt vmcnt(8)
	s_waitcnt lgkmcnt(0)
	s_barrier
	v_mfma_f32_16x16x32_bf16 v[94:97], v[110:113], v[162:165], v[94:97]
	v_mfma_f32_16x16x32_bf16 v[10:13], v[122:125], v[162:165], v[10:13]
	v_mfma_f32_16x16x32_bf16 v[90:93], v[110:113], v[196:199], v[90:93]
	v_mfma_f32_16x16x32_bf16 v[6:9], v[122:125], v[196:199], v[6:9]
	v_mfma_f32_16x16x32_bf16 v[86:89], v[110:113], v[204:207], v[86:89]
	v_mfma_f32_16x16x32_bf16 v[2:5], v[122:125], v[204:207], v[2:5]
	v_mfma_f32_16x16x32_bf16 v[30:33], v[110:113], v[224:227], v[30:33]
	v_mfma_f32_16x16x32_bf16 v[26:29], v[122:125], v[224:227], v[26:29]
	v_mfma_f32_16x16x32_bf16 v[94:97], v[114:117], v[166:169], v[94:97]
	v_mfma_f32_16x16x32_bf16 v[10:13], v[126:129], v[166:169], v[10:13]
	v_mfma_f32_16x16x32_bf16 v[90:93], v[114:117], v[200:203], v[90:93]
	v_mfma_f32_16x16x32_bf16 v[6:9], v[126:129], v[200:203], v[6:9]
	v_mfma_f32_16x16x32_bf16 v[86:89], v[114:117], v[208:211], v[86:89]
	v_mfma_f32_16x16x32_bf16 v[2:5], v[126:129], v[208:211], v[2:5]
	v_mfma_f32_16x16x32_bf16 v[114:117], v[114:117], v[228:231], v[30:33]
	v_mfma_f32_16x16x32_bf16 v[26:29], v[126:129], v[228:231], v[26:29]
	v_mfma_f32_16x16x32_bf16 v[30:33], v[146:149], v[162:165], v[54:57]
	v_mfma_f32_16x16x32_bf16 v[110:113], v[150:153], v[166:169], v[30:33]
	v_mfma_f32_16x16x32_bf16 v[30:33], v[146:149], v[196:199], v[106:109]
	v_mfma_f32_16x16x32_bf16 v[106:109], v[150:153], v[200:203], v[30:33]
	v_mfma_f32_16x16x32_bf16 v[30:33], v[146:149], v[204:207], v[102:105]
	v_mfma_f32_16x16x32_bf16 v[102:105], v[150:153], v[208:211], v[30:33]
	v_mfma_f32_16x16x32_bf16 v[30:33], v[146:149], v[224:227], v[118:121]
	v_mfma_f32_16x16x32_bf16 v[22:25], v[154:157], v[162:165], v[22:25]
	v_mfma_f32_16x16x32_bf16 v[18:21], v[154:157], v[196:199], v[18:21]
	v_mfma_f32_16x16x32_bf16 v[14:17], v[154:157], v[204:207], v[14:17]
	v_mfma_f32_16x16x32_bf16 v[126:129], v[150:153], v[228:231], v[30:33]
	v_mfma_f32_16x16x32_bf16 v[30:33], v[154:157], v[224:227], v[58:61]
	v_mfma_f32_16x16x32_bf16 v[22:25], v[158:161], v[166:169], v[22:25]
	v_mfma_f32_16x16x32_bf16 v[18:21], v[158:161], v[200:203], v[18:21]
	v_mfma_f32_16x16x32_bf16 v[14:17], v[158:161], v[208:211], v[14:17]
	v_mfma_f32_16x16x32_bf16 v[58:61], v[158:161], v[228:231], v[30:33]
	s_barrier
	s_add_i32 s93, s93, 2
	s_add_u32 s8, s8, 0x100
	s_addc_u32 s9, s9, 0
	s_add_u32 s91, s91, 0x100
	s_addc_u32 s92, s92, 0
	s_cmp_gt_u32 s93, 13
	s_cbranch_scc0 .LBB0_1317
	s_and_b64 vcc, exec, s[18:19]
	s_cbranch_vccz .LBB0_1320
	s_barrier

.LBB0_1462:
	s_add_u32 s16, s16, 0xb0080
	s_addc_u32 s17, s17, 0
	s_add_u32 s43, s18, 0x100
	s_addc_u32 s44, s19, 0
	s_mov_b32 s45, -2
	ds_read_b128 v[128:131], v169
	ds_read_b128 v[132:135], v169 offset:1024
	ds_read_b128 v[136:139], v169 offset:2048
	ds_read_b128 v[140:143], v169 offset:3072
	ds_read_b128 v[160:163], v170
	ds_read_b128 v[172:175], v170 offset:1024
	ds_read_b128 v[176:179], v170 offset:2048
	ds_read_b128 v[180:183], v170 offset:3072
	s_add_u32 s18, s16, 0xfff50080
	s_addc_u32 s19, s17, -1
	s_cmp_eq_u32 s45, 40
	s_cselect_b32 s21, s5, s19
	s_cselect_b32 s20, s4, s18
	s_cselect_b32 s19, s15, s44
	s_cselect_b32 s18, s14, s43
	s_add_i32 m0, s26, 0xc000
	ds_read_b128 v[184:187], v171
	ds_read_b128 v[188:191], v171 offset:1024
	ds_read_b128 v[192:195], v171 offset:2048
	ds_read_b128 v[196:199], v171 offset:3072
	ds_read_b128 v[200:203], v171 offset:4096
	ds_read_b128 v[204:207], v171 offset:5120
	ds_read_b128 v[208:211], v171 offset:6144
	ds_read_b128 v[212:215], v171 offset:7168
	global_load_lds_dwordx4 v152, s[16:17]
	s_add_i32 m0, s26, 0xe000
	s_nop 0
	global_load_lds_dwordx4 v154, s[16:17]
	s_waitcnt vmcnt(8)
	s_waitcnt lgkmcnt(0)
	s_barrier
	v_mfma_f32_16x16x32_bf16 v[124:127], v[128:131], v[184:187], 0
	v_mfma_f32_16x16x32_bf16 v[120:123], v[136:139], v[184:187], 0
	v_mfma_f32_16x16x32_bf16 v[116:119], v[128:131], v[192:195], 0
	v_mfma_f32_16x16x32_bf16 v[108:111], v[136:139], v[192:195], 0
	v_mfma_f32_16x16x32_bf16 v[92:95], v[128:131], v[200:203], 0
	v_mfma_f32_16x16x32_bf16 v[88:91], v[136:139], v[200:203], 0
	v_mfma_f32_16x16x32_bf16 v[84:87], v[128:131], v[208:211], 0
	v_mfma_f32_16x16x32_bf16 v[80:83], v[136:139], v[208:211], 0
	v_mfma_f32_16x16x32_bf16 v[124:127], v[132:135], v[188:191], v[124:127]
	v_mfma_f32_16x16x32_bf16 v[120:123], v[140:143], v[188:191], v[120:123]
	v_mfma_f32_16x16x32_bf16 v[116:119], v[132:135], v[196:199], v[116:119]
	v_mfma_f32_16x16x32_bf16 v[108:111], v[140:143], v[196:199], v[108:111]
	v_mfma_f32_16x16x32_bf16 v[92:95], v[132:135], v[204:207], v[92:95]
	v_mfma_f32_16x16x32_bf16 v[88:91], v[140:143], v[204:207], v[88:91]
	v_mfma_f32_16x16x32_bf16 v[84:87], v[132:135], v[212:215], v[84:87]
	v_mfma_f32_16x16x32_bf16 v[80:83], v[140:143], v[212:215], v[80:83]
	v_mfma_f32_16x16x32_bf16 v[112:115], v[160:163], v[184:187], 0
	v_mfma_f32_16x16x32_bf16 v[104:107], v[176:179], v[184:187], 0
	v_mfma_f32_16x16x32_bf16 v[100:103], v[160:163], v[192:195], 0
	v_mfma_f32_16x16x32_bf16 v[96:99], v[176:179], v[192:195], 0
	v_mfma_f32_16x16x32_bf16 v[76:79], v[160:163], v[200:203], 0
	v_mfma_f32_16x16x32_bf16 v[72:75], v[176:179], v[200:203], 0
	v_mfma_f32_16x16x32_bf16 v[68:71], v[160:163], v[208:211], 0
	v_mfma_f32_16x16x32_bf16 v[64:67], v[176:179], v[208:211], 0
	v_mfma_f32_16x16x32_bf16 v[112:115], v[172:175], v[188:191], v[112:115]
	v_mfma_f32_16x16x32_bf16 v[104:107], v[180:183], v[188:191], v[104:107]
	v_mfma_f32_16x16x32_bf16 v[100:103], v[172:175], v[196:199], v[100:103]
	v_mfma_f32_16x16x32_bf16 v[96:99], v[180:183], v[196:199], v[96:99]
	v_mfma_f32_16x16x32_bf16 v[76:79], v[172:175], v[204:207], v[76:79]
	v_mfma_f32_16x16x32_bf16 v[72:75], v[180:183], v[204:207], v[72:75]
	v_mfma_f32_16x16x32_bf16 v[68:71], v[172:175], v[212:215], v[68:71]
	v_mfma_f32_16x16x32_bf16 v[64:67], v[180:183], v[212:215], v[64:67]
	s_barrier
	s_add_u32 s98, s18, 0x80
	s_addc_u32 s99, s19, 0
	s_add_u32 s100, s20, 0x80
	s_addc_u32 s101, s21, 0
	s_add_i32 s46, s37, s25
	s_mov_b32 m0, s46
	ds_read_b128 v[184:187], v171 offset:16384
	ds_read_b128 v[188:191], v171 offset:17408
	ds_read_b128 v[192:195], v171 offset:18432
	ds_read_b128 v[196:199], v171 offset:19456
	ds_read_b128 v[200:203], v171 offset:20480
	ds_read_b128 v[204:207], v171 offset:21504
	ds_read_b128 v[208:211], v171 offset:22528
	ds_read_b128 v[212:215], v171 offset:23552
	s_cmp_eq_u32 s45, 40
	s_cselect_b64 exec, 0, -1
	s_cmp_lg_u32 s33, 0x100
	s_cselect_b64 exec, -1, exec
	global_load_lds_dwordx4 v146, s[18:19]
	s_add_i32 m0, s46, 0x2000
	s_add_u32 s46, s18, 0xb0000
	s_addc_u32 s47, s19, 0
	s_add_i32 s48, s38, s25
	global_load_lds_dwordx4 v150, s[18:19]
	s_mov_b32 m0, s48
	s_nop 0
	global_load_lds_dwordx4 v146, s[46:47]
	s_add_i32 m0, s48, 0x2000
	s_nop 0
	global_load_lds_dwordx4 v150, s[46:47]
	s_mov_b32 m0, s26
	s_nop 0
	global_load_lds_dwordx4 v144, s[20:21]
	s_mov_b32 m0, s27
	s_nop 0
	global_load_lds_dwordx4 v148, s[20:21]
	s_mov_b64 exec, -1
	s_waitcnt vmcnt(8)
	s_waitcnt lgkmcnt(0)
	s_barrier
	v_mfma_f32_16x16x32_bf16 v[60:63], v[128:131], v[184:187], 0
	v_mfma_f32_16x16x32_bf16 v[56:59], v[136:139], v[184:187], 0
	v_mfma_f32_16x16x32_bf16 v[52:55], v[128:131], v[192:195], 0
	v_mfma_f32_16x16x32_bf16 v[48:51], v[136:139], v[192:195], 0
	v_mfma_f32_16x16x32_bf16 v[28:31], v[128:131], v[200:203], 0
	v_mfma_f32_16x16x32_bf16 v[24:27], v[136:139], v[200:203], 0
	v_mfma_f32_16x16x32_bf16 v[20:23], v[128:131], v[208:211], 0
	v_mfma_f32_16x16x32_bf16 v[16:19], v[136:139], v[208:211], 0
	v_mfma_f32_16x16x32_bf16 v[60:63], v[132:135], v[188:191], v[60:63]
	v_mfma_f32_16x16x32_bf16 v[56:59], v[140:143], v[188:191], v[56:59]
	v_mfma_f32_16x16x32_bf16 v[52:55], v[132:135], v[196:199], v[52:55]
	v_mfma_f32_16x16x32_bf16 v[48:51], v[140:143], v[196:199], v[48:51]
	v_mfma_f32_16x16x32_bf16 v[28:31], v[132:135], v[204:207], v[28:31]
	v_mfma_f32_16x16x32_bf16 v[24:27], v[140:143], v[204:207], v[24:27]
	v_mfma_f32_16x16x32_bf16 v[20:23], v[132:135], v[212:215], v[20:23]
	v_mfma_f32_16x16x32_bf16 v[16:19], v[140:143], v[212:215], v[16:19]
	v_mfma_f32_16x16x32_bf16 v[44:47], v[160:163], v[184:187], 0
	v_mfma_f32_16x16x32_bf16 v[40:43], v[176:179], v[184:187], 0
	v_mfma_f32_16x16x32_bf16 v[36:39], v[160:163], v[192:195], 0
	v_mfma_f32_16x16x32_bf16 v[32:35], v[176:179], v[192:195], 0
	v_mfma_f32_16x16x32_bf16 v[12:15], v[160:163], v[200:203], 0
	v_mfma_f32_16x16x32_bf16 v[8:11], v[176:179], v[200:203], 0
	v_mfma_f32_16x16x32_bf16 v[4:7], v[160:163], v[208:211], 0
	v_mfma_f32_16x16x32_bf16 v[0:3], v[176:179], v[208:211], 0
	v_mfma_f32_16x16x32_bf16 v[44:47], v[172:175], v[188:191], v[44:47]
	v_mfma_f32_16x16x32_bf16 v[40:43], v[180:183], v[188:191], v[40:43]
	v_mfma_f32_16x16x32_bf16 v[36:39], v[172:175], v[196:199], v[36:39]
	v_mfma_f32_16x16x32_bf16 v[32:35], v[180:183], v[196:199], v[32:35]
	v_mfma_f32_16x16x32_bf16 v[12:15], v[172:175], v[204:207], v[12:15]
	v_mfma_f32_16x16x32_bf16 v[8:11], v[180:183], v[204:207], v[8:11]
	v_mfma_f32_16x16x32_bf16 v[4:7], v[172:175], v[212:215], v[4:7]
	v_mfma_f32_16x16x32_bf16 v[0:3], v[180:183], v[212:215], v[0:3]
	s_barrier
	s_add_i32 s46, 0, 0x18000
	s_add_i32 s47, 0, 0x1c000
	v_add_u32_e32 v140, s46, v167
	v_add_u32_e32 v180, s47, v167
	ds_read_b128 v[128:131], v140
	ds_read_b128 v[132:135], v140 offset:1024
	ds_read_b128 v[136:139], v140 offset:2048
	ds_read_b128 v[140:143], v140 offset:3072
	ds_read_b128 v[160:163], v180
	ds_read_b128 v[172:175], v180 offset:1024
	ds_read_b128 v[176:179], v180 offset:2048
	ds_read_b128 v[180:183], v180 offset:3072
	s_add_u32 s20, s20, 0xb0000
	s_addc_u32 s21, s21, 0
	s_mov_b32 m0, s28
	ds_read_b128 v[184:187], v171 offset:32768
	ds_read_b128 v[188:191], v171 offset:33792
	ds_read_b128 v[192:195], v171 offset:34816
	ds_read_b128 v[196:199], v171 offset:35840
	ds_read_b128 v[200:203], v171 offset:36864
	ds_read_b128 v[204:207], v171 offset:37888
	ds_read_b128 v[208:211], v171 offset:38912
	ds_read_b128 v[212:215], v171 offset:39936
	s_cmp_eq_u32 s45, 40
	s_cselect_b64 exec, 0, -1
	s_cmp_lg_u32 s33, 0x100
	s_cselect_b64 exec, -1, exec
	global_load_lds_dwordx4 v144, s[20:21]
	s_mov_b32 m0, s29
	s_nop 0
	global_load_lds_dwordx4 v148, s[20:21]
	s_mov_b64 exec, -1
	s_waitcnt vmcnt(8)
	s_waitcnt lgkmcnt(0)
	s_barrier
	v_mfma_f32_16x16x32_bf16 v[124:127], v[128:131], v[184:187], v[124:127]
	v_mfma_f32_16x16x32_bf16 v[120:123], v[136:139], v[184:187], v[120:123]
	v_mfma_f32_16x16x32_bf16 v[116:119], v[128:131], v[192:195], v[116:119]
	v_mfma_f32_16x16x32_bf16 v[108:111], v[136:139], v[192:195], v[108:111]
	v_mfma_f32_16x16x32_bf16 v[92:95], v[128:131], v[200:203], v[92:95]
	v_mfma_f32_16x16x32_bf16 v[88:91], v[136:139], v[200:203], v[88:91]
	v_mfma_f32_16x16x32_bf16 v[84:87], v[128:131], v[208:211], v[84:87]
	v_mfma_f32_16x16x32_bf16 v[80:83], v[136:139], v[208:211], v[80:83]
	v_mfma_f32_16x16x32_bf16 v[124:127], v[132:135], v[188:191], v[124:127]
	v_mfma_f32_16x16x32_bf16 v[120:123], v[140:143], v[188:191], v[120:123]
	v_mfma_f32_16x16x32_bf16 v[116:119], v[132:135], v[196:199], v[116:119]
	v_mfma_f32_16x16x32_bf16 v[108:111], v[140:143], v[196:199], v[108:111]
	v_mfma_f32_16x16x32_bf16 v[92:95], v[132:135], v[204:207], v[92:95]
	v_mfma_f32_16x16x32_bf16 v[88:91], v[140:143], v[204:207], v[88:91]
	v_mfma_f32_16x16x32_bf16 v[84:87], v[132:135], v[212:215], v[84:87]
	v_mfma_f32_16x16x32_bf16 v[80:83], v[140:143], v[212:215], v[80:83]
	v_mfma_f32_16x16x32_bf16 v[112:115], v[160:163], v[184:187], v[112:115]
	v_mfma_f32_16x16x32_bf16 v[104:107], v[176:179], v[184:187], v[104:107]
	v_mfma_f32_16x16x32_bf16 v[100:103], v[160:163], v[192:195], v[100:103]
	v_mfma_f32_16x16x32_bf16 v[96:99], v[176:179], v[192:195], v[96:99]
	v_mfma_f32_16x16x32_bf16 v[76:79], v[160:163], v[200:203], v[76:79]
	v_mfma_f32_16x16x32_bf16 v[72:75], v[176:179], v[200:203], v[72:75]
	v_mfma_f32_16x16x32_bf16 v[68:71], v[160:163], v[208:211], v[68:71]
	v_mfma_f32_16x16x32_bf16 v[64:67], v[176:179], v[208:211], v[64:67]
	v_mfma_f32_16x16x32_bf16 v[112:115], v[172:175], v[188:191], v[112:115]
	v_mfma_f32_16x16x32_bf16 v[104:107], v[180:183], v[188:191], v[104:107]
	v_mfma_f32_16x16x32_bf16 v[100:103], v[172:175], v[196:199], v[100:103]
	v_mfma_f32_16x16x32_bf16 v[96:99], v[180:183], v[196:199], v[96:99]
	v_mfma_f32_16x16x32_bf16 v[76:79], v[172:175], v[204:207], v[76:79]
	v_mfma_f32_16x16x32_bf16 v[72:75], v[180:183], v[204:207], v[72:75]
	v_mfma_f32_16x16x32_bf16 v[68:71], v[172:175], v[212:215], v[68:71]
	v_mfma_f32_16x16x32_bf16 v[64:67], v[180:183], v[212:215], v[64:67]
	s_barrier
	s_add_i32 s20, s46, s25
	s_mov_b32 m0, s20
	ds_read_b128 v[184:187], v171 offset:49152
	ds_read_b128 v[188:191], v171 offset:50176
	ds_read_b128 v[192:195], v171 offset:51200
	ds_read_b128 v[196:199], v171 offset:52224
	ds_read_b128 v[200:203], v171 offset:53248
	ds_read_b128 v[204:207], v171 offset:54272
	ds_read_b128 v[208:211], v171 offset:55296
	ds_read_b128 v[212:215], v171 offset:56320
	s_cmp_eq_u32 s45, 40
	s_cselect_b64 exec, 0, -1
	s_cmp_lg_u32 s33, 0x100
	s_cselect_b64 exec, -1, exec
	global_load_lds_dwordx4 v146, s[98:99]
	s_add_i32 m0, s20, 0x2000
	s_add_u32 s18, s18, 0xb0080
	s_addc_u32 s19, s19, 0
	s_add_i32 s20, s47, s25
	global_load_lds_dwordx4 v150, s[98:99]
	s_mov_b32 m0, s20
	s_nop 0
	global_load_lds_dwordx4 v146, s[18:19]
	s_add_i32 m0, s20, 0x2000
	s_nop 0
	global_load_lds_dwordx4 v150, s[18:19]
	s_mov_b32 m0, s35
	s_nop 0
	global_load_lds_dwordx4 v144, s[100:101]
	s_mov_b32 m0, s36
	s_nop 0
	global_load_lds_dwordx4 v148, s[100:101]
	s_mov_b64 exec, -1
	s_waitcnt vmcnt(8)
	s_waitcnt lgkmcnt(0)
	s_barrier
	v_mfma_f32_16x16x32_bf16 v[60:63], v[128:131], v[184:187], v[60:63]
	v_mfma_f32_16x16x32_bf16 v[56:59], v[136:139], v[184:187], v[56:59]
	v_mfma_f32_16x16x32_bf16 v[52:55], v[128:131], v[192:195], v[52:55]
	v_mfma_f32_16x16x32_bf16 v[48:51], v[136:139], v[192:195], v[48:51]
	v_mfma_f32_16x16x32_bf16 v[28:31], v[128:131], v[200:203], v[28:31]
	v_mfma_f32_16x16x32_bf16 v[24:27], v[136:139], v[200:203], v[24:27]
	v_mfma_f32_16x16x32_bf16 v[20:23], v[128:131], v[208:211], v[20:23]
	v_mfma_f32_16x16x32_bf16 v[16:19], v[136:139], v[208:211], v[16:19]
	v_mfma_f32_16x16x32_bf16 v[60:63], v[132:135], v[188:191], v[60:63]
	v_mfma_f32_16x16x32_bf16 v[56:59], v[140:143], v[188:191], v[56:59]
	v_mfma_f32_16x16x32_bf16 v[52:55], v[132:135], v[196:199], v[52:55]
	v_mfma_f32_16x16x32_bf16 v[48:51], v[140:143], v[196:199], v[48:51]
	v_mfma_f32_16x16x32_bf16 v[28:31], v[132:135], v[204:207], v[28:31]
	v_mfma_f32_16x16x32_bf16 v[24:27], v[140:143], v[204:207], v[24:27]
	v_mfma_f32_16x16x32_bf16 v[20:23], v[132:135], v[212:215], v[20:23]
	v_mfma_f32_16x16x32_bf16 v[16:19], v[140:143], v[212:215], v[16:19]
	v_mfma_f32_16x16x32_bf16 v[44:47], v[160:163], v[184:187], v[44:47]
	v_mfma_f32_16x16x32_bf16 v[40:43], v[176:179], v[184:187], v[40:43]
	v_mfma_f32_16x16x32_bf16 v[36:39], v[160:163], v[192:195], v[36:39]
	v_mfma_f32_16x16x32_bf16 v[32:35], v[176:179], v[192:195], v[32:35]
	v_mfma_f32_16x16x32_bf16 v[12:15], v[160:163], v[200:203], v[12:15]
	v_mfma_f32_16x16x32_bf16 v[8:11], v[176:179], v[200:203], v[8:11]
	v_mfma_f32_16x16x32_bf16 v[4:7], v[160:163], v[208:211], v[4:7]
	v_mfma_f32_16x16x32_bf16 v[0:3], v[176:179], v[208:211], v[0:3]
	v_mfma_f32_16x16x32_bf16 v[44:47], v[172:175], v[188:191], v[44:47]
	v_mfma_f32_16x16x32_bf16 v[40:43], v[180:183], v[188:191], v[40:43]
	v_mfma_f32_16x16x32_bf16 v[36:39], v[172:175], v[196:199], v[36:39]
	v_mfma_f32_16x16x32_bf16 v[32:35], v[180:183], v[196:199], v[32:35]
	v_mfma_f32_16x16x32_bf16 v[12:15], v[172:175], v[204:207], v[12:15]
	v_mfma_f32_16x16x32_bf16 v[8:11], v[180:183], v[204:207], v[8:11]
	v_mfma_f32_16x16x32_bf16 v[4:7], v[172:175], v[212:215], v[4:7]
	v_mfma_f32_16x16x32_bf16 v[0:3], v[180:183], v[212:215], v[0:3]
	s_barrier
	s_add_i32 s45, s45, 2
	s_add_u32 s16, s16, 0x100
	s_addc_u32 s17, s17, 0
	s_add_u32 s43, s43, 0x100
	s_addc_u32 s44, s44, 0
	s_cmp_gt_u32 s45, 41
.LBB0_1463:
	ds_read_b128 v[128:131], v169
	ds_read_b128 v[132:135], v169 offset:1024
	ds_read_b128 v[136:139], v169 offset:2048
	ds_read_b128 v[140:143], v169 offset:3072
	ds_read_b128 v[160:163], v170
	ds_read_b128 v[172:175], v170 offset:1024
	ds_read_b128 v[176:179], v170 offset:2048
	ds_read_b128 v[180:183], v170 offset:3072
	s_add_u32 s18, s16, 0xfff50080
	s_addc_u32 s19, s17, -1
	s_cmp_eq_u32 s45, 40
	s_cselect_b32 s21, s5, s19
	s_cselect_b32 s20, s4, s18
	s_cselect_b32 s19, s15, s44
	s_cselect_b32 s18, s14, s43
	s_add_i32 m0, s26, 0xc000
	ds_read_b128 v[184:187], v171
	ds_read_b128 v[188:191], v171 offset:1024
	ds_read_b128 v[192:195], v171 offset:2048
	ds_read_b128 v[196:199], v171 offset:3072
	ds_read_b128 v[200:203], v171 offset:4096
	ds_read_b128 v[204:207], v171 offset:5120
	ds_read_b128 v[208:211], v171 offset:6144
	ds_read_b128 v[212:215], v171 offset:7168
	global_load_lds_dwordx4 v152, s[16:17]
	s_add_i32 m0, s26, 0xe000
	s_nop 0
	global_load_lds_dwordx4 v154, s[16:17]
	s_waitcnt vmcnt(8)
	s_waitcnt lgkmcnt(0)
	s_barrier
	v_mfma_f32_16x16x32_bf16 v[124:127], v[128:131], v[184:187], v[124:127]
	v_mfma_f32_16x16x32_bf16 v[120:123], v[136:139], v[184:187], v[120:123]
	v_mfma_f32_16x16x32_bf16 v[116:119], v[128:131], v[192:195], v[116:119]
	v_mfma_f32_16x16x32_bf16 v[108:111], v[136:139], v[192:195], v[108:111]
	v_mfma_f32_16x16x32_bf16 v[92:95], v[128:131], v[200:203], v[92:95]
	v_mfma_f32_16x16x32_bf16 v[88:91], v[136:139], v[200:203], v[88:91]
	v_mfma_f32_16x16x32_bf16 v[84:87], v[128:131], v[208:211], v[84:87]
	v_mfma_f32_16x16x32_bf16 v[80:83], v[136:139], v[208:211], v[80:83]
	v_mfma_f32_16x16x32_bf16 v[124:127], v[132:135], v[188:191], v[124:127]
	v_mfma_f32_16x16x32_bf16 v[120:123], v[140:143], v[188:191], v[120:123]
	v_mfma_f32_16x16x32_bf16 v[116:119], v[132:135], v[196:199], v[116:119]
	v_mfma_f32_16x16x32_bf16 v[108:111], v[140:143], v[196:199], v[108:111]
	v_mfma_f32_16x16x32_bf16 v[92:95], v[132:135], v[204:207], v[92:95]
	v_mfma_f32_16x16x32_bf16 v[88:91], v[140:143], v[204:207], v[88:91]
	v_mfma_f32_16x16x32_bf16 v[84:87], v[132:135], v[212:215], v[84:87]
	v_mfma_f32_16x16x32_bf16 v[80:83], v[140:143], v[212:215], v[80:83]
	v_mfma_f32_16x16x32_bf16 v[112:115], v[160:163], v[184:187], v[112:115]
	v_mfma_f32_16x16x32_bf16 v[104:107], v[176:179], v[184:187], v[104:107]
	v_mfma_f32_16x16x32_bf16 v[100:103], v[160:163], v[192:195], v[100:103]
	v_mfma_f32_16x16x32_bf16 v[96:99], v[176:179], v[192:195], v[96:99]
	v_mfma_f32_16x16x32_bf16 v[76:79], v[160:163], v[200:203], v[76:79]
	v_mfma_f32_16x16x32_bf16 v[72:75], v[176:179], v[200:203], v[72:75]
	v_mfma_f32_16x16x32_bf16 v[68:71], v[160:163], v[208:211], v[68:71]
	v_mfma_f32_16x16x32_bf16 v[64:67], v[176:179], v[208:211], v[64:67]
	v_mfma_f32_16x16x32_bf16 v[112:115], v[172:175], v[188:191], v[112:115]
	v_mfma_f32_16x16x32_bf16 v[104:107], v[180:183], v[188:191], v[104:107]
	v_mfma_f32_16x16x32_bf16 v[100:103], v[172:175], v[196:199], v[100:103]
	v_mfma_f32_16x16x32_bf16 v[96:99], v[180:183], v[196:199], v[96:99]
	v_mfma_f32_16x16x32_bf16 v[76:79], v[172:175], v[204:207], v[76:79]
	v_mfma_f32_16x16x32_bf16 v[72:75], v[180:183], v[204:207], v[72:75]
	v_mfma_f32_16x16x32_bf16 v[68:71], v[172:175], v[212:215], v[68:71]
	v_mfma_f32_16x16x32_bf16 v[64:67], v[180:183], v[212:215], v[64:67]
	s_barrier
	s_add_u32 s98, s18, 0x80
	s_addc_u32 s99, s19, 0
	s_add_u32 s100, s20, 0x80
	s_addc_u32 s101, s21, 0
	s_add_i32 s46, s37, s25
	s_mov_b32 m0, s46
	ds_read_b128 v[184:187], v171 offset:16384
	ds_read_b128 v[188:191], v171 offset:17408
	ds_read_b128 v[192:195], v171 offset:18432
	ds_read_b128 v[196:199], v171 offset:19456
	ds_read_b128 v[200:203], v171 offset:20480
	ds_read_b128 v[204:207], v171 offset:21504
	ds_read_b128 v[208:211], v171 offset:22528
	ds_read_b128 v[212:215], v171 offset:23552
	s_cmp_eq_u32 s45, 40
	s_cselect_b64 exec, 0, -1
	s_cmp_lg_u32 s33, 0x100
	s_cselect_b64 exec, -1, exec
	global_load_lds_dwordx4 v146, s[18:19]
	s_add_i32 m0, s46, 0x2000
	s_add_u32 s46, s18, 0xb0000
	s_addc_u32 s47, s19, 0
	s_add_i32 s48, s38, s25
	global_load_lds_dwordx4 v150, s[18:19]
	s_mov_b32 m0, s48
	s_nop 0
	global_load_lds_dwordx4 v146, s[46:47]
	s_add_i32 m0, s48, 0x2000
	s_nop 0
	global_load_lds_dwordx4 v150, s[46:47]
	s_mov_b32 m0, s26
	s_nop 0
	global_load_lds_dwordx4 v144, s[20:21]
	s_mov_b32 m0, s27
	s_nop 0
	global_load_lds_dwordx4 v148, s[20:21]
	s_mov_b64 exec, -1
	s_waitcnt vmcnt(8)
	s_waitcnt lgkmcnt(0)
	s_barrier
	v_mfma_f32_16x16x32_bf16 v[60:63], v[128:131], v[184:187], v[60:63]
	v_mfma_f32_16x16x32_bf16 v[56:59], v[136:139], v[184:187], v[56:59]
	v_mfma_f32_16x16x32_bf16 v[52:55], v[128:131], v[192:195], v[52:55]
	v_mfma_f32_16x16x32_bf16 v[48:51], v[136:139], v[192:195], v[48:51]
	v_mfma_f32_16x16x32_bf16 v[28:31], v[128:131], v[200:203], v[28:31]
	v_mfma_f32_16x16x32_bf16 v[24:27], v[136:139], v[200:203], v[24:27]
	v_mfma_f32_16x16x32_bf16 v[20:23], v[128:131], v[208:211], v[20:23]
	v_mfma_f32_16x16x32_bf16 v[16:19], v[136:139], v[208:211], v[16:19]
	v_mfma_f32_16x16x32_bf16 v[60:63], v[132:135], v[188:191], v[60:63]
	v_mfma_f32_16x16x32_bf16 v[56:59], v[140:143], v[188:191], v[56:59]
	v_mfma_f32_16x16x32_bf16 v[52:55], v[132:135], v[196:199], v[52:55]
	v_mfma_f32_16x16x32_bf16 v[48:51], v[140:143], v[196:199], v[48:51]
	v_mfma_f32_16x16x32_bf16 v[28:31], v[132:135], v[204:207], v[28:31]
	v_mfma_f32_16x16x32_bf16 v[24:27], v[140:143], v[204:207], v[24:27]
	v_mfma_f32_16x16x32_bf16 v[20:23], v[132:135], v[212:215], v[20:23]
	v_mfma_f32_16x16x32_bf16 v[16:19], v[140:143], v[212:215], v[16:19]
	v_mfma_f32_16x16x32_bf16 v[44:47], v[160:163], v[184:187], v[44:47]
	v_mfma_f32_16x16x32_bf16 v[40:43], v[176:179], v[184:187], v[40:43]
	v_mfma_f32_16x16x32_bf16 v[36:39], v[160:163], v[192:195], v[36:39]
	v_mfma_f32_16x16x32_bf16 v[32:35], v[176:179], v[192:195], v[32:35]
	v_mfma_f32_16x16x32_bf16 v[12:15], v[160:163], v[200:203], v[12:15]
	v_mfma_f32_16x16x32_bf16 v[8:11], v[176:179], v[200:203], v[8:11]
	v_mfma_f32_16x16x32_bf16 v[4:7], v[160:163], v[208:211], v[4:7]
	v_mfma_f32_16x16x32_bf16 v[0:3], v[176:179], v[208:211], v[0:3]
	v_mfma_f32_16x16x32_bf16 v[44:47], v[172:175], v[188:191], v[44:47]
	v_mfma_f32_16x16x32_bf16 v[40:43], v[180:183], v[188:191], v[40:43]
	v_mfma_f32_16x16x32_bf16 v[36:39], v[172:175], v[196:199], v[36:39]
	v_mfma_f32_16x16x32_bf16 v[32:35], v[180:183], v[196:199], v[32:35]
	v_mfma_f32_16x16x32_bf16 v[12:15], v[172:175], v[204:207], v[12:15]
	v_mfma_f32_16x16x32_bf16 v[8:11], v[180:183], v[204:207], v[8:11]
	v_mfma_f32_16x16x32_bf16 v[4:7], v[172:175], v[212:215], v[4:7]
	v_mfma_f32_16x16x32_bf16 v[0:3], v[180:183], v[212:215], v[0:3]
	s_barrier
	s_add_i32 s46, 0, 0x18000
	s_add_i32 s47, 0, 0x1c000
	v_add_u32_e32 v140, s46, v167
	v_add_u32_e32 v180, s47, v167
	ds_read_b128 v[128:131], v140
	ds_read_b128 v[132:135], v140 offset:1024
	ds_read_b128 v[136:139], v140 offset:2048
	ds_read_b128 v[140:143], v140 offset:3072
	ds_read_b128 v[160:163], v180
	ds_read_b128 v[172:175], v180 offset:1024
	ds_read_b128 v[176:179], v180 offset:2048
	ds_read_b128 v[180:183], v180 offset:3072
	s_add_u32 s20, s20, 0xb0000
	s_addc_u32 s21, s21, 0
	s_mov_b32 m0, s28
	ds_read_b128 v[184:187], v171 offset:32768
	ds_read_b128 v[188:191], v171 offset:33792
	ds_read_b128 v[192:195], v171 offset:34816
	ds_read_b128 v[196:199], v171 offset:35840
	ds_read_b128 v[200:203], v171 offset:36864
	ds_read_b128 v[204:207], v171 offset:37888
	ds_read_b128 v[208:211], v171 offset:38912
	ds_read_b128 v[212:215], v171 offset:39936
	s_cmp_eq_u32 s45, 40
	s_cselect_b64 exec, 0, -1
	s_cmp_lg_u32 s33, 0x100
	s_cselect_b64 exec, -1, exec
	global_load_lds_dwordx4 v144, s[20:21]
	s_mov_b32 m0, s29
	s_nop 0
	global_load_lds_dwordx4 v148, s[20:21]
	s_mov_b64 exec, -1
	s_waitcnt vmcnt(8)
	s_waitcnt lgkmcnt(0)
	s_barrier
	v_mfma_f32_16x16x32_bf16 v[124:127], v[128:131], v[184:187], v[124:127]
	v_mfma_f32_16x16x32_bf16 v[120:123], v[136:139], v[184:187], v[120:123]
	v_mfma_f32_16x16x32_bf16 v[116:119], v[128:131], v[192:195], v[116:119]
	v_mfma_f32_16x16x32_bf16 v[108:111], v[136:139], v[192:195], v[108:111]
	v_mfma_f32_16x16x32_bf16 v[92:95], v[128:131], v[200:203], v[92:95]
	v_mfma_f32_16x16x32_bf16 v[88:91], v[136:139], v[200:203], v[88:91]
	v_mfma_f32_16x16x32_bf16 v[84:87], v[128:131], v[208:211], v[84:87]
	v_mfma_f32_16x16x32_bf16 v[80:83], v[136:139], v[208:211], v[80:83]
	v_mfma_f32_16x16x32_bf16 v[124:127], v[132:135], v[188:191], v[124:127]
	v_mfma_f32_16x16x32_bf16 v[120:123], v[140:143], v[188:191], v[120:123]
	v_mfma_f32_16x16x32_bf16 v[116:119], v[132:135], v[196:199], v[116:119]
	v_mfma_f32_16x16x32_bf16 v[108:111], v[140:143], v[196:199], v[108:111]
	v_mfma_f32_16x16x32_bf16 v[92:95], v[132:135], v[204:207], v[92:95]
	v_mfma_f32_16x16x32_bf16 v[88:91], v[140:143], v[204:207], v[88:91]
	v_mfma_f32_16x16x32_bf16 v[84:87], v[132:135], v[212:215], v[84:87]
	v_mfma_f32_16x16x32_bf16 v[80:83], v[140:143], v[212:215], v[80:83]
	v_mfma_f32_16x16x32_bf16 v[112:115], v[160:163], v[184:187], v[112:115]
	v_mfma_f32_16x16x32_bf16 v[104:107], v[176:179], v[184:187], v[104:107]
	v_mfma_f32_16x16x32_bf16 v[100:103], v[160:163], v[192:195], v[100:103]
	v_mfma_f32_16x16x32_bf16 v[96:99], v[176:179], v[192:195], v[96:99]
	v_mfma_f32_16x16x32_bf16 v[76:79], v[160:163], v[200:203], v[76:79]
	v_mfma_f32_16x16x32_bf16 v[72:75], v[176:179], v[200:203], v[72:75]
	v_mfma_f32_16x16x32_bf16 v[68:71], v[160:163], v[208:211], v[68:71]
	v_mfma_f32_16x16x32_bf16 v[64:67], v[176:179], v[208:211], v[64:67]
	v_mfma_f32_16x16x32_bf16 v[112:115], v[172:175], v[188:191], v[112:115]
	v_mfma_f32_16x16x32_bf16 v[104:107], v[180:183], v[188:191], v[104:107]
	v_mfma_f32_16x16x32_bf16 v[100:103], v[172:175], v[196:199], v[100:103]
	v_mfma_f32_16x16x32_bf16 v[96:99], v[180:183], v[196:199], v[96:99]
	v_mfma_f32_16x16x32_bf16 v[76:79], v[172:175], v[204:207], v[76:79]
	v_mfma_f32_16x16x32_bf16 v[72:75], v[180:183], v[204:207], v[72:75]
	v_mfma_f32_16x16x32_bf16 v[68:71], v[172:175], v[212:215], v[68:71]
	v_mfma_f32_16x16x32_bf16 v[64:67], v[180:183], v[212:215], v[64:67]
	s_barrier
	s_add_i32 s20, s46, s25
	s_mov_b32 m0, s20
	ds_read_b128 v[184:187], v171 offset:49152
	ds_read_b128 v[188:191], v171 offset:50176
	ds_read_b128 v[192:195], v171 offset:51200
	ds_read_b128 v[196:199], v171 offset:52224
	ds_read_b128 v[200:203], v171 offset:53248
	ds_read_b128 v[204:207], v171 offset:54272
	ds_read_b128 v[208:211], v171 offset:55296
	ds_read_b128 v[212:215], v171 offset:56320
	s_cmp_eq_u32 s45, 40
	s_cselect_b64 exec, 0, -1
	s_cmp_lg_u32 s33, 0x100
	s_cselect_b64 exec, -1, exec
	global_load_lds_dwordx4 v146, s[98:99]
	s_add_i32 m0, s20, 0x2000
	s_add_u32 s18, s18, 0xb0080
	s_addc_u32 s19, s19, 0
	s_add_i32 s20, s47, s25
	global_load_lds_dwordx4 v150, s[98:99]
	s_mov_b32 m0, s20
	s_nop 0
	global_load_lds_dwordx4 v146, s[18:19]
	s_add_i32 m0, s20, 0x2000
	s_nop 0
	global_load_lds_dwordx4 v150, s[18:19]
	s_mov_b32 m0, s35
	s_nop 0
	global_load_lds_dwordx4 v144, s[100:101]
	s_mov_b32 m0, s36
	s_nop 0
	global_load_lds_dwordx4 v148, s[100:101]
	s_mov_b64 exec, -1
	s_waitcnt vmcnt(8)
	s_waitcnt lgkmcnt(0)
	s_barrier
	v_mfma_f32_16x16x32_bf16 v[60:63], v[128:131], v[184:187], v[60:63]
	v_mfma_f32_16x16x32_bf16 v[56:59], v[136:139], v[184:187], v[56:59]
	v_mfma_f32_16x16x32_bf16 v[52:55], v[128:131], v[192:195], v[52:55]
	v_mfma_f32_16x16x32_bf16 v[48:51], v[136:139], v[192:195], v[48:51]
	v_mfma_f32_16x16x32_bf16 v[28:31], v[128:131], v[200:203], v[28:31]
	v_mfma_f32_16x16x32_bf16 v[24:27], v[136:139], v[200:203], v[24:27]
	v_mfma_f32_16x16x32_bf16 v[20:23], v[128:131], v[208:211], v[20:23]
	v_mfma_f32_16x16x32_bf16 v[16:19], v[136:139], v[208:211], v[16:19]
	v_mfma_f32_16x16x32_bf16 v[60:63], v[132:135], v[188:191], v[60:63]
	v_mfma_f32_16x16x32_bf16 v[56:59], v[140:143], v[188:191], v[56:59]
	v_mfma_f32_16x16x32_bf16 v[52:55], v[132:135], v[196:199], v[52:55]
	v_mfma_f32_16x16x32_bf16 v[48:51], v[140:143], v[196:199], v[48:51]
	v_mfma_f32_16x16x32_bf16 v[28:31], v[132:135], v[204:207], v[28:31]
	v_mfma_f32_16x16x32_bf16 v[24:27], v[140:143], v[204:207], v[24:27]
	v_mfma_f32_16x16x32_bf16 v[20:23], v[132:135], v[212:215], v[20:23]
	v_mfma_f32_16x16x32_bf16 v[16:19], v[140:143], v[212:215], v[16:19]
	v_mfma_f32_16x16x32_bf16 v[44:47], v[160:163], v[184:187], v[44:47]
	v_mfma_f32_16x16x32_bf16 v[40:43], v[176:179], v[184:187], v[40:43]
	v_mfma_f32_16x16x32_bf16 v[36:39], v[160:163], v[192:195], v[36:39]
	v_mfma_f32_16x16x32_bf16 v[32:35], v[176:179], v[192:195], v[32:35]
	v_mfma_f32_16x16x32_bf16 v[12:15], v[160:163], v[200:203], v[12:15]
	v_mfma_f32_16x16x32_bf16 v[8:11], v[176:179], v[200:203], v[8:11]
	v_mfma_f32_16x16x32_bf16 v[4:7], v[160:163], v[208:211], v[4:7]
	v_mfma_f32_16x16x32_bf16 v[0:3], v[176:179], v[208:211], v[0:3]
	v_mfma_f32_16x16x32_bf16 v[44:47], v[172:175], v[188:191], v[44:47]
	v_mfma_f32_16x16x32_bf16 v[40:43], v[180:183], v[188:191], v[40:43]
	v_mfma_f32_16x16x32_bf16 v[36:39], v[172:175], v[196:199], v[36:39]
	v_mfma_f32_16x16x32_bf16 v[32:35], v[180:183], v[196:199], v[32:35]
	v_mfma_f32_16x16x32_bf16 v[12:15], v[172:175], v[204:207], v[12:15]
	v_mfma_f32_16x16x32_bf16 v[8:11], v[180:183], v[204:207], v[8:11]
	v_mfma_f32_16x16x32_bf16 v[4:7], v[172:175], v[212:215], v[4:7]
	v_mfma_f32_16x16x32_bf16 v[0:3], v[180:183], v[212:215], v[0:3]
	s_barrier
	s_add_i32 s45, s45, 2
	s_add_u32 s16, s16, 0x100
	s_addc_u32 s17, s17, 0
	s_add_u32 s43, s43, 0x100
	s_addc_u32 s44, s44, 0
	s_cmp_gt_u32 s45, 41
	s_cbranch_scc0 .LBB0_1463
	s_and_b64 vcc, exec, s[12:13]
	s_cbranch_vccz .LBB0_1466
	s_barrier
